# K-loops: LDS-DMA pair issued at the start of each load segment (before the ds_reads) where register dependences allow (31 of 48 segments)
# baseline (speedup 1.0000x reference)
.LBB0_124:
	s_ashr_i32 s79, s78, 31
	s_lshl_b64 s[10:11], s[78:79], 19
	s_add_u32 s80, s54, s10
	v_cmp_lt_i64_e32 vcc, s[72:73], v[178:179]
	s_addc_u32 s81, s55, s11
	s_and_b64 s[10:11], vcc, exec
	s_cselect_b32 s1, s81, s87
	s_cselect_b32 s10, s80, s86
	s_ashr_i32 s77, s76, 31
	s_lshl_b64 s[36:37], s[76:77], 19
	s_add_u32 s72, s66, s36
	s_addc_u32 s73, s59, s37
	s_and_b64 s[36:37], vcc, exec
	s_cselect_b32 s11, s73, s83
	s_cselect_b32 s25, s72, s82
	s_add_u32 s86, s86, 0x40080
	s_addc_u32 s87, s87, 0
	s_add_u32 s33, s82, 0x100
	s_addc_u32 s36, s83, 0
	s_mov_b32 s37, -2
	s_add_u32 s27, s86, 0xfffc0080
	s_addc_u32 s56, s87, -1
	s_add_i32 s57, 0, 0x10000
	v_add_u32_e32 v76, s57, v217
	ds_read_b128 v[64:67], v76
	ds_read_b128 v[68:71], v76 offset:1024
	ds_read_b128 v[72:75], v76 offset:2048
	ds_read_b128 v[76:79], v76 offset:3072
	s_cmp_eq_u32 s37, 12
	s_cselect_b32 vcc_hi, s1, s56
	s_cselect_b32 vcc_lo, s10, s27
	s_cselect_b32 s83, s11, s36
	s_cselect_b32 s82, s25, s33
	v_lshl_add_u64 v[168:169], s[86:87], 0, v[164:165]
	s_add_i32 m0, s75, 0xc000
	ds_read_b128 v[80:83], v220
	ds_read_b128 v[84:87], v220 offset:1024
	ds_read_b128 v[88:91], v220 offset:2048
	ds_read_b128 v[92:95], v220 offset:3072
	ds_read_b128 v[188:191], v220 offset:4096
	ds_read_b128 v[192:195], v220 offset:5120
	ds_read_b128 v[196:199], v220 offset:6144
	ds_read_b128 v[200:203], v220 offset:7168
	global_load_lds_dwordx4 v[168:169], off
	v_lshl_add_u64 v[168:169], s[86:87], 0, v[166:167]
	s_add_i32 m0, s75, 0xe000
	s_nop 0
	global_load_lds_dwordx4 v[168:169], off
	s_waitcnt lgkmcnt(8)
	s_setprio 1
	s_barrier
	s_waitcnt lgkmcnt(0)
	v_mfma_f32_16x16x32_bf16 v[146:149], v[64:67], v[80:83], 0
	v_mfma_f32_16x16x32_bf16 v[116:119], v[72:75], v[80:83], 0
	v_mfma_f32_16x16x32_bf16 v[158:161], v[64:67], v[88:91], 0
	v_mfma_f32_16x16x32_bf16 v[124:127], v[72:75], v[88:91], 0
	v_mfma_f32_16x16x32_bf16 v[154:157], v[64:67], v[188:191], 0
	v_mfma_f32_16x16x32_bf16 v[112:115], v[72:75], v[188:191], 0
	v_mfma_f32_16x16x32_bf16 v[150:153], v[64:67], v[196:199], 0
	v_mfma_f32_16x16x32_bf16 v[120:123], v[72:75], v[196:199], 0
	v_mfma_f32_16x16x32_bf16 v[146:149], v[68:71], v[84:87], v[146:149]
	v_mfma_f32_16x16x32_bf16 v[116:119], v[76:79], v[84:87], v[116:119]
	v_mfma_f32_16x16x32_bf16 v[158:161], v[68:71], v[92:95], v[158:161]
	v_mfma_f32_16x16x32_bf16 v[124:127], v[76:79], v[92:95], v[124:127]
	v_mfma_f32_16x16x32_bf16 v[154:157], v[68:71], v[192:195], v[154:157]
	v_mfma_f32_16x16x32_bf16 v[112:115], v[76:79], v[192:195], v[112:115]
	v_mfma_f32_16x16x32_bf16 v[150:153], v[68:71], v[200:203], v[150:153]
	v_mfma_f32_16x16x32_bf16 v[120:123], v[76:79], v[200:203], v[120:123]
	s_barrier
	s_setprio 0
	s_add_i32 s27, 0, 0x14000
	v_add_u32_e32 v168, s27, v217
	s_add_i32 s56, s57, s74
	ds_read_b128 v[204:207], v168
	ds_read_b128 v[222:225], v168 offset:1024
	ds_read_b128 v[228:231], v168 offset:2048
	ds_read_b128 v[232:235], v168 offset:3072
	v_lshl_add_u64 v[168:169], s[82:83], 0, v[144:145]
	s_mov_b32 m0, s56
	v_lshl_add_u64 v[176:177], s[82:83], 0, v[162:163]
	global_load_lds_dwordx4 v[168:169], off
	s_add_i32 m0, s56, 0x2000
	s_nop 0
	global_load_lds_dwordx4 v[176:177], off
	s_setprio 1
	s_barrier
	s_waitcnt lgkmcnt(0)
	v_mfma_f32_16x16x32_bf16 v[140:143], v[204:207], v[80:83], 0
	v_mfma_f32_16x16x32_bf16 v[80:83], v[228:231], v[80:83], 0
	v_mfma_f32_16x16x32_bf16 v[140:143], v[222:225], v[84:87], v[140:143]
	v_mfma_f32_16x16x32_bf16 v[80:83], v[232:235], v[84:87], v[80:83]
	v_mfma_f32_16x16x32_bf16 v[84:87], v[204:207], v[88:91], 0
	v_mfma_f32_16x16x32_bf16 v[88:91], v[228:231], v[88:91], 0
	v_mfma_f32_16x16x32_bf16 v[100:103], v[228:231], v[188:191], 0
	v_mfma_f32_16x16x32_bf16 v[104:107], v[204:207], v[196:199], 0
	v_mfma_f32_16x16x32_bf16 v[96:99], v[228:231], v[196:199], 0
	v_mfma_f32_16x16x32_bf16 v[84:87], v[222:225], v[92:95], v[84:87]
	v_mfma_f32_16x16x32_bf16 v[88:91], v[232:235], v[92:95], v[88:91]
	v_mfma_f32_16x16x32_bf16 v[92:95], v[204:207], v[188:191], 0
	v_mfma_f32_16x16x32_bf16 v[100:103], v[232:235], v[192:195], v[100:103]
	v_mfma_f32_16x16x32_bf16 v[128:131], v[222:225], v[200:203], v[104:107]
	v_mfma_f32_16x16x32_bf16 v[96:99], v[232:235], v[200:203], v[96:99]
	v_mfma_f32_16x16x32_bf16 v[92:95], v[222:225], v[192:195], v[92:95]
	s_barrier
	s_setprio 0
	s_mov_b32 m0, s75
	v_lshl_add_u64 v[240:241], vcc, 0, v[144:145]
	global_load_lds_dwordx4 v[240:241], off
	v_lshl_add_u64 v[242:243], vcc, 0, v[162:163]
	s_mov_b32 m0, s85
	s_nop 0
	global_load_lds_dwordx4 v[242:243], off
	ds_read_b128 v[104:107], v220 offset:16384
	ds_read_b128 v[108:111], v220 offset:17408
	ds_read_b128 v[132:135], v220 offset:18432
	ds_read_b128 v[136:139], v220 offset:19456
	ds_read_b128 v[188:191], v220 offset:20480
	ds_read_b128 v[192:195], v220 offset:21504
	ds_read_b128 v[196:199], v220 offset:22528
	ds_read_b128 v[200:203], v220 offset:23552
	s_setprio 1
	s_barrier
	s_waitcnt lgkmcnt(0)
	v_mfma_f32_16x16x32_bf16 v[48:51], v[64:67], v[104:107], 0
	v_mfma_f32_16x16x32_bf16 v[20:23], v[72:75], v[104:107], 0
	v_mfma_f32_16x16x32_bf16 v[60:63], v[64:67], v[132:135], 0
	v_mfma_f32_16x16x32_bf16 v[28:31], v[72:75], v[132:135], 0
	v_mfma_f32_16x16x32_bf16 v[56:59], v[64:67], v[188:191], 0
	v_mfma_f32_16x16x32_bf16 v[16:19], v[72:75], v[188:191], 0
	v_mfma_f32_16x16x32_bf16 v[52:55], v[64:67], v[196:199], 0
	v_mfma_f32_16x16x32_bf16 v[24:27], v[72:75], v[196:199], 0
	v_mfma_f32_16x16x32_bf16 v[48:51], v[68:71], v[108:111], v[48:51]
	v_mfma_f32_16x16x32_bf16 v[20:23], v[76:79], v[108:111], v[20:23]
	v_mfma_f32_16x16x32_bf16 v[60:63], v[68:71], v[136:139], v[60:63]
	v_mfma_f32_16x16x32_bf16 v[28:31], v[76:79], v[136:139], v[28:31]
	v_mfma_f32_16x16x32_bf16 v[56:59], v[68:71], v[192:195], v[56:59]
	v_mfma_f32_16x16x32_bf16 v[16:19], v[76:79], v[192:195], v[16:19]
	v_mfma_f32_16x16x32_bf16 v[52:55], v[68:71], v[200:203], v[52:55]
	v_mfma_f32_16x16x32_bf16 v[24:27], v[76:79], v[200:203], v[24:27]
	s_barrier
	s_setprio 0
	s_add_u32 s56, s82, 0x40000
	s_addc_u32 s57, s83, 0
	s_add_i32 s27, s27, s74
	v_lshl_add_u64 v[64:65], s[56:57], 0, v[144:145]
	s_mov_b32 m0, s27
	s_nop 0
	global_load_lds_dwordx4 v[64:65], off
	v_lshl_add_u64 v[64:65], s[56:57], 0, v[162:163]
	s_add_i32 m0, s27, 0x2000
	s_nop 0
	global_load_lds_dwordx4 v[64:65], off
	s_waitcnt vmcnt(6)
	s_setprio 1
	s_barrier
	v_mfma_f32_16x16x32_bf16 v[44:47], v[204:207], v[104:107], 0
	v_mfma_f32_16x16x32_bf16 v[12:15], v[228:231], v[104:107], 0
	v_mfma_f32_16x16x32_bf16 v[40:43], v[204:207], v[132:135], 0
	v_mfma_f32_16x16x32_bf16 v[8:11], v[228:231], v[132:135], 0
	v_mfma_f32_16x16x32_bf16 v[36:39], v[204:207], v[188:191], 0
	v_mfma_f32_16x16x32_bf16 v[4:7], v[228:231], v[188:191], 0
	v_mfma_f32_16x16x32_bf16 v[32:35], v[204:207], v[196:199], 0
	v_mfma_f32_16x16x32_bf16 v[0:3], v[228:231], v[196:199], 0
	v_mfma_f32_16x16x32_bf16 v[44:47], v[222:225], v[108:111], v[44:47]
	v_mfma_f32_16x16x32_bf16 v[12:15], v[232:235], v[108:111], v[12:15]
	v_mfma_f32_16x16x32_bf16 v[40:43], v[222:225], v[136:139], v[40:43]
	v_mfma_f32_16x16x32_bf16 v[8:11], v[232:235], v[136:139], v[8:11]
	v_mfma_f32_16x16x32_bf16 v[36:39], v[222:225], v[192:195], v[36:39]
	v_mfma_f32_16x16x32_bf16 v[4:7], v[232:235], v[192:195], v[4:7]
	v_mfma_f32_16x16x32_bf16 v[32:35], v[222:225], v[200:203], v[32:35]
	v_mfma_f32_16x16x32_bf16 v[0:3], v[232:235], v[200:203], v[0:3]
	s_barrier
	s_setprio 0
	s_add_i32 s27, 0, 0x18000
	v_add_u32_e32 v76, s27, v217
	ds_read_b128 v[64:67], v76
	ds_read_b128 v[68:71], v76 offset:1024
	ds_read_b128 v[72:75], v76 offset:2048
	ds_read_b128 v[76:79], v76 offset:3072
	s_add_u32 s56, vcc_lo, 0x40000
	s_addc_u32 s57, vcc_hi, 0
	s_mov_b32 m0, s98
	v_lshl_add_u64 v[136:137], s[56:57], 0, v[144:145]
	ds_read_b128 v[104:107], v220 offset:32768
	ds_read_b128 v[108:111], v220 offset:33792
	ds_read_b128 v[132:135], v220 offset:34816
	ds_read_b128 v[188:191], v220 offset:35840
	ds_read_b128 v[192:195], v220 offset:36864
	ds_read_b128 v[196:199], v220 offset:37888
	ds_read_b128 v[200:203], v220 offset:38912
	ds_read_b128 v[204:207], v220 offset:39936
	global_load_lds_dwordx4 v[136:137], off
	v_lshl_add_u64 v[136:137], s[56:57], 0, v[162:163]
	s_mov_b32 m0, s29
	s_nop 0
	global_load_lds_dwordx4 v[136:137], off
	s_waitcnt lgkmcnt(8)
	s_setprio 1
	s_barrier
	s_waitcnt lgkmcnt(0)
	v_mfma_f32_16x16x32_bf16 v[136:139], v[64:67], v[104:107], v[146:149]
	v_mfma_f32_16x16x32_bf16 v[146:149], v[68:71], v[108:111], v[136:139]
	v_mfma_f32_16x16x32_bf16 v[136:139], v[64:67], v[132:135], v[158:161]
	v_mfma_f32_16x16x32_bf16 v[158:161], v[68:71], v[188:191], v[136:139]
	v_mfma_f32_16x16x32_bf16 v[136:139], v[64:67], v[192:195], v[154:157]
	v_mfma_f32_16x16x32_bf16 v[116:119], v[72:75], v[104:107], v[116:119]
	v_mfma_f32_16x16x32_bf16 v[124:127], v[72:75], v[132:135], v[124:127]
	v_mfma_f32_16x16x32_bf16 v[154:157], v[68:71], v[196:199], v[136:139]
	v_mfma_f32_16x16x32_bf16 v[112:115], v[72:75], v[192:195], v[112:115]
	v_mfma_f32_16x16x32_bf16 v[136:139], v[64:67], v[200:203], v[150:153]
	v_mfma_f32_16x16x32_bf16 v[120:123], v[72:75], v[200:203], v[120:123]
	v_mfma_f32_16x16x32_bf16 v[116:119], v[76:79], v[108:111], v[116:119]
	v_mfma_f32_16x16x32_bf16 v[124:127], v[76:79], v[188:191], v[124:127]
	v_mfma_f32_16x16x32_bf16 v[112:115], v[76:79], v[196:199], v[112:115]
	v_mfma_f32_16x16x32_bf16 v[150:153], v[68:71], v[204:207], v[136:139]
	v_mfma_f32_16x16x32_bf16 v[120:123], v[76:79], v[204:207], v[120:123]
	s_barrier
	s_setprio 0
	s_add_i32 s58, 0, 0x1c000
	v_add_u32_e32 v136, s58, v217
	s_add_i32 s27, s27, s74
	ds_read_b128 v[222:225], v136
	ds_read_b128 v[228:231], v136 offset:1024
	ds_read_b128 v[232:235], v136 offset:2048
	ds_read_b128 v[236:239], v136 offset:3072
	v_lshl_add_u64 v[136:137], v[168:169], 0, s[18:19]
	s_mov_b32 m0, s27
	s_nop 0
	global_load_lds_dwordx4 v[136:137], off
	v_lshl_add_u64 v[136:137], v[176:177], 0, s[18:19]
	s_add_i32 m0, s27, 0x2000
	s_nop 0
	global_load_lds_dwordx4 v[136:137], off
	s_setprio 1
	s_barrier
	s_waitcnt lgkmcnt(0)
	v_mfma_f32_16x16x32_bf16 v[136:139], v[222:225], v[104:107], v[140:143]
	v_mfma_f32_16x16x32_bf16 v[80:83], v[232:235], v[104:107], v[80:83]
	v_mfma_f32_16x16x32_bf16 v[140:143], v[228:231], v[108:111], v[136:139]
	v_mfma_f32_16x16x32_bf16 v[108:111], v[236:239], v[108:111], v[80:83]
	v_mfma_f32_16x16x32_bf16 v[80:83], v[222:225], v[132:135], v[84:87]
	v_mfma_f32_16x16x32_bf16 v[136:139], v[228:231], v[188:191], v[80:83]
	v_mfma_f32_16x16x32_bf16 v[80:83], v[232:235], v[132:135], v[88:91]
	v_mfma_f32_16x16x32_bf16 v[104:107], v[236:239], v[188:191], v[80:83]
	v_mfma_f32_16x16x32_bf16 v[80:83], v[222:225], v[192:195], v[92:95]
	v_mfma_f32_16x16x32_bf16 v[132:135], v[228:231], v[196:199], v[80:83]
	v_mfma_f32_16x16x32_bf16 v[80:83], v[232:235], v[192:195], v[100:103]
	v_mfma_f32_16x16x32_bf16 v[100:103], v[236:239], v[196:199], v[80:83]
	v_mfma_f32_16x16x32_bf16 v[80:83], v[222:225], v[200:203], v[128:131]
	v_mfma_f32_16x16x32_bf16 v[128:131], v[228:231], v[204:207], v[80:83]
	v_mfma_f32_16x16x32_bf16 v[80:83], v[232:235], v[200:203], v[96:99]
	v_mfma_f32_16x16x32_bf16 v[96:99], v[236:239], v[204:207], v[80:83]
	s_barrier
	s_setprio 0
	s_mov_b32 m0, s31
	v_lshl_add_u64 v[168:169], v[240:241], 0, s[18:19]
	global_load_lds_dwordx4 v[168:169], off
	v_lshl_add_u64 v[168:169], v[242:243], 0, s[18:19]
	s_mov_b32 m0, s34
	s_nop 0
	global_load_lds_dwordx4 v[168:169], off
	s_nop 2
	ds_read_b128 v[80:83], v220 offset:49152
	ds_read_b128 v[84:87], v220 offset:50176
	ds_read_b128 v[88:91], v220 offset:51200
	ds_read_b128 v[92:95], v220 offset:52224
	ds_read_b128 v[188:191], v220 offset:53248
	ds_read_b128 v[192:195], v220 offset:54272
	ds_read_b128 v[196:199], v220 offset:55296
	ds_read_b128 v[200:203], v220 offset:56320
	s_setprio 1
	s_barrier
	s_waitcnt lgkmcnt(0)
	v_mfma_f32_16x16x32_bf16 v[48:51], v[64:67], v[80:83], v[48:51]
	v_mfma_f32_16x16x32_bf16 v[20:23], v[72:75], v[80:83], v[20:23]
	v_mfma_f32_16x16x32_bf16 v[60:63], v[64:67], v[88:91], v[60:63]
	v_mfma_f32_16x16x32_bf16 v[28:31], v[72:75], v[88:91], v[28:31]
	v_mfma_f32_16x16x32_bf16 v[56:59], v[64:67], v[188:191], v[56:59]
	v_mfma_f32_16x16x32_bf16 v[16:19], v[72:75], v[188:191], v[16:19]
	v_mfma_f32_16x16x32_bf16 v[52:55], v[64:67], v[196:199], v[52:55]
	v_mfma_f32_16x16x32_bf16 v[24:27], v[72:75], v[196:199], v[24:27]
	v_mfma_f32_16x16x32_bf16 v[48:51], v[68:71], v[84:87], v[48:51]
	v_mfma_f32_16x16x32_bf16 v[20:23], v[76:79], v[84:87], v[20:23]
	v_mfma_f32_16x16x32_bf16 v[60:63], v[68:71], v[92:95], v[60:63]
	v_mfma_f32_16x16x32_bf16 v[28:31], v[76:79], v[92:95], v[28:31]
	v_mfma_f32_16x16x32_bf16 v[56:59], v[68:71], v[192:195], v[56:59]
	v_mfma_f32_16x16x32_bf16 v[16:19], v[76:79], v[192:195], v[16:19]
	v_mfma_f32_16x16x32_bf16 v[52:55], v[68:71], v[200:203], v[52:55]
	v_mfma_f32_16x16x32_bf16 v[24:27], v[76:79], v[200:203], v[24:27]
	s_barrier
	s_setprio 0
	s_add_u32 s56, s82, 0x40080
	s_addc_u32 s57, s83, 0
	s_add_i32 s27, s58, s74
	v_lshl_add_u64 v[64:65], s[56:57], 0, v[144:145]
	s_mov_b32 m0, s27
	s_nop 0
	global_load_lds_dwordx4 v[64:65], off
	v_lshl_add_u64 v[64:65], s[56:57], 0, v[162:163]
	s_add_i32 m0, s27, 0x2000
	s_nop 0
	global_load_lds_dwordx4 v[64:65], off
	s_waitcnt vmcnt(6)
	s_setprio 1
	s_barrier
	v_mfma_f32_16x16x32_bf16 v[44:47], v[222:225], v[80:83], v[44:47]
	v_mfma_f32_16x16x32_bf16 v[12:15], v[232:235], v[80:83], v[12:15]
	v_mfma_f32_16x16x32_bf16 v[40:43], v[222:225], v[88:91], v[40:43]
	v_mfma_f32_16x16x32_bf16 v[8:11], v[232:235], v[88:91], v[8:11]
	v_mfma_f32_16x16x32_bf16 v[36:39], v[222:225], v[188:191], v[36:39]
	v_mfma_f32_16x16x32_bf16 v[4:7], v[232:235], v[188:191], v[4:7]
	v_mfma_f32_16x16x32_bf16 v[32:35], v[222:225], v[196:199], v[32:35]
	v_mfma_f32_16x16x32_bf16 v[0:3], v[232:235], v[196:199], v[0:3]
	v_mfma_f32_16x16x32_bf16 v[44:47], v[228:231], v[84:87], v[44:47]
	v_mfma_f32_16x16x32_bf16 v[12:15], v[236:239], v[84:87], v[12:15]
	v_mfma_f32_16x16x32_bf16 v[40:43], v[228:231], v[92:95], v[40:43]
	v_mfma_f32_16x16x32_bf16 v[8:11], v[236:239], v[92:95], v[8:11]
	v_mfma_f32_16x16x32_bf16 v[36:39], v[228:231], v[192:195], v[36:39]
	v_mfma_f32_16x16x32_bf16 v[4:7], v[236:239], v[192:195], v[4:7]
	v_mfma_f32_16x16x32_bf16 v[32:35], v[228:231], v[200:203], v[32:35]
	v_mfma_f32_16x16x32_bf16 v[0:3], v[236:239], v[200:203], v[0:3]
	s_barrier
	s_setprio 0
	s_add_i32 s37, s37, 2
	s_add_u32 s86, s86, 0x100
	s_addc_u32 s87, s87, 0
	s_add_u32 s33, s33, 0x100
	s_addc_u32 s36, s36, 0
	s_cmp_gt_u32 s37, 13
.LBB0_125:
	v_lshl_add_u64 v[168:169], s[86:87], 0, v[164:165]
	s_add_i32 m0, s75, 0xc000
	s_nop 0
	global_load_lds_dwordx4 v[168:169], off
	v_lshl_add_u64 v[168:169], s[86:87], 0, v[166:167]
	s_add_i32 m0, s75, 0xe000
	s_nop 0
	global_load_lds_dwordx4 v[168:169], off
	s_add_u32 s27, s86, 0xfffc0080
	s_addc_u32 s56, s87, -1
	s_add_i32 s57, 0, 0x10000
	v_add_u32_e32 v76, s57, v217
	ds_read_b128 v[64:67], v76
	ds_read_b128 v[68:71], v76 offset:1024
	ds_read_b128 v[72:75], v76 offset:2048
	ds_read_b128 v[76:79], v76 offset:3072
	s_cmp_eq_u32 s37, 12
	s_cselect_b32 vcc_hi, s1, s56
	s_cselect_b32 vcc_lo, s10, s27
	s_cselect_b32 s83, s11, s36
	s_cselect_b32 s82, s25, s33
	ds_read_b128 v[80:83], v220
	ds_read_b128 v[84:87], v220 offset:1024
	ds_read_b128 v[88:91], v220 offset:2048
	ds_read_b128 v[92:95], v220 offset:3072
	ds_read_b128 v[188:191], v220 offset:4096
	ds_read_b128 v[192:195], v220 offset:5120
	ds_read_b128 v[196:199], v220 offset:6144
	ds_read_b128 v[200:203], v220 offset:7168
	s_waitcnt lgkmcnt(8)
	s_setprio 1
	s_barrier
	s_waitcnt lgkmcnt(0)
	v_mfma_f32_16x16x32_bf16 v[146:149], v[64:67], v[80:83], v[146:149]
	v_mfma_f32_16x16x32_bf16 v[116:119], v[72:75], v[80:83], v[116:119]
	v_mfma_f32_16x16x32_bf16 v[158:161], v[64:67], v[88:91], v[158:161]
	v_mfma_f32_16x16x32_bf16 v[124:127], v[72:75], v[88:91], v[124:127]
	v_mfma_f32_16x16x32_bf16 v[154:157], v[64:67], v[188:191], v[154:157]
	v_mfma_f32_16x16x32_bf16 v[112:115], v[72:75], v[188:191], v[112:115]
	v_mfma_f32_16x16x32_bf16 v[150:153], v[64:67], v[196:199], v[150:153]
	v_mfma_f32_16x16x32_bf16 v[120:123], v[72:75], v[196:199], v[120:123]
	v_mfma_f32_16x16x32_bf16 v[146:149], v[68:71], v[84:87], v[146:149]
	v_mfma_f32_16x16x32_bf16 v[116:119], v[76:79], v[84:87], v[116:119]
	v_mfma_f32_16x16x32_bf16 v[158:161], v[68:71], v[92:95], v[158:161]
	v_mfma_f32_16x16x32_bf16 v[124:127], v[76:79], v[92:95], v[124:127]
	v_mfma_f32_16x16x32_bf16 v[154:157], v[68:71], v[192:195], v[154:157]
	v_mfma_f32_16x16x32_bf16 v[112:115], v[76:79], v[192:195], v[112:115]
	v_mfma_f32_16x16x32_bf16 v[150:153], v[68:71], v[200:203], v[150:153]
	v_mfma_f32_16x16x32_bf16 v[120:123], v[76:79], v[200:203], v[120:123]
	s_barrier
	s_setprio 0
	s_add_i32 s27, 0, 0x14000
	v_add_u32_e32 v168, s27, v217
	s_add_i32 s56, s57, s74
	ds_read_b128 v[204:207], v168
	ds_read_b128 v[222:225], v168 offset:1024
	ds_read_b128 v[228:231], v168 offset:2048
	ds_read_b128 v[232:235], v168 offset:3072
	v_lshl_add_u64 v[168:169], s[82:83], 0, v[144:145]
	s_mov_b32 m0, s56
	v_lshl_add_u64 v[176:177], s[82:83], 0, v[162:163]
	global_load_lds_dwordx4 v[168:169], off
	s_add_i32 m0, s56, 0x2000
	s_nop 0
	global_load_lds_dwordx4 v[176:177], off
	s_setprio 1
	s_barrier
	s_waitcnt lgkmcnt(0)
	v_mfma_f32_16x16x32_bf16 v[140:143], v[204:207], v[80:83], v[140:143]
	v_mfma_f32_16x16x32_bf16 v[80:83], v[228:231], v[80:83], v[108:111]
	v_mfma_f32_16x16x32_bf16 v[140:143], v[222:225], v[84:87], v[140:143]
	v_mfma_f32_16x16x32_bf16 v[80:83], v[232:235], v[84:87], v[80:83]
	v_mfma_f32_16x16x32_bf16 v[84:87], v[204:207], v[88:91], v[136:139]
	v_mfma_f32_16x16x32_bf16 v[88:91], v[228:231], v[88:91], v[104:107]
	v_mfma_f32_16x16x32_bf16 v[100:103], v[228:231], v[188:191], v[100:103]
	v_mfma_f32_16x16x32_bf16 v[104:107], v[204:207], v[196:199], v[128:131]
	v_mfma_f32_16x16x32_bf16 v[96:99], v[228:231], v[196:199], v[96:99]
	v_mfma_f32_16x16x32_bf16 v[84:87], v[222:225], v[92:95], v[84:87]
	v_mfma_f32_16x16x32_bf16 v[88:91], v[232:235], v[92:95], v[88:91]
	v_mfma_f32_16x16x32_bf16 v[92:95], v[204:207], v[188:191], v[132:135]
	v_mfma_f32_16x16x32_bf16 v[100:103], v[232:235], v[192:195], v[100:103]
	v_mfma_f32_16x16x32_bf16 v[128:131], v[222:225], v[200:203], v[104:107]
	v_mfma_f32_16x16x32_bf16 v[96:99], v[232:235], v[200:203], v[96:99]
	v_mfma_f32_16x16x32_bf16 v[92:95], v[222:225], v[192:195], v[92:95]
	s_barrier
	s_setprio 0
	s_mov_b32 m0, s75
	v_lshl_add_u64 v[240:241], vcc, 0, v[144:145]
	global_load_lds_dwordx4 v[240:241], off
	v_lshl_add_u64 v[242:243], vcc, 0, v[162:163]
	s_mov_b32 m0, s85
	s_nop 0
	global_load_lds_dwordx4 v[242:243], off
	ds_read_b128 v[104:107], v220 offset:16384
	ds_read_b128 v[108:111], v220 offset:17408
	ds_read_b128 v[132:135], v220 offset:18432
	ds_read_b128 v[136:139], v220 offset:19456
	ds_read_b128 v[188:191], v220 offset:20480
	ds_read_b128 v[192:195], v220 offset:21504
	ds_read_b128 v[196:199], v220 offset:22528
	ds_read_b128 v[200:203], v220 offset:23552
	s_setprio 1
	s_barrier
	s_waitcnt lgkmcnt(0)
	v_mfma_f32_16x16x32_bf16 v[48:51], v[64:67], v[104:107], v[48:51]
	v_mfma_f32_16x16x32_bf16 v[20:23], v[72:75], v[104:107], v[20:23]
	v_mfma_f32_16x16x32_bf16 v[60:63], v[64:67], v[132:135], v[60:63]
	v_mfma_f32_16x16x32_bf16 v[28:31], v[72:75], v[132:135], v[28:31]
	v_mfma_f32_16x16x32_bf16 v[56:59], v[64:67], v[188:191], v[56:59]
	v_mfma_f32_16x16x32_bf16 v[16:19], v[72:75], v[188:191], v[16:19]
	v_mfma_f32_16x16x32_bf16 v[52:55], v[64:67], v[196:199], v[52:55]
	v_mfma_f32_16x16x32_bf16 v[24:27], v[72:75], v[196:199], v[24:27]
	v_mfma_f32_16x16x32_bf16 v[48:51], v[68:71], v[108:111], v[48:51]
	v_mfma_f32_16x16x32_bf16 v[20:23], v[76:79], v[108:111], v[20:23]
	v_mfma_f32_16x16x32_bf16 v[60:63], v[68:71], v[136:139], v[60:63]
	v_mfma_f32_16x16x32_bf16 v[28:31], v[76:79], v[136:139], v[28:31]
	v_mfma_f32_16x16x32_bf16 v[56:59], v[68:71], v[192:195], v[56:59]
	v_mfma_f32_16x16x32_bf16 v[16:19], v[76:79], v[192:195], v[16:19]
	v_mfma_f32_16x16x32_bf16 v[52:55], v[68:71], v[200:203], v[52:55]
	v_mfma_f32_16x16x32_bf16 v[24:27], v[76:79], v[200:203], v[24:27]
	s_barrier
	s_setprio 0
	s_add_u32 s56, s82, 0x40000
	s_addc_u32 s57, s83, 0
	s_add_i32 s27, s27, s74
	v_lshl_add_u64 v[64:65], s[56:57], 0, v[144:145]
	s_mov_b32 m0, s27
	s_nop 0
	global_load_lds_dwordx4 v[64:65], off
	v_lshl_add_u64 v[64:65], s[56:57], 0, v[162:163]
	s_add_i32 m0, s27, 0x2000
	s_nop 0
	global_load_lds_dwordx4 v[64:65], off
	s_waitcnt vmcnt(6)
	s_setprio 1
	s_barrier
	v_mfma_f32_16x16x32_bf16 v[44:47], v[204:207], v[104:107], v[44:47]
	v_mfma_f32_16x16x32_bf16 v[12:15], v[228:231], v[104:107], v[12:15]
	v_mfma_f32_16x16x32_bf16 v[40:43], v[204:207], v[132:135], v[40:43]
	v_mfma_f32_16x16x32_bf16 v[8:11], v[228:231], v[132:135], v[8:11]
	v_mfma_f32_16x16x32_bf16 v[36:39], v[204:207], v[188:191], v[36:39]
	v_mfma_f32_16x16x32_bf16 v[4:7], v[228:231], v[188:191], v[4:7]
	v_mfma_f32_16x16x32_bf16 v[32:35], v[204:207], v[196:199], v[32:35]
	v_mfma_f32_16x16x32_bf16 v[0:3], v[228:231], v[196:199], v[0:3]
	v_mfma_f32_16x16x32_bf16 v[44:47], v[222:225], v[108:111], v[44:47]
	v_mfma_f32_16x16x32_bf16 v[12:15], v[232:235], v[108:111], v[12:15]
	v_mfma_f32_16x16x32_bf16 v[40:43], v[222:225], v[136:139], v[40:43]
	v_mfma_f32_16x16x32_bf16 v[8:11], v[232:235], v[136:139], v[8:11]
	v_mfma_f32_16x16x32_bf16 v[36:39], v[222:225], v[192:195], v[36:39]
	v_mfma_f32_16x16x32_bf16 v[4:7], v[232:235], v[192:195], v[4:7]
	v_mfma_f32_16x16x32_bf16 v[32:35], v[222:225], v[200:203], v[32:35]
	v_mfma_f32_16x16x32_bf16 v[0:3], v[232:235], v[200:203], v[0:3]
	s_barrier
	s_setprio 0
	s_add_i32 s27, 0, 0x18000
	v_add_u32_e32 v76, s27, v217
	ds_read_b128 v[64:67], v76
	ds_read_b128 v[68:71], v76 offset:1024
	ds_read_b128 v[72:75], v76 offset:2048
	ds_read_b128 v[76:79], v76 offset:3072
	s_add_u32 s56, vcc_lo, 0x40000
	s_addc_u32 s57, vcc_hi, 0
	s_mov_b32 m0, s98
	v_lshl_add_u64 v[136:137], s[56:57], 0, v[144:145]
	ds_read_b128 v[104:107], v220 offset:32768
	ds_read_b128 v[108:111], v220 offset:33792
	ds_read_b128 v[132:135], v220 offset:34816
	ds_read_b128 v[188:191], v220 offset:35840
	ds_read_b128 v[192:195], v220 offset:36864
	ds_read_b128 v[196:199], v220 offset:37888
	ds_read_b128 v[200:203], v220 offset:38912
	ds_read_b128 v[204:207], v220 offset:39936
	global_load_lds_dwordx4 v[136:137], off
	v_lshl_add_u64 v[136:137], s[56:57], 0, v[162:163]
	s_mov_b32 m0, s29
	s_nop 0
	global_load_lds_dwordx4 v[136:137], off
	s_waitcnt lgkmcnt(8)
	s_setprio 1
	s_barrier
	s_waitcnt lgkmcnt(0)
	v_mfma_f32_16x16x32_bf16 v[136:139], v[64:67], v[104:107], v[146:149]
	v_mfma_f32_16x16x32_bf16 v[146:149], v[68:71], v[108:111], v[136:139]
	v_mfma_f32_16x16x32_bf16 v[136:139], v[64:67], v[132:135], v[158:161]
	v_mfma_f32_16x16x32_bf16 v[158:161], v[68:71], v[188:191], v[136:139]
	v_mfma_f32_16x16x32_bf16 v[136:139], v[64:67], v[192:195], v[154:157]
	v_mfma_f32_16x16x32_bf16 v[116:119], v[72:75], v[104:107], v[116:119]
	v_mfma_f32_16x16x32_bf16 v[124:127], v[72:75], v[132:135], v[124:127]
	v_mfma_f32_16x16x32_bf16 v[154:157], v[68:71], v[196:199], v[136:139]
	v_mfma_f32_16x16x32_bf16 v[112:115], v[72:75], v[192:195], v[112:115]
	v_mfma_f32_16x16x32_bf16 v[136:139], v[64:67], v[200:203], v[150:153]
	v_mfma_f32_16x16x32_bf16 v[120:123], v[72:75], v[200:203], v[120:123]
	v_mfma_f32_16x16x32_bf16 v[116:119], v[76:79], v[108:111], v[116:119]
	v_mfma_f32_16x16x32_bf16 v[124:127], v[76:79], v[188:191], v[124:127]
	v_mfma_f32_16x16x32_bf16 v[112:115], v[76:79], v[196:199], v[112:115]
	v_mfma_f32_16x16x32_bf16 v[150:153], v[68:71], v[204:207], v[136:139]
	v_mfma_f32_16x16x32_bf16 v[120:123], v[76:79], v[204:207], v[120:123]
	s_barrier
	s_setprio 0
	s_add_i32 s58, 0, 0x1c000
	v_add_u32_e32 v136, s58, v217
	s_add_i32 s27, s27, s74
	ds_read_b128 v[222:225], v136
	ds_read_b128 v[228:231], v136 offset:1024
	ds_read_b128 v[232:235], v136 offset:2048
	ds_read_b128 v[236:239], v136 offset:3072
	v_lshl_add_u64 v[136:137], v[168:169], 0, s[18:19]
	s_mov_b32 m0, s27
	s_nop 0
	global_load_lds_dwordx4 v[136:137], off
	v_lshl_add_u64 v[136:137], v[176:177], 0, s[18:19]
	s_add_i32 m0, s27, 0x2000
	s_nop 0
	global_load_lds_dwordx4 v[136:137], off
	s_setprio 1
	s_barrier
	s_waitcnt lgkmcnt(0)
	v_mfma_f32_16x16x32_bf16 v[136:139], v[222:225], v[104:107], v[140:143]
	v_mfma_f32_16x16x32_bf16 v[80:83], v[232:235], v[104:107], v[80:83]
	v_mfma_f32_16x16x32_bf16 v[140:143], v[228:231], v[108:111], v[136:139]
	v_mfma_f32_16x16x32_bf16 v[108:111], v[236:239], v[108:111], v[80:83]
	v_mfma_f32_16x16x32_bf16 v[80:83], v[222:225], v[132:135], v[84:87]
	v_mfma_f32_16x16x32_bf16 v[136:139], v[228:231], v[188:191], v[80:83]
	v_mfma_f32_16x16x32_bf16 v[80:83], v[232:235], v[132:135], v[88:91]
	v_mfma_f32_16x16x32_bf16 v[104:107], v[236:239], v[188:191], v[80:83]
	v_mfma_f32_16x16x32_bf16 v[80:83], v[222:225], v[192:195], v[92:95]
	v_mfma_f32_16x16x32_bf16 v[132:135], v[228:231], v[196:199], v[80:83]
	v_mfma_f32_16x16x32_bf16 v[80:83], v[232:235], v[192:195], v[100:103]
	v_mfma_f32_16x16x32_bf16 v[100:103], v[236:239], v[196:199], v[80:83]
	v_mfma_f32_16x16x32_bf16 v[80:83], v[222:225], v[200:203], v[128:131]
	v_mfma_f32_16x16x32_bf16 v[128:131], v[228:231], v[204:207], v[80:83]
	v_mfma_f32_16x16x32_bf16 v[80:83], v[232:235], v[200:203], v[96:99]
	v_mfma_f32_16x16x32_bf16 v[96:99], v[236:239], v[204:207], v[80:83]
	s_barrier
	s_setprio 0
	s_mov_b32 m0, s31
	v_lshl_add_u64 v[168:169], v[240:241], 0, s[18:19]
	global_load_lds_dwordx4 v[168:169], off
	v_lshl_add_u64 v[168:169], v[242:243], 0, s[18:19]
	s_mov_b32 m0, s34
	s_nop 0
	global_load_lds_dwordx4 v[168:169], off
	s_nop 2
	ds_read_b128 v[80:83], v220 offset:49152
	ds_read_b128 v[84:87], v220 offset:50176
	ds_read_b128 v[88:91], v220 offset:51200
	ds_read_b128 v[92:95], v220 offset:52224
	ds_read_b128 v[188:191], v220 offset:53248
	ds_read_b128 v[192:195], v220 offset:54272
	ds_read_b128 v[196:199], v220 offset:55296
	ds_read_b128 v[200:203], v220 offset:56320
	s_setprio 1
	s_barrier
	s_waitcnt lgkmcnt(0)
	v_mfma_f32_16x16x32_bf16 v[48:51], v[64:67], v[80:83], v[48:51]
	v_mfma_f32_16x16x32_bf16 v[20:23], v[72:75], v[80:83], v[20:23]
	v_mfma_f32_16x16x32_bf16 v[60:63], v[64:67], v[88:91], v[60:63]
	v_mfma_f32_16x16x32_bf16 v[28:31], v[72:75], v[88:91], v[28:31]
	v_mfma_f32_16x16x32_bf16 v[56:59], v[64:67], v[188:191], v[56:59]
	v_mfma_f32_16x16x32_bf16 v[16:19], v[72:75], v[188:191], v[16:19]
	v_mfma_f32_16x16x32_bf16 v[52:55], v[64:67], v[196:199], v[52:55]
	v_mfma_f32_16x16x32_bf16 v[24:27], v[72:75], v[196:199], v[24:27]
	v_mfma_f32_16x16x32_bf16 v[48:51], v[68:71], v[84:87], v[48:51]
	v_mfma_f32_16x16x32_bf16 v[20:23], v[76:79], v[84:87], v[20:23]
	v_mfma_f32_16x16x32_bf16 v[60:63], v[68:71], v[92:95], v[60:63]
	v_mfma_f32_16x16x32_bf16 v[28:31], v[76:79], v[92:95], v[28:31]
	v_mfma_f32_16x16x32_bf16 v[56:59], v[68:71], v[192:195], v[56:59]
	v_mfma_f32_16x16x32_bf16 v[16:19], v[76:79], v[192:195], v[16:19]
	v_mfma_f32_16x16x32_bf16 v[52:55], v[68:71], v[200:203], v[52:55]
	v_mfma_f32_16x16x32_bf16 v[24:27], v[76:79], v[200:203], v[24:27]
	s_barrier
	s_setprio 0
	s_add_u32 s56, s82, 0x40080
	s_addc_u32 s57, s83, 0
	s_add_i32 s27, s58, s74
	v_lshl_add_u64 v[64:65], s[56:57], 0, v[144:145]
	s_mov_b32 m0, s27
	s_nop 0
	global_load_lds_dwordx4 v[64:65], off
	v_lshl_add_u64 v[64:65], s[56:57], 0, v[162:163]
	s_add_i32 m0, s27, 0x2000
	s_nop 0
	global_load_lds_dwordx4 v[64:65], off
	s_waitcnt vmcnt(6)
	s_setprio 1
	s_barrier
	v_mfma_f32_16x16x32_bf16 v[44:47], v[222:225], v[80:83], v[44:47]
	v_mfma_f32_16x16x32_bf16 v[12:15], v[232:235], v[80:83], v[12:15]
	v_mfma_f32_16x16x32_bf16 v[40:43], v[222:225], v[88:91], v[40:43]
	v_mfma_f32_16x16x32_bf16 v[8:11], v[232:235], v[88:91], v[8:11]
	v_mfma_f32_16x16x32_bf16 v[36:39], v[222:225], v[188:191], v[36:39]
	v_mfma_f32_16x16x32_bf16 v[4:7], v[232:235], v[188:191], v[4:7]
	v_mfma_f32_16x16x32_bf16 v[32:35], v[222:225], v[196:199], v[32:35]
	v_mfma_f32_16x16x32_bf16 v[0:3], v[232:235], v[196:199], v[0:3]
	v_mfma_f32_16x16x32_bf16 v[44:47], v[228:231], v[84:87], v[44:47]
	v_mfma_f32_16x16x32_bf16 v[12:15], v[236:239], v[84:87], v[12:15]
	v_mfma_f32_16x16x32_bf16 v[40:43], v[228:231], v[92:95], v[40:43]
	v_mfma_f32_16x16x32_bf16 v[8:11], v[236:239], v[92:95], v[8:11]
	v_mfma_f32_16x16x32_bf16 v[36:39], v[228:231], v[192:195], v[36:39]
	v_mfma_f32_16x16x32_bf16 v[4:7], v[236:239], v[192:195], v[4:7]
	v_mfma_f32_16x16x32_bf16 v[32:35], v[228:231], v[200:203], v[32:35]
	v_mfma_f32_16x16x32_bf16 v[0:3], v[236:239], v[200:203], v[0:3]
	s_barrier
	s_setprio 0
	s_add_i32 s37, s37, 2
	s_add_u32 s86, s86, 0x100
	s_addc_u32 s87, s87, 0
	s_add_u32 s33, s33, 0x100
	s_addc_u32 s36, s36, 0
	s_cmp_gt_u32 s37, 13
	s_cbranch_scc0 .LBB0_125
	s_lshl_b32 s1, s84, 8
	v_readlane_b32 s10, v254, 61
	s_add_i32 s1, s1, s10
	v_or_b32_e32 v198, s1, v216
	s_add_i32 s10, s1, 0x80
	v_or_b32_e32 v168, s10, v216
	v_lshl_or_b32 v188, s0, 7, v219
	v_lshlrev_b32_e32 v190, 2, v188
	v_lshlrev_b32_e32 v189, 1, v188
	s_ashr_i32 s11, s1, 5
	s_movk_i32 s10, 0xb00
	s_movk_i32 s20, 0x1600
	s_mov_b32 s101, 0xbfb8aa3b
	s_cmp_eq_u32 s84, s100
	s_cbranch_scc1 .Ldepi_w
	v_ashrrev_i32_e32 v199, 31, v198
	v_ashrrev_i32_e32 v169, 31, v168
	v_lshl_add_u64 v[170:171], v[198:199], 3, s[48:49]
	v_lshl_add_u64 v[172:173], v[168:169], 3, s[48:49]
	global_load_dwordx2 v[176:177], v[170:171], off
	global_load_dwordx2 v[202:203], v[170:171], off offset:128
	global_load_dwordx2 v[206:207], v[170:171], off offset:256
	global_load_dwordx2 v[222:223], v[170:171], off offset:384
	global_load_dwordx2 v[200:201], v[172:173], off
	global_load_dwordx2 v[196:197], v[172:173], off offset:128
	global_load_dwordx2 v[194:195], v[172:173], off offset:256
	global_load_dwordx2 v[192:193], v[172:173], off offset:384

.LBB0_195:
	s_add_u32 s42, s78, 0x80
	s_addc_u32 s43, s79, 0
	v_lshl_add_u64 v[176:177], s[42:43], 0, v[190:191]
	s_add_i32 m0, s85, 0xc000
	s_nop 0
	global_load_lds_dwordx4 v[176:177], off
	v_lshl_add_u64 v[176:177], s[42:43], 0, v[192:193]
	s_add_i32 m0, s85, 0xe000
	s_nop 0
	global_load_lds_dwordx4 v[176:177], off
	s_add_u32 s33, s44, 0x100
	s_addc_u32 s37, s45, 0
	s_mov_b32 s27, 0
	s_waitcnt lgkmcnt(0)
	s_add_i32 s56, s27, 2
	s_add_u32 s44, s42, 0x80
	s_addc_u32 s45, s43, 0
	s_add_i32 s57, 0, 0x10000
	v_add_u32_e32 v140, s57, v207
	ds_read_b128 v[128:131], v140
	ds_read_b128 v[132:135], v140 offset:1024
	ds_read_b128 v[136:139], v140 offset:2048
	ds_read_b128 v[140:143], v140 offset:3072
	s_cmp_eq_u32 s82, s27
	s_cselect_b32 s45, s77, s45
	s_cselect_b32 s44, s76, s44
	s_cselect_b32 s79, s1, s37
	s_cselect_b32 s78, s0, s33
	ds_read_b128 v[146:149], v217
	ds_read_b128 v[150:153], v217 offset:1024
	ds_read_b128 v[154:157], v217 offset:2048
	ds_read_b128 v[158:161], v217 offset:3072
	ds_read_b128 v[162:165], v217 offset:4096
	ds_read_b128 v[166:169], v217 offset:5120
	ds_read_b128 v[194:197], v217 offset:6144
	ds_read_b128 v[198:201], v217 offset:7168
	s_waitcnt lgkmcnt(8)
	s_setprio 1
	s_barrier
	s_waitcnt lgkmcnt(0)
	v_mfma_f32_16x16x32_bf16 v[124:127], v[128:131], v[146:149], 0
	v_mfma_f32_16x16x32_bf16 v[120:123], v[136:139], v[146:149], 0
	v_mfma_f32_16x16x32_bf16 v[108:111], v[128:131], v[154:157], 0
	v_mfma_f32_16x16x32_bf16 v[104:107], v[136:139], v[154:157], 0
	v_mfma_f32_16x16x32_bf16 v[92:95], v[128:131], v[162:165], 0
	v_mfma_f32_16x16x32_bf16 v[88:91], v[136:139], v[162:165], 0
	v_mfma_f32_16x16x32_bf16 v[76:79], v[128:131], v[194:197], 0
	v_mfma_f32_16x16x32_bf16 v[72:75], v[136:139], v[194:197], 0
	v_mfma_f32_16x16x32_bf16 v[124:127], v[132:135], v[150:153], v[124:127]
	v_mfma_f32_16x16x32_bf16 v[120:123], v[140:143], v[150:153], v[120:123]
	v_mfma_f32_16x16x32_bf16 v[108:111], v[132:135], v[158:161], v[108:111]
	v_mfma_f32_16x16x32_bf16 v[104:107], v[140:143], v[158:161], v[104:107]
	v_mfma_f32_16x16x32_bf16 v[92:95], v[132:135], v[166:169], v[92:95]
	v_mfma_f32_16x16x32_bf16 v[88:91], v[140:143], v[166:169], v[88:91]
	v_mfma_f32_16x16x32_bf16 v[76:79], v[132:135], v[198:201], v[76:79]
	v_mfma_f32_16x16x32_bf16 v[72:75], v[140:143], v[198:201], v[72:75]
	s_barrier
	s_setprio 0
	s_add_i32 s27, 0, 0x14000
	v_add_u32_e32 v176, s27, v207
	s_add_i32 s57, s57, s84
	ds_read_b128 v[202:205], v176
	ds_read_b128 v[218:221], v176 offset:1024
	ds_read_b128 v[222:225], v176 offset:2048
	ds_read_b128 v[228:231], v176 offset:3072
	v_lshl_add_u64 v[176:177], s[78:79], 0, v[144:145]
	s_mov_b32 m0, s57
	v_lshl_add_u64 v[232:233], s[78:79], 0, v[188:189]
	global_load_lds_dwordx4 v[176:177], off
	s_add_i32 m0, s57, 0x2000
	s_nop 0
	global_load_lds_dwordx4 v[232:233], off
	s_setprio 1
	s_barrier
	s_waitcnt lgkmcnt(0)
	v_mfma_f32_16x16x32_bf16 v[116:119], v[202:205], v[146:149], 0
	v_mfma_f32_16x16x32_bf16 v[112:115], v[222:225], v[146:149], 0
	v_mfma_f32_16x16x32_bf16 v[100:103], v[202:205], v[154:157], 0
	v_mfma_f32_16x16x32_bf16 v[96:99], v[222:225], v[154:157], 0
	v_mfma_f32_16x16x32_bf16 v[84:87], v[202:205], v[162:165], 0
	v_mfma_f32_16x16x32_bf16 v[80:83], v[222:225], v[162:165], 0
	v_mfma_f32_16x16x32_bf16 v[68:71], v[202:205], v[194:197], 0
	v_mfma_f32_16x16x32_bf16 v[64:67], v[222:225], v[194:197], 0
	v_mfma_f32_16x16x32_bf16 v[116:119], v[218:221], v[150:153], v[116:119]
	v_mfma_f32_16x16x32_bf16 v[112:115], v[228:231], v[150:153], v[112:115]
	v_mfma_f32_16x16x32_bf16 v[100:103], v[218:221], v[158:161], v[100:103]
	v_mfma_f32_16x16x32_bf16 v[96:99], v[228:231], v[158:161], v[96:99]
	v_mfma_f32_16x16x32_bf16 v[84:87], v[218:221], v[166:169], v[84:87]
	v_mfma_f32_16x16x32_bf16 v[80:83], v[228:231], v[166:169], v[80:83]
	v_mfma_f32_16x16x32_bf16 v[68:71], v[218:221], v[198:201], v[68:71]
	v_mfma_f32_16x16x32_bf16 v[64:67], v[228:231], v[198:201], v[64:67]
	s_barrier
	s_setprio 0
	s_mov_b32 m0, s85
	v_lshl_add_u64 v[234:235], s[44:45], 0, v[144:145]
	global_load_lds_dwordx4 v[234:235], off
	v_lshl_add_u64 v[236:237], s[44:45], 0, v[188:189]
	s_mov_b32 m0, s86
	s_nop 0
	global_load_lds_dwordx4 v[236:237], off
	ds_read_b128 v[146:149], v217 offset:16384
	ds_read_b128 v[150:153], v217 offset:17408
	ds_read_b128 v[154:157], v217 offset:18432
	ds_read_b128 v[158:161], v217 offset:19456
	ds_read_b128 v[162:165], v217 offset:20480
	ds_read_b128 v[166:169], v217 offset:21504
	ds_read_b128 v[194:197], v217 offset:22528
	ds_read_b128 v[198:201], v217 offset:23552
	s_setprio 1
	s_barrier
	s_waitcnt lgkmcnt(0)
	v_mfma_f32_16x16x32_bf16 v[60:63], v[128:131], v[146:149], 0
	v_mfma_f32_16x16x32_bf16 v[56:59], v[136:139], v[146:149], 0
	v_mfma_f32_16x16x32_bf16 v[44:47], v[128:131], v[154:157], 0
	v_mfma_f32_16x16x32_bf16 v[40:43], v[136:139], v[154:157], 0
	v_mfma_f32_16x16x32_bf16 v[28:31], v[128:131], v[162:165], 0
	v_mfma_f32_16x16x32_bf16 v[24:27], v[136:139], v[162:165], 0
	v_mfma_f32_16x16x32_bf16 v[12:15], v[128:131], v[194:197], 0
	v_mfma_f32_16x16x32_bf16 v[8:11], v[136:139], v[194:197], 0
	v_mfma_f32_16x16x32_bf16 v[60:63], v[132:135], v[150:153], v[60:63]
	v_mfma_f32_16x16x32_bf16 v[56:59], v[140:143], v[150:153], v[56:59]
	v_mfma_f32_16x16x32_bf16 v[44:47], v[132:135], v[158:161], v[44:47]
	v_mfma_f32_16x16x32_bf16 v[40:43], v[140:143], v[158:161], v[40:43]
	v_mfma_f32_16x16x32_bf16 v[28:31], v[132:135], v[166:169], v[28:31]
	v_mfma_f32_16x16x32_bf16 v[24:27], v[140:143], v[166:169], v[24:27]
	v_mfma_f32_16x16x32_bf16 v[12:15], v[132:135], v[198:201], v[12:15]
	v_mfma_f32_16x16x32_bf16 v[8:11], v[140:143], v[198:201], v[8:11]
	s_barrier
	s_setprio 0
	s_add_u32 s58, s78, s98
	s_addc_u32 s59, s79, 0
	s_add_i32 s27, s27, s84
	v_lshl_add_u64 v[238:239], s[58:59], 0, v[144:145]
	s_mov_b32 m0, s27
	v_lshl_add_u64 v[240:241], s[58:59], 0, v[188:189]
	global_load_lds_dwordx4 v[238:239], off
	s_add_i32 m0, s27, 0x2000
	s_nop 0
	global_load_lds_dwordx4 v[240:241], off
	s_waitcnt vmcnt(6)
	s_setprio 1
	s_barrier
	v_mfma_f32_16x16x32_bf16 v[52:55], v[202:205], v[146:149], 0
	v_mfma_f32_16x16x32_bf16 v[48:51], v[222:225], v[146:149], 0
	v_mfma_f32_16x16x32_bf16 v[36:39], v[202:205], v[154:157], 0
	v_mfma_f32_16x16x32_bf16 v[32:35], v[222:225], v[154:157], 0
	v_mfma_f32_16x16x32_bf16 v[20:23], v[202:205], v[162:165], 0
	v_mfma_f32_16x16x32_bf16 v[16:19], v[222:225], v[162:165], 0
	v_mfma_f32_16x16x32_bf16 v[4:7], v[202:205], v[194:197], 0
	v_mfma_f32_16x16x32_bf16 v[0:3], v[222:225], v[194:197], 0
	v_mfma_f32_16x16x32_bf16 v[52:55], v[218:221], v[150:153], v[52:55]
	v_mfma_f32_16x16x32_bf16 v[48:51], v[228:231], v[150:153], v[48:51]
	v_mfma_f32_16x16x32_bf16 v[36:39], v[218:221], v[158:161], v[36:39]
	v_mfma_f32_16x16x32_bf16 v[32:35], v[228:231], v[158:161], v[32:35]
	v_mfma_f32_16x16x32_bf16 v[20:23], v[218:221], v[166:169], v[20:23]
	v_mfma_f32_16x16x32_bf16 v[16:19], v[228:231], v[166:169], v[16:19]
	v_mfma_f32_16x16x32_bf16 v[4:7], v[218:221], v[198:201], v[4:7]
	v_mfma_f32_16x16x32_bf16 v[0:3], v[228:231], v[198:201], v[0:3]
	s_barrier
	s_setprio 0
	s_add_i32 s27, 0, 0x18000
	v_add_u32_e32 v140, s27, v207
	ds_read_b128 v[128:131], v140
	ds_read_b128 v[132:135], v140 offset:1024
	ds_read_b128 v[136:139], v140 offset:2048
	ds_read_b128 v[140:143], v140 offset:3072
	s_add_u32 s44, s44, s98
	s_addc_u32 s45, s45, 0
	s_mov_b32 m0, s87
	v_lshl_add_u64 v[202:203], s[44:45], 0, v[144:145]
	ds_read_b128 v[146:149], v217 offset:32768
	ds_read_b128 v[150:153], v217 offset:33792
	ds_read_b128 v[154:157], v217 offset:34816
	ds_read_b128 v[158:161], v217 offset:35840
	ds_read_b128 v[162:165], v217 offset:36864
	ds_read_b128 v[166:169], v217 offset:37888
	ds_read_b128 v[194:197], v217 offset:38912
	ds_read_b128 v[198:201], v217 offset:39936
	global_load_lds_dwordx4 v[202:203], off
	v_lshl_add_u64 v[202:203], s[44:45], 0, v[188:189]
	s_mov_b32 m0, s80
	s_nop 0
	global_load_lds_dwordx4 v[202:203], off
	s_waitcnt lgkmcnt(8)
	s_setprio 1
	s_barrier
	s_waitcnt lgkmcnt(0)
	v_mfma_f32_16x16x32_bf16 v[124:127], v[128:131], v[146:149], v[124:127]
	v_mfma_f32_16x16x32_bf16 v[120:123], v[136:139], v[146:149], v[120:123]
	v_mfma_f32_16x16x32_bf16 v[108:111], v[128:131], v[154:157], v[108:111]
	v_mfma_f32_16x16x32_bf16 v[104:107], v[136:139], v[154:157], v[104:107]
	v_mfma_f32_16x16x32_bf16 v[92:95], v[128:131], v[162:165], v[92:95]
	v_mfma_f32_16x16x32_bf16 v[88:91], v[136:139], v[162:165], v[88:91]
	v_mfma_f32_16x16x32_bf16 v[76:79], v[128:131], v[194:197], v[76:79]
	v_mfma_f32_16x16x32_bf16 v[72:75], v[136:139], v[194:197], v[72:75]
	v_mfma_f32_16x16x32_bf16 v[124:127], v[132:135], v[150:153], v[124:127]
	v_mfma_f32_16x16x32_bf16 v[120:123], v[140:143], v[150:153], v[120:123]
	v_mfma_f32_16x16x32_bf16 v[108:111], v[132:135], v[158:161], v[108:111]
	v_mfma_f32_16x16x32_bf16 v[104:107], v[140:143], v[158:161], v[104:107]
	v_mfma_f32_16x16x32_bf16 v[92:95], v[132:135], v[166:169], v[92:95]
	v_mfma_f32_16x16x32_bf16 v[88:91], v[140:143], v[166:169], v[88:91]
	v_mfma_f32_16x16x32_bf16 v[76:79], v[132:135], v[198:201], v[76:79]
	v_mfma_f32_16x16x32_bf16 v[72:75], v[140:143], v[198:201], v[72:75]
	s_barrier
	s_setprio 0
	s_add_i32 s27, s27, s84
	v_lshl_add_u64 v[176:177], v[176:177], 0, s[18:19]
	s_mov_b32 m0, s27
	s_nop 0
	global_load_lds_dwordx4 v[176:177], off
	v_lshl_add_u64 v[176:177], v[232:233], 0, s[18:19]
	s_add_i32 m0, s27, 0x2000
	s_nop 0
	global_load_lds_dwordx4 v[176:177], off
	s_add_i32 s44, 0, 0x1c000
	v_add_u32_e32 v228, s44, v207
	ds_read_b128 v[202:205], v228
	ds_read_b128 v[218:221], v228 offset:1024
	ds_read_b128 v[222:225], v228 offset:2048
	ds_read_b128 v[228:231], v228 offset:3072
	s_setprio 1
	s_barrier
	s_waitcnt lgkmcnt(0)
	v_mfma_f32_16x16x32_bf16 v[116:119], v[202:205], v[146:149], v[116:119]
	v_mfma_f32_16x16x32_bf16 v[112:115], v[222:225], v[146:149], v[112:115]
	v_mfma_f32_16x16x32_bf16 v[100:103], v[202:205], v[154:157], v[100:103]
	v_mfma_f32_16x16x32_bf16 v[96:99], v[222:225], v[154:157], v[96:99]
	v_mfma_f32_16x16x32_bf16 v[84:87], v[202:205], v[162:165], v[84:87]
	v_mfma_f32_16x16x32_bf16 v[80:83], v[222:225], v[162:165], v[80:83]
	v_mfma_f32_16x16x32_bf16 v[68:71], v[202:205], v[194:197], v[68:71]
	v_mfma_f32_16x16x32_bf16 v[64:67], v[222:225], v[194:197], v[64:67]
	v_mfma_f32_16x16x32_bf16 v[116:119], v[218:221], v[150:153], v[116:119]
	v_mfma_f32_16x16x32_bf16 v[112:115], v[228:231], v[150:153], v[112:115]
	v_mfma_f32_16x16x32_bf16 v[100:103], v[218:221], v[158:161], v[100:103]
	v_mfma_f32_16x16x32_bf16 v[96:99], v[228:231], v[158:161], v[96:99]
	v_mfma_f32_16x16x32_bf16 v[84:87], v[218:221], v[166:169], v[84:87]
	v_mfma_f32_16x16x32_bf16 v[80:83], v[228:231], v[166:169], v[80:83]
	v_mfma_f32_16x16x32_bf16 v[68:71], v[218:221], v[198:201], v[68:71]
	v_mfma_f32_16x16x32_bf16 v[64:67], v[228:231], v[198:201], v[64:67]
	s_barrier
	s_setprio 0
	s_mov_b32 m0, s30
	v_lshl_add_u64 v[176:177], v[234:235], 0, s[18:19]
	global_load_lds_dwordx4 v[176:177], off
	v_lshl_add_u64 v[176:177], v[236:237], 0, s[18:19]
	s_mov_b32 m0, s31
	s_nop 0
	global_load_lds_dwordx4 v[176:177], off
	ds_read_b128 v[146:149], v217 offset:49152
	ds_read_b128 v[150:153], v217 offset:50176
	ds_read_b128 v[154:157], v217 offset:51200
	ds_read_b128 v[158:161], v217 offset:52224
	ds_read_b128 v[162:165], v217 offset:53248
	ds_read_b128 v[166:169], v217 offset:54272
	ds_read_b128 v[194:197], v217 offset:55296
	ds_read_b128 v[198:201], v217 offset:56320
	s_setprio 1
	s_barrier
	s_waitcnt lgkmcnt(0)
	v_mfma_f32_16x16x32_bf16 v[60:63], v[128:131], v[146:149], v[60:63]
	v_mfma_f32_16x16x32_bf16 v[56:59], v[136:139], v[146:149], v[56:59]
	v_mfma_f32_16x16x32_bf16 v[44:47], v[128:131], v[154:157], v[44:47]
	v_mfma_f32_16x16x32_bf16 v[40:43], v[136:139], v[154:157], v[40:43]
	v_mfma_f32_16x16x32_bf16 v[28:31], v[128:131], v[162:165], v[28:31]
	v_mfma_f32_16x16x32_bf16 v[24:27], v[136:139], v[162:165], v[24:27]
	v_mfma_f32_16x16x32_bf16 v[12:15], v[128:131], v[194:197], v[12:15]
	v_mfma_f32_16x16x32_bf16 v[8:11], v[136:139], v[194:197], v[8:11]
	v_mfma_f32_16x16x32_bf16 v[60:63], v[132:135], v[150:153], v[60:63]
	v_mfma_f32_16x16x32_bf16 v[56:59], v[140:143], v[150:153], v[56:59]
	v_mfma_f32_16x16x32_bf16 v[44:47], v[132:135], v[158:161], v[44:47]
	v_mfma_f32_16x16x32_bf16 v[40:43], v[140:143], v[158:161], v[40:43]
	v_mfma_f32_16x16x32_bf16 v[28:31], v[132:135], v[166:169], v[28:31]
	v_mfma_f32_16x16x32_bf16 v[24:27], v[140:143], v[166:169], v[24:27]
	v_mfma_f32_16x16x32_bf16 v[12:15], v[132:135], v[198:201], v[12:15]
	v_mfma_f32_16x16x32_bf16 v[8:11], v[140:143], v[198:201], v[8:11]
	s_barrier
	s_setprio 0
	s_add_i32 s27, s44, s84
	v_lshl_add_u64 v[128:129], v[238:239], 0, s[18:19]
	s_mov_b32 m0, s27
	s_nop 0
	global_load_lds_dwordx4 v[128:129], off
	v_lshl_add_u64 v[128:129], v[240:241], 0, s[18:19]
	s_add_i32 m0, s27, 0x2000
	s_nop 0
	global_load_lds_dwordx4 v[128:129], off
	s_waitcnt vmcnt(6)
	s_setprio 1
	s_barrier
	v_mfma_f32_16x16x32_bf16 v[52:55], v[202:205], v[146:149], v[52:55]
	v_mfma_f32_16x16x32_bf16 v[48:51], v[222:225], v[146:149], v[48:51]
	v_mfma_f32_16x16x32_bf16 v[36:39], v[202:205], v[154:157], v[36:39]
	v_mfma_f32_16x16x32_bf16 v[32:35], v[222:225], v[154:157], v[32:35]
	v_mfma_f32_16x16x32_bf16 v[20:23], v[202:205], v[162:165], v[20:23]
	v_mfma_f32_16x16x32_bf16 v[16:19], v[222:225], v[162:165], v[16:19]
	v_mfma_f32_16x16x32_bf16 v[4:7], v[202:205], v[194:197], v[4:7]
	v_mfma_f32_16x16x32_bf16 v[0:3], v[222:225], v[194:197], v[0:3]
	v_mfma_f32_16x16x32_bf16 v[52:55], v[218:221], v[150:153], v[52:55]
	v_mfma_f32_16x16x32_bf16 v[48:51], v[228:231], v[150:153], v[48:51]
	v_mfma_f32_16x16x32_bf16 v[36:39], v[218:221], v[158:161], v[36:39]
	v_mfma_f32_16x16x32_bf16 v[32:35], v[228:231], v[158:161], v[32:35]
	v_mfma_f32_16x16x32_bf16 v[20:23], v[218:221], v[166:169], v[20:23]
	v_mfma_f32_16x16x32_bf16 v[16:19], v[228:231], v[166:169], v[16:19]
	v_mfma_f32_16x16x32_bf16 v[4:7], v[218:221], v[198:201], v[4:7]
	v_mfma_f32_16x16x32_bf16 v[0:3], v[228:231], v[198:201], v[0:3]
	s_barrier
	s_setprio 0
	s_add_u32 s42, s42, 0x100
	s_addc_u32 s43, s43, 0
	s_add_u32 s33, s33, 0x100
	s_addc_u32 s37, s37, 0
	s_cmp_ge_u32 s56, s34
	s_mov_b32 s27, s56
.LBB0_196:
	v_lshl_add_u64 v[176:177], s[42:43], 0, v[190:191]
	s_add_i32 m0, s85, 0xc000
	s_nop 0
	global_load_lds_dwordx4 v[176:177], off
	v_lshl_add_u64 v[176:177], s[42:43], 0, v[192:193]
	s_add_i32 m0, s85, 0xe000
	s_nop 0
	global_load_lds_dwordx4 v[176:177], off
	s_add_i32 s56, s27, 2
	s_add_u32 s44, s42, 0x80
	s_addc_u32 s45, s43, 0
	s_add_i32 s57, 0, 0x10000
	v_add_u32_e32 v140, s57, v207
	ds_read_b128 v[128:131], v140
	ds_read_b128 v[132:135], v140 offset:1024
	ds_read_b128 v[136:139], v140 offset:2048
	ds_read_b128 v[140:143], v140 offset:3072
	s_cmp_eq_u32 s82, s27
	s_cselect_b32 s45, s77, s45
	s_cselect_b32 s44, s76, s44
	s_cselect_b32 s79, s1, s37
	s_cselect_b32 s78, s0, s33
	ds_read_b128 v[146:149], v217
	ds_read_b128 v[150:153], v217 offset:1024
	ds_read_b128 v[154:157], v217 offset:2048
	ds_read_b128 v[158:161], v217 offset:3072
	ds_read_b128 v[162:165], v217 offset:4096
	ds_read_b128 v[166:169], v217 offset:5120
	ds_read_b128 v[194:197], v217 offset:6144
	ds_read_b128 v[198:201], v217 offset:7168
	s_waitcnt lgkmcnt(8)
	s_setprio 1
	s_barrier
	s_waitcnt lgkmcnt(0)
	v_mfma_f32_16x16x32_bf16 v[124:127], v[128:131], v[146:149], v[124:127]
	v_mfma_f32_16x16x32_bf16 v[120:123], v[136:139], v[146:149], v[120:123]
	v_mfma_f32_16x16x32_bf16 v[108:111], v[128:131], v[154:157], v[108:111]
	v_mfma_f32_16x16x32_bf16 v[104:107], v[136:139], v[154:157], v[104:107]
	v_mfma_f32_16x16x32_bf16 v[92:95], v[128:131], v[162:165], v[92:95]
	v_mfma_f32_16x16x32_bf16 v[88:91], v[136:139], v[162:165], v[88:91]
	v_mfma_f32_16x16x32_bf16 v[76:79], v[128:131], v[194:197], v[76:79]
	v_mfma_f32_16x16x32_bf16 v[72:75], v[136:139], v[194:197], v[72:75]
	v_mfma_f32_16x16x32_bf16 v[124:127], v[132:135], v[150:153], v[124:127]
	v_mfma_f32_16x16x32_bf16 v[120:123], v[140:143], v[150:153], v[120:123]
	v_mfma_f32_16x16x32_bf16 v[108:111], v[132:135], v[158:161], v[108:111]
	v_mfma_f32_16x16x32_bf16 v[104:107], v[140:143], v[158:161], v[104:107]
	v_mfma_f32_16x16x32_bf16 v[92:95], v[132:135], v[166:169], v[92:95]
	v_mfma_f32_16x16x32_bf16 v[88:91], v[140:143], v[166:169], v[88:91]
	v_mfma_f32_16x16x32_bf16 v[76:79], v[132:135], v[198:201], v[76:79]
	v_mfma_f32_16x16x32_bf16 v[72:75], v[140:143], v[198:201], v[72:75]
	s_barrier
	s_setprio 0
	s_add_i32 s27, 0, 0x14000
	v_add_u32_e32 v176, s27, v207
	s_add_i32 s57, s57, s84
	ds_read_b128 v[202:205], v176
	ds_read_b128 v[218:221], v176 offset:1024
	ds_read_b128 v[222:225], v176 offset:2048
	ds_read_b128 v[228:231], v176 offset:3072
	v_lshl_add_u64 v[176:177], s[78:79], 0, v[144:145]
	s_mov_b32 m0, s57
	v_lshl_add_u64 v[232:233], s[78:79], 0, v[188:189]
	global_load_lds_dwordx4 v[176:177], off
	s_add_i32 m0, s57, 0x2000
	s_nop 0
	global_load_lds_dwordx4 v[232:233], off
	s_setprio 1
	s_barrier
	s_waitcnt lgkmcnt(0)
	v_mfma_f32_16x16x32_bf16 v[116:119], v[202:205], v[146:149], v[116:119]
	v_mfma_f32_16x16x32_bf16 v[112:115], v[222:225], v[146:149], v[112:115]
	v_mfma_f32_16x16x32_bf16 v[100:103], v[202:205], v[154:157], v[100:103]
	v_mfma_f32_16x16x32_bf16 v[96:99], v[222:225], v[154:157], v[96:99]
	v_mfma_f32_16x16x32_bf16 v[84:87], v[202:205], v[162:165], v[84:87]
	v_mfma_f32_16x16x32_bf16 v[80:83], v[222:225], v[162:165], v[80:83]
	v_mfma_f32_16x16x32_bf16 v[68:71], v[202:205], v[194:197], v[68:71]
	v_mfma_f32_16x16x32_bf16 v[64:67], v[222:225], v[194:197], v[64:67]
	v_mfma_f32_16x16x32_bf16 v[116:119], v[218:221], v[150:153], v[116:119]
	v_mfma_f32_16x16x32_bf16 v[112:115], v[228:231], v[150:153], v[112:115]
	v_mfma_f32_16x16x32_bf16 v[100:103], v[218:221], v[158:161], v[100:103]
	v_mfma_f32_16x16x32_bf16 v[96:99], v[228:231], v[158:161], v[96:99]
	v_mfma_f32_16x16x32_bf16 v[84:87], v[218:221], v[166:169], v[84:87]
	v_mfma_f32_16x16x32_bf16 v[80:83], v[228:231], v[166:169], v[80:83]
	v_mfma_f32_16x16x32_bf16 v[68:71], v[218:221], v[198:201], v[68:71]
	v_mfma_f32_16x16x32_bf16 v[64:67], v[228:231], v[198:201], v[64:67]
	s_barrier
	s_setprio 0
	s_mov_b32 m0, s85
	v_lshl_add_u64 v[234:235], s[44:45], 0, v[144:145]
	global_load_lds_dwordx4 v[234:235], off
	v_lshl_add_u64 v[236:237], s[44:45], 0, v[188:189]
	s_mov_b32 m0, s86
	s_nop 0
	global_load_lds_dwordx4 v[236:237], off
	ds_read_b128 v[146:149], v217 offset:16384
	ds_read_b128 v[150:153], v217 offset:17408
	ds_read_b128 v[154:157], v217 offset:18432
	ds_read_b128 v[158:161], v217 offset:19456
	ds_read_b128 v[162:165], v217 offset:20480
	ds_read_b128 v[166:169], v217 offset:21504
	ds_read_b128 v[194:197], v217 offset:22528
	ds_read_b128 v[198:201], v217 offset:23552
	s_setprio 1
	s_barrier
	s_waitcnt lgkmcnt(0)
	v_mfma_f32_16x16x32_bf16 v[60:63], v[128:131], v[146:149], v[60:63]
	v_mfma_f32_16x16x32_bf16 v[56:59], v[136:139], v[146:149], v[56:59]
	v_mfma_f32_16x16x32_bf16 v[44:47], v[128:131], v[154:157], v[44:47]
	v_mfma_f32_16x16x32_bf16 v[40:43], v[136:139], v[154:157], v[40:43]
	v_mfma_f32_16x16x32_bf16 v[28:31], v[128:131], v[162:165], v[28:31]
	v_mfma_f32_16x16x32_bf16 v[24:27], v[136:139], v[162:165], v[24:27]
	v_mfma_f32_16x16x32_bf16 v[12:15], v[128:131], v[194:197], v[12:15]
	v_mfma_f32_16x16x32_bf16 v[8:11], v[136:139], v[194:197], v[8:11]
	v_mfma_f32_16x16x32_bf16 v[60:63], v[132:135], v[150:153], v[60:63]
	v_mfma_f32_16x16x32_bf16 v[56:59], v[140:143], v[150:153], v[56:59]
	v_mfma_f32_16x16x32_bf16 v[44:47], v[132:135], v[158:161], v[44:47]
	v_mfma_f32_16x16x32_bf16 v[40:43], v[140:143], v[158:161], v[40:43]
	v_mfma_f32_16x16x32_bf16 v[28:31], v[132:135], v[166:169], v[28:31]
	v_mfma_f32_16x16x32_bf16 v[24:27], v[140:143], v[166:169], v[24:27]
	v_mfma_f32_16x16x32_bf16 v[12:15], v[132:135], v[198:201], v[12:15]
	v_mfma_f32_16x16x32_bf16 v[8:11], v[140:143], v[198:201], v[8:11]
	s_barrier
	s_setprio 0
	s_add_u32 s58, s78, s98
	s_addc_u32 s59, s79, 0
	s_add_i32 s27, s27, s84
	v_lshl_add_u64 v[238:239], s[58:59], 0, v[144:145]
	s_mov_b32 m0, s27
	v_lshl_add_u64 v[240:241], s[58:59], 0, v[188:189]
	global_load_lds_dwordx4 v[238:239], off
	s_add_i32 m0, s27, 0x2000
	s_nop 0
	global_load_lds_dwordx4 v[240:241], off
	s_waitcnt vmcnt(6)
	s_setprio 1
	s_barrier
	v_mfma_f32_16x16x32_bf16 v[52:55], v[202:205], v[146:149], v[52:55]
	v_mfma_f32_16x16x32_bf16 v[48:51], v[222:225], v[146:149], v[48:51]
	v_mfma_f32_16x16x32_bf16 v[36:39], v[202:205], v[154:157], v[36:39]
	v_mfma_f32_16x16x32_bf16 v[32:35], v[222:225], v[154:157], v[32:35]
	v_mfma_f32_16x16x32_bf16 v[20:23], v[202:205], v[162:165], v[20:23]
	v_mfma_f32_16x16x32_bf16 v[16:19], v[222:225], v[162:165], v[16:19]
	v_mfma_f32_16x16x32_bf16 v[4:7], v[202:205], v[194:197], v[4:7]
	v_mfma_f32_16x16x32_bf16 v[0:3], v[222:225], v[194:197], v[0:3]
	v_mfma_f32_16x16x32_bf16 v[52:55], v[218:221], v[150:153], v[52:55]
	v_mfma_f32_16x16x32_bf16 v[48:51], v[228:231], v[150:153], v[48:51]
	v_mfma_f32_16x16x32_bf16 v[36:39], v[218:221], v[158:161], v[36:39]
	v_mfma_f32_16x16x32_bf16 v[32:35], v[228:231], v[158:161], v[32:35]
	v_mfma_f32_16x16x32_bf16 v[20:23], v[218:221], v[166:169], v[20:23]
	v_mfma_f32_16x16x32_bf16 v[16:19], v[228:231], v[166:169], v[16:19]
	v_mfma_f32_16x16x32_bf16 v[4:7], v[218:221], v[198:201], v[4:7]
	v_mfma_f32_16x16x32_bf16 v[0:3], v[228:231], v[198:201], v[0:3]
	s_barrier
	s_setprio 0
	s_add_i32 s27, 0, 0x18000
	v_add_u32_e32 v140, s27, v207
	ds_read_b128 v[128:131], v140
	ds_read_b128 v[132:135], v140 offset:1024
	ds_read_b128 v[136:139], v140 offset:2048
	ds_read_b128 v[140:143], v140 offset:3072
	s_add_u32 s44, s44, s98
	s_addc_u32 s45, s45, 0
	s_mov_b32 m0, s87
	v_lshl_add_u64 v[202:203], s[44:45], 0, v[144:145]
	ds_read_b128 v[146:149], v217 offset:32768
	ds_read_b128 v[150:153], v217 offset:33792
	ds_read_b128 v[154:157], v217 offset:34816
	ds_read_b128 v[158:161], v217 offset:35840
	ds_read_b128 v[162:165], v217 offset:36864
	ds_read_b128 v[166:169], v217 offset:37888
	ds_read_b128 v[194:197], v217 offset:38912
	ds_read_b128 v[198:201], v217 offset:39936
	global_load_lds_dwordx4 v[202:203], off
	v_lshl_add_u64 v[202:203], s[44:45], 0, v[188:189]
	s_mov_b32 m0, s80
	s_nop 0
	global_load_lds_dwordx4 v[202:203], off
	s_waitcnt lgkmcnt(8)
	s_setprio 1
	s_barrier
	s_waitcnt lgkmcnt(0)
	v_mfma_f32_16x16x32_bf16 v[124:127], v[128:131], v[146:149], v[124:127]
	v_mfma_f32_16x16x32_bf16 v[120:123], v[136:139], v[146:149], v[120:123]
	v_mfma_f32_16x16x32_bf16 v[108:111], v[128:131], v[154:157], v[108:111]
	v_mfma_f32_16x16x32_bf16 v[104:107], v[136:139], v[154:157], v[104:107]
	v_mfma_f32_16x16x32_bf16 v[92:95], v[128:131], v[162:165], v[92:95]
	v_mfma_f32_16x16x32_bf16 v[88:91], v[136:139], v[162:165], v[88:91]
	v_mfma_f32_16x16x32_bf16 v[76:79], v[128:131], v[194:197], v[76:79]
	v_mfma_f32_16x16x32_bf16 v[72:75], v[136:139], v[194:197], v[72:75]
	v_mfma_f32_16x16x32_bf16 v[124:127], v[132:135], v[150:153], v[124:127]
	v_mfma_f32_16x16x32_bf16 v[120:123], v[140:143], v[150:153], v[120:123]
	v_mfma_f32_16x16x32_bf16 v[108:111], v[132:135], v[158:161], v[108:111]
	v_mfma_f32_16x16x32_bf16 v[104:107], v[140:143], v[158:161], v[104:107]
	v_mfma_f32_16x16x32_bf16 v[92:95], v[132:135], v[166:169], v[92:95]
	v_mfma_f32_16x16x32_bf16 v[88:91], v[140:143], v[166:169], v[88:91]
	v_mfma_f32_16x16x32_bf16 v[76:79], v[132:135], v[198:201], v[76:79]
	v_mfma_f32_16x16x32_bf16 v[72:75], v[140:143], v[198:201], v[72:75]
	s_barrier
	s_setprio 0
	s_add_i32 s27, s27, s84
	v_lshl_add_u64 v[176:177], v[176:177], 0, s[18:19]
	s_mov_b32 m0, s27
	s_nop 0
	global_load_lds_dwordx4 v[176:177], off
	v_lshl_add_u64 v[176:177], v[232:233], 0, s[18:19]
	s_add_i32 m0, s27, 0x2000
	s_nop 0
	global_load_lds_dwordx4 v[176:177], off
	s_add_i32 s44, 0, 0x1c000
	v_add_u32_e32 v228, s44, v207
	ds_read_b128 v[202:205], v228
	ds_read_b128 v[218:221], v228 offset:1024
	ds_read_b128 v[222:225], v228 offset:2048
	ds_read_b128 v[228:231], v228 offset:3072
	s_setprio 1
	s_barrier
	s_waitcnt lgkmcnt(0)
	v_mfma_f32_16x16x32_bf16 v[116:119], v[202:205], v[146:149], v[116:119]
	v_mfma_f32_16x16x32_bf16 v[112:115], v[222:225], v[146:149], v[112:115]
	v_mfma_f32_16x16x32_bf16 v[100:103], v[202:205], v[154:157], v[100:103]
	v_mfma_f32_16x16x32_bf16 v[96:99], v[222:225], v[154:157], v[96:99]
	v_mfma_f32_16x16x32_bf16 v[84:87], v[202:205], v[162:165], v[84:87]
	v_mfma_f32_16x16x32_bf16 v[80:83], v[222:225], v[162:165], v[80:83]
	v_mfma_f32_16x16x32_bf16 v[68:71], v[202:205], v[194:197], v[68:71]
	v_mfma_f32_16x16x32_bf16 v[64:67], v[222:225], v[194:197], v[64:67]
	v_mfma_f32_16x16x32_bf16 v[116:119], v[218:221], v[150:153], v[116:119]
	v_mfma_f32_16x16x32_bf16 v[112:115], v[228:231], v[150:153], v[112:115]
	v_mfma_f32_16x16x32_bf16 v[100:103], v[218:221], v[158:161], v[100:103]
	v_mfma_f32_16x16x32_bf16 v[96:99], v[228:231], v[158:161], v[96:99]
	v_mfma_f32_16x16x32_bf16 v[84:87], v[218:221], v[166:169], v[84:87]
	v_mfma_f32_16x16x32_bf16 v[80:83], v[228:231], v[166:169], v[80:83]
	v_mfma_f32_16x16x32_bf16 v[68:71], v[218:221], v[198:201], v[68:71]
	v_mfma_f32_16x16x32_bf16 v[64:67], v[228:231], v[198:201], v[64:67]
	s_barrier
	s_setprio 0
	s_mov_b32 m0, s30
	v_lshl_add_u64 v[176:177], v[234:235], 0, s[18:19]
	global_load_lds_dwordx4 v[176:177], off
	v_lshl_add_u64 v[176:177], v[236:237], 0, s[18:19]
	s_mov_b32 m0, s31
	s_nop 0
	global_load_lds_dwordx4 v[176:177], off
	ds_read_b128 v[146:149], v217 offset:49152
	ds_read_b128 v[150:153], v217 offset:50176
	ds_read_b128 v[154:157], v217 offset:51200
	ds_read_b128 v[158:161], v217 offset:52224
	ds_read_b128 v[162:165], v217 offset:53248
	ds_read_b128 v[166:169], v217 offset:54272
	ds_read_b128 v[194:197], v217 offset:55296
	ds_read_b128 v[198:201], v217 offset:56320
	s_setprio 1
	s_barrier
	s_waitcnt lgkmcnt(0)
	v_mfma_f32_16x16x32_bf16 v[60:63], v[128:131], v[146:149], v[60:63]
	v_mfma_f32_16x16x32_bf16 v[56:59], v[136:139], v[146:149], v[56:59]
	v_mfma_f32_16x16x32_bf16 v[44:47], v[128:131], v[154:157], v[44:47]
	v_mfma_f32_16x16x32_bf16 v[40:43], v[136:139], v[154:157], v[40:43]
	v_mfma_f32_16x16x32_bf16 v[28:31], v[128:131], v[162:165], v[28:31]
	v_mfma_f32_16x16x32_bf16 v[24:27], v[136:139], v[162:165], v[24:27]
	v_mfma_f32_16x16x32_bf16 v[12:15], v[128:131], v[194:197], v[12:15]
	v_mfma_f32_16x16x32_bf16 v[8:11], v[136:139], v[194:197], v[8:11]
	v_mfma_f32_16x16x32_bf16 v[60:63], v[132:135], v[150:153], v[60:63]
	v_mfma_f32_16x16x32_bf16 v[56:59], v[140:143], v[150:153], v[56:59]
	v_mfma_f32_16x16x32_bf16 v[44:47], v[132:135], v[158:161], v[44:47]
	v_mfma_f32_16x16x32_bf16 v[40:43], v[140:143], v[158:161], v[40:43]
	v_mfma_f32_16x16x32_bf16 v[28:31], v[132:135], v[166:169], v[28:31]
	v_mfma_f32_16x16x32_bf16 v[24:27], v[140:143], v[166:169], v[24:27]
	v_mfma_f32_16x16x32_bf16 v[12:15], v[132:135], v[198:201], v[12:15]
	v_mfma_f32_16x16x32_bf16 v[8:11], v[140:143], v[198:201], v[8:11]
	s_barrier
	s_setprio 0
	s_add_i32 s27, s44, s84
	v_lshl_add_u64 v[128:129], v[238:239], 0, s[18:19]
	s_mov_b32 m0, s27
	s_nop 0
	global_load_lds_dwordx4 v[128:129], off
	v_lshl_add_u64 v[128:129], v[240:241], 0, s[18:19]
	s_add_i32 m0, s27, 0x2000
	s_nop 0
	global_load_lds_dwordx4 v[128:129], off
	s_waitcnt vmcnt(6)
	s_setprio 1
	s_barrier
	v_mfma_f32_16x16x32_bf16 v[52:55], v[202:205], v[146:149], v[52:55]
	v_mfma_f32_16x16x32_bf16 v[48:51], v[222:225], v[146:149], v[48:51]
	v_mfma_f32_16x16x32_bf16 v[36:39], v[202:205], v[154:157], v[36:39]
	v_mfma_f32_16x16x32_bf16 v[32:35], v[222:225], v[154:157], v[32:35]
	v_mfma_f32_16x16x32_bf16 v[20:23], v[202:205], v[162:165], v[20:23]
	v_mfma_f32_16x16x32_bf16 v[16:19], v[222:225], v[162:165], v[16:19]
	v_mfma_f32_16x16x32_bf16 v[4:7], v[202:205], v[194:197], v[4:7]
	v_mfma_f32_16x16x32_bf16 v[0:3], v[222:225], v[194:197], v[0:3]
	v_mfma_f32_16x16x32_bf16 v[52:55], v[218:221], v[150:153], v[52:55]
	v_mfma_f32_16x16x32_bf16 v[48:51], v[228:231], v[150:153], v[48:51]
	v_mfma_f32_16x16x32_bf16 v[36:39], v[218:221], v[158:161], v[36:39]
	v_mfma_f32_16x16x32_bf16 v[32:35], v[228:231], v[158:161], v[32:35]
	v_mfma_f32_16x16x32_bf16 v[20:23], v[218:221], v[166:169], v[20:23]
	v_mfma_f32_16x16x32_bf16 v[16:19], v[228:231], v[166:169], v[16:19]
	v_mfma_f32_16x16x32_bf16 v[4:7], v[218:221], v[198:201], v[4:7]
	v_mfma_f32_16x16x32_bf16 v[0:3], v[228:231], v[198:201], v[0:3]
	s_barrier
	s_setprio 0
	s_add_u32 s42, s42, 0x100
	s_addc_u32 s43, s43, 0
	s_add_u32 s33, s33, 0x100
	s_addc_u32 s37, s37, 0
	s_cmp_ge_u32 s56, s34
	s_mov_b32 s27, s56
	s_cbranch_scc0 .LBB0_196
	v_lshl_add_u32 v194, s11, 8, v206
	v_ashrrev_i32_e32 v195, 31, v194
	v_lshl_or_b32 v196, s10, 8, v216
	v_lshlrev_b64 v[128:129], 11, v[194:195]
	v_ashrrev_i32_e32 v197, 31, v196
	s_and_b64 vcc, exec, s[92:93]
	v_or_b32_e32 v198, 16, v194
	v_lshl_add_u64 v[200:201], s[54:55], 0, v[128:129]
	s_cbranch_vccz .LBB0_215
	v_lshlrev_b64 v[128:129], 12, v[194:195]
	v_lshl_add_u64 v[128:129], s[50:51], 0, v[128:129]
	v_lshlrev_b64 v[130:131], 2, v[196:197]
	v_lshl_add_u64 v[128:129], v[128:129], 0, v[130:131]
	global_load_dwordx4 v[146:149], v[128:129], off offset:16
	global_load_dwordx4 v[150:153], v[128:129], off
	global_load_dwordx4 v[154:157], v[128:129], off offset:528
	global_load_dwordx4 v[158:161], v[128:129], off offset:512
	v_ashrrev_i32_e32 v199, 31, v198
	v_lshlrev_b64 v[128:129], 12, v[198:199]
	v_lshl_add_u64 v[128:129], s[50:51], 0, v[128:129]
	v_lshl_add_u64 v[132:133], v[128:129], 0, v[130:131]
	global_load_dwordx4 v[136:139], v[132:133], off offset:16
	global_load_dwordx4 v[140:143], v[132:133], off
	global_load_dwordx4 v[128:131], v[132:133], off offset:528
	s_nop 0
	global_load_dwordx4 v[132:135], v[132:133], off offset:512
	v_lshl_add_u64 v[166:167], v[196:197], 1, v[200:201]
	s_waitcnt vmcnt(0)
	v_pk_add_f32 v[164:165], v[120:121], v[146:147]
	v_pk_add_f32 v[152:153], v[126:127], v[152:153]
	v_pk_add_f32 v[150:151], v[124:125], v[150:151]
	v_pk_add_f32 v[162:163], v[122:123], v[148:149]
	v_cvt_pk_bf16_f32 v146, v150, v151
	v_cvt_pk_bf16_f32 v147, v152, v153
	v_cvt_pk_bf16_f32 v148, v164, v165
	v_pk_add_f32 v[156:157], v[114:115], v[156:157]
	v_cvt_pk_bf16_f32 v149, v162, v163
	global_store_dwordx4 v[166:167], v[146:149], off
	v_pk_add_f32 v[154:155], v[112:113], v[154:155]
	s_nop 0
	v_mul_f32_e32 v146, v151, v151
	v_mul_f32_e32 v147, v153, v153
	v_fmac_f32_e32 v146, v150, v150
	v_fmac_f32_e32 v147, v152, v152
	v_add_f32_e32 v146, v146, v147
	v_mul_f32_e32 v147, v165, v165
	v_mul_f32_e32 v148, v163, v163
	v_fmac_f32_e32 v147, v164, v164
	v_fmac_f32_e32 v148, v162, v162
	v_add_f32_e32 v147, v147, v148
	v_add_f32_e32 v162, v146, v147
	v_pk_add_f32 v[150:151], v[118:119], v[160:161]
	v_pk_add_f32 v[152:153], v[116:117], v[158:159]
	s_nop 0
	v_cvt_pk_bf16_f32 v146, v152, v153
	v_cvt_pk_bf16_f32 v147, v150, v151
	v_cvt_pk_bf16_f32 v148, v154, v155
	v_cvt_pk_bf16_f32 v149, v156, v157
	global_store_dwordx4 v[166:167], v[146:149], off offset:256
	s_nop 1
	v_mul_f32_e32 v146, v153, v153
	v_mul_f32_e32 v147, v151, v151
	v_fmac_f32_e32 v146, v152, v152
	v_fmac_f32_e32 v147, v150, v150
	v_add_f32_e32 v146, v146, v147
	v_mul_f32_e32 v147, v155, v155
	v_mul_f32_e32 v148, v157, v157
	v_fmac_f32_e32 v147, v154, v154
	v_fmac_f32_e32 v148, v156, v156
	v_add_f32_e32 v147, v147, v148
	v_and_b32_e32 v148, 64, v214
	v_add_f32_e32 v146, v146, v147
	v_xor_b32_e32 v147, 16, v214
	v_add_u32_e32 v148, 64, v148
	v_cmp_lt_i32_e32 vcc, v147, v148
	v_add_f32_e32 v146, v162, v146
	s_nop 0
	v_cndmask_b32_e32 v147, v214, v147, vcc
	v_lshlrev_b32_e32 v218, 2, v147
	ds_bpermute_b32 v147, v218, v146
	s_waitcnt lgkmcnt(0)
	v_add_f32_e32 v146, v146, v147
	v_xor_b32_e32 v147, 32, v214
	v_cmp_lt_i32_e32 vcc, v147, v148
	s_nop 1
	v_cndmask_b32_e32 v147, v214, v147, vcc
	v_lshlrev_b32_e32 v219, 2, v147
	ds_bpermute_b32 v147, v219, v146
	s_and_saveexec_b64 s[42:43], s[38:39]
	s_cbranch_execz .LBB0_200
	s_waitcnt lgkmcnt(0)
	v_add_f32_e32 v146, v146, v147
	v_fma_f32 v146, v146, s91, 0.5
	v_trunc_f32_e32 v146, v146
	v_mul_f32_e32 v147, 0x2f800000, v146
	v_floor_f32_e32 v147, v147
	v_fmac_f32_e32 v146, 0xcf800000, v147
	v_cvt_u32_f32_e32 v146, v146
	v_cvt_u32_f32_e32 v147, v147
	v_lshl_add_u64 v[148:149], v[194:195], 3, s[52:53]
	global_atomic_add_x2 v[148:149], v[146:147], off

.LBB0_325:
	s_ashr_i32 s93, s92, 31
	s_lshl_b64 s[30:31], s[92:93], 19
	s_add_u32 s94, s54, s30
	v_cmp_lt_i64_e32 vcc, s[50:51], v[186:187]
	s_addc_u32 s95, s55, s31
	s_and_b64 s[30:31], vcc, exec
	s_cselect_b32 s1, s95, s53
	s_cselect_b32 s11, s94, s52
	s_ashr_i32 s9, s8, 31
	s_lshl_b64 s[30:31], s[8:9], 19
	s_add_u32 s28, s80, s30
	s_addc_u32 s29, s78, s31
	s_and_b64 s[30:31], vcc, exec
	s_cselect_b32 s25, s29, s73
	s_cselect_b32 s30, s28, s72
	s_add_u32 s52, s52, 0x40080
	s_addc_u32 s53, s53, 0
	s_add_u32 s31, s72, 0x100
	s_addc_u32 s33, s73, 0
	s_mov_b32 s34, -2
	s_add_u32 s27, s52, 0xfffc0080
	s_addc_u32 s35, s53, -1
	s_add_i32 s36, 0, 0x10000
	v_add_u32_e32 v140, s36, v216
	ds_read_b128 v[128:131], v140
	ds_read_b128 v[132:135], v140 offset:1024
	ds_read_b128 v[136:139], v140 offset:2048
	ds_read_b128 v[140:143], v140 offset:3072
	s_cmp_eq_u32 s34, 12
	s_cselect_b32 s75, s1, s35
	s_cselect_b32 s74, s11, s27
	s_cselect_b32 s73, s25, s33
	s_cselect_b32 s72, s30, s31
	v_lshl_add_u64 v[168:169], s[52:53], 0, v[152:153]
	s_add_i32 m0, s83, 0xc000
	ds_read_b128 v[156:159], v217
	ds_read_b128 v[160:163], v217 offset:1024
	ds_read_b128 v[164:167], v217 offset:2048
	ds_read_b128 v[188:191], v217 offset:3072
	ds_read_b128 v[192:195], v217 offset:4096
	ds_read_b128 v[196:199], v217 offset:5120
	ds_read_b128 v[200:203], v217 offset:6144
	ds_read_b128 v[204:207], v217 offset:7168
	global_load_lds_dwordx4 v[168:169], off
	v_lshl_add_u64 v[168:169], s[52:53], 0, v[154:155]
	s_add_i32 m0, s83, 0xe000
	s_nop 0
	global_load_lds_dwordx4 v[168:169], off
	s_waitcnt lgkmcnt(8)
	s_setprio 1
	s_barrier
	s_waitcnt lgkmcnt(0)
	v_mfma_f32_16x16x32_bf16 v[124:127], v[128:131], v[156:159], 0
	v_mfma_f32_16x16x32_bf16 v[120:123], v[136:139], v[156:159], 0
	v_mfma_f32_16x16x32_bf16 v[108:111], v[128:131], v[164:167], 0
	v_mfma_f32_16x16x32_bf16 v[104:107], v[136:139], v[164:167], 0
	v_mfma_f32_16x16x32_bf16 v[92:95], v[128:131], v[192:195], 0
	v_mfma_f32_16x16x32_bf16 v[88:91], v[136:139], v[192:195], 0
	v_mfma_f32_16x16x32_bf16 v[76:79], v[128:131], v[200:203], 0
	v_mfma_f32_16x16x32_bf16 v[72:75], v[136:139], v[200:203], 0
	v_mfma_f32_16x16x32_bf16 v[124:127], v[132:135], v[160:163], v[124:127]
	v_mfma_f32_16x16x32_bf16 v[120:123], v[140:143], v[160:163], v[120:123]
	v_mfma_f32_16x16x32_bf16 v[108:111], v[132:135], v[188:191], v[108:111]
	v_mfma_f32_16x16x32_bf16 v[104:107], v[140:143], v[188:191], v[104:107]
	v_mfma_f32_16x16x32_bf16 v[92:95], v[132:135], v[196:199], v[92:95]
	v_mfma_f32_16x16x32_bf16 v[88:91], v[140:143], v[196:199], v[88:91]
	v_mfma_f32_16x16x32_bf16 v[76:79], v[132:135], v[204:207], v[76:79]
	v_mfma_f32_16x16x32_bf16 v[72:75], v[140:143], v[204:207], v[72:75]
	s_barrier
	s_setprio 0
	s_add_i32 s35, s36, s81
	v_lshl_add_u64 v[168:169], s[72:73], 0, v[148:149]
	s_mov_b32 m0, s35
	s_nop 0
	global_load_lds_dwordx4 v[168:169], off
	v_lshl_add_u64 v[176:177], s[72:73], 0, v[146:147]
	s_add_i32 m0, s35, 0x2000
	s_nop 0
	global_load_lds_dwordx4 v[176:177], off
	s_add_i32 s27, 0, 0x14000
	v_add_u32_e32 v144, s27, v216
	ds_read_b128 v[220:223], v144
	ds_read_b128 v[228:231], v144 offset:1024
	ds_read_b128 v[232:235], v144 offset:2048
	ds_read_b128 v[236:239], v144 offset:3072
	s_setprio 1
	s_barrier
	s_waitcnt lgkmcnt(0)
	v_mfma_f32_16x16x32_bf16 v[116:119], v[220:223], v[156:159], 0
	v_mfma_f32_16x16x32_bf16 v[112:115], v[232:235], v[156:159], 0
	v_mfma_f32_16x16x32_bf16 v[100:103], v[220:223], v[164:167], 0
	v_mfma_f32_16x16x32_bf16 v[96:99], v[232:235], v[164:167], 0
	v_mfma_f32_16x16x32_bf16 v[84:87], v[220:223], v[192:195], 0
	v_mfma_f32_16x16x32_bf16 v[80:83], v[232:235], v[192:195], 0
	v_mfma_f32_16x16x32_bf16 v[68:71], v[220:223], v[200:203], 0
	v_mfma_f32_16x16x32_bf16 v[64:67], v[232:235], v[200:203], 0
	v_mfma_f32_16x16x32_bf16 v[116:119], v[228:231], v[160:163], v[116:119]
	v_mfma_f32_16x16x32_bf16 v[112:115], v[236:239], v[160:163], v[112:115]
	v_mfma_f32_16x16x32_bf16 v[100:103], v[228:231], v[188:191], v[100:103]
	v_mfma_f32_16x16x32_bf16 v[96:99], v[236:239], v[188:191], v[96:99]
	v_mfma_f32_16x16x32_bf16 v[84:87], v[228:231], v[196:199], v[84:87]
	v_mfma_f32_16x16x32_bf16 v[80:83], v[236:239], v[196:199], v[80:83]
	v_mfma_f32_16x16x32_bf16 v[68:71], v[228:231], v[204:207], v[68:71]
	v_mfma_f32_16x16x32_bf16 v[64:67], v[236:239], v[204:207], v[64:67]
	s_barrier
	s_setprio 0
	s_mov_b32 m0, s83
	v_lshl_add_u64 v[224:225], s[74:75], 0, v[148:149]
	global_load_lds_dwordx4 v[224:225], off
	v_lshl_add_u64 v[240:241], s[74:75], 0, v[146:147]
	s_mov_b32 m0, s84
	s_nop 0
	global_load_lds_dwordx4 v[240:241], off
	ds_read_b128 v[156:159], v217 offset:16384
	ds_read_b128 v[160:163], v217 offset:17408
	ds_read_b128 v[164:167], v217 offset:18432
	ds_read_b128 v[188:191], v217 offset:19456
	ds_read_b128 v[192:195], v217 offset:20480
	ds_read_b128 v[196:199], v217 offset:21504
	ds_read_b128 v[200:203], v217 offset:22528
	ds_read_b128 v[204:207], v217 offset:23552
	s_setprio 1
	s_barrier
	s_waitcnt lgkmcnt(0)
	v_mfma_f32_16x16x32_bf16 v[60:63], v[128:131], v[156:159], 0
	v_mfma_f32_16x16x32_bf16 v[56:59], v[136:139], v[156:159], 0
	v_mfma_f32_16x16x32_bf16 v[44:47], v[128:131], v[164:167], 0
	v_mfma_f32_16x16x32_bf16 v[40:43], v[136:139], v[164:167], 0
	v_mfma_f32_16x16x32_bf16 v[28:31], v[128:131], v[192:195], 0
	v_mfma_f32_16x16x32_bf16 v[24:27], v[136:139], v[192:195], 0
	v_mfma_f32_16x16x32_bf16 v[12:15], v[128:131], v[200:203], 0
	v_mfma_f32_16x16x32_bf16 v[8:11], v[136:139], v[200:203], 0
	v_mfma_f32_16x16x32_bf16 v[60:63], v[132:135], v[160:163], v[60:63]
	v_mfma_f32_16x16x32_bf16 v[56:59], v[140:143], v[160:163], v[56:59]
	v_mfma_f32_16x16x32_bf16 v[44:47], v[132:135], v[188:191], v[44:47]
	v_mfma_f32_16x16x32_bf16 v[40:43], v[140:143], v[188:191], v[40:43]
	v_mfma_f32_16x16x32_bf16 v[28:31], v[132:135], v[196:199], v[28:31]
	v_mfma_f32_16x16x32_bf16 v[24:27], v[140:143], v[196:199], v[24:27]
	v_mfma_f32_16x16x32_bf16 v[12:15], v[132:135], v[204:207], v[12:15]
	v_mfma_f32_16x16x32_bf16 v[8:11], v[140:143], v[204:207], v[8:11]
	s_barrier
	s_setprio 0
	s_add_u32 s36, s72, 0x40000
	s_addc_u32 s37, s73, 0
	s_add_i32 s27, s27, s81
	v_lshl_add_u64 v[128:129], s[36:37], 0, v[148:149]
	s_mov_b32 m0, s27
	s_nop 0
	global_load_lds_dwordx4 v[128:129], off
	v_lshl_add_u64 v[128:129], s[36:37], 0, v[146:147]
	s_add_i32 m0, s27, 0x2000
	s_nop 0
	global_load_lds_dwordx4 v[128:129], off
	s_waitcnt vmcnt(6)
	s_setprio 1
	s_barrier
	v_mfma_f32_16x16x32_bf16 v[52:55], v[220:223], v[156:159], 0
	v_mfma_f32_16x16x32_bf16 v[48:51], v[232:235], v[156:159], 0
	v_mfma_f32_16x16x32_bf16 v[36:39], v[220:223], v[164:167], 0
	v_mfma_f32_16x16x32_bf16 v[32:35], v[232:235], v[164:167], 0
	v_mfma_f32_16x16x32_bf16 v[20:23], v[220:223], v[192:195], 0
	v_mfma_f32_16x16x32_bf16 v[16:19], v[232:235], v[192:195], 0
	v_mfma_f32_16x16x32_bf16 v[4:7], v[220:223], v[200:203], 0
	v_mfma_f32_16x16x32_bf16 v[0:3], v[232:235], v[200:203], 0
	v_mfma_f32_16x16x32_bf16 v[52:55], v[228:231], v[160:163], v[52:55]
	v_mfma_f32_16x16x32_bf16 v[48:51], v[236:239], v[160:163], v[48:51]
	v_mfma_f32_16x16x32_bf16 v[36:39], v[228:231], v[188:191], v[36:39]
	v_mfma_f32_16x16x32_bf16 v[32:35], v[236:239], v[188:191], v[32:35]
	v_mfma_f32_16x16x32_bf16 v[20:23], v[228:231], v[196:199], v[20:23]
	v_mfma_f32_16x16x32_bf16 v[16:19], v[236:239], v[196:199], v[16:19]
	v_mfma_f32_16x16x32_bf16 v[4:7], v[228:231], v[204:207], v[4:7]
	v_mfma_f32_16x16x32_bf16 v[0:3], v[236:239], v[204:207], v[0:3]
	s_barrier
	s_setprio 0
	s_add_i32 s27, 0, 0x18000
	v_add_u32_e32 v140, s27, v216
	ds_read_b128 v[128:131], v140
	ds_read_b128 v[132:135], v140 offset:1024
	ds_read_b128 v[136:139], v140 offset:2048
	ds_read_b128 v[140:143], v140 offset:3072
	s_add_u32 s36, s74, 0x40000
	s_addc_u32 s37, s75, 0
	s_mov_b32 m0, s85
	v_lshl_add_u64 v[220:221], s[36:37], 0, v[148:149]
	ds_read_b128 v[156:159], v217 offset:32768
	ds_read_b128 v[160:163], v217 offset:33792
	ds_read_b128 v[164:167], v217 offset:34816
	ds_read_b128 v[188:191], v217 offset:35840
	ds_read_b128 v[192:195], v217 offset:36864
	ds_read_b128 v[196:199], v217 offset:37888
	ds_read_b128 v[200:203], v217 offset:38912
	ds_read_b128 v[204:207], v217 offset:39936
	global_load_lds_dwordx4 v[220:221], off
	v_lshl_add_u64 v[220:221], s[36:37], 0, v[146:147]
	s_mov_b32 m0, s86
	s_nop 0
	global_load_lds_dwordx4 v[220:221], off
	s_waitcnt lgkmcnt(8)
	s_setprio 1
	s_barrier
	s_waitcnt lgkmcnt(0)
	v_mfma_f32_16x16x32_bf16 v[124:127], v[128:131], v[156:159], v[124:127]
	v_mfma_f32_16x16x32_bf16 v[120:123], v[136:139], v[156:159], v[120:123]
	v_mfma_f32_16x16x32_bf16 v[108:111], v[128:131], v[164:167], v[108:111]
	v_mfma_f32_16x16x32_bf16 v[104:107], v[136:139], v[164:167], v[104:107]
	v_mfma_f32_16x16x32_bf16 v[92:95], v[128:131], v[192:195], v[92:95]
	v_mfma_f32_16x16x32_bf16 v[88:91], v[136:139], v[192:195], v[88:91]
	v_mfma_f32_16x16x32_bf16 v[76:79], v[128:131], v[200:203], v[76:79]
	v_mfma_f32_16x16x32_bf16 v[72:75], v[136:139], v[200:203], v[72:75]
	v_mfma_f32_16x16x32_bf16 v[124:127], v[132:135], v[160:163], v[124:127]
	v_mfma_f32_16x16x32_bf16 v[120:123], v[140:143], v[160:163], v[120:123]
	v_mfma_f32_16x16x32_bf16 v[108:111], v[132:135], v[188:191], v[108:111]
	v_mfma_f32_16x16x32_bf16 v[104:107], v[140:143], v[188:191], v[104:107]
	v_mfma_f32_16x16x32_bf16 v[92:95], v[132:135], v[196:199], v[92:95]
	v_mfma_f32_16x16x32_bf16 v[88:91], v[140:143], v[196:199], v[88:91]
	v_mfma_f32_16x16x32_bf16 v[76:79], v[132:135], v[204:207], v[76:79]
	v_mfma_f32_16x16x32_bf16 v[72:75], v[140:143], v[204:207], v[72:75]
	s_barrier
	s_setprio 0
	s_add_i32 s27, s27, s81
	v_lshl_add_u64 v[168:169], v[168:169], 0, s[18:19]
	s_mov_b32 m0, s27
	s_nop 0
	global_load_lds_dwordx4 v[168:169], off
	v_lshl_add_u64 v[168:169], v[176:177], 0, s[18:19]
	s_add_i32 m0, s27, 0x2000
	s_nop 0
	global_load_lds_dwordx4 v[168:169], off
	s_add_i32 s35, 0, 0x1c000
	v_add_u32_e32 v144, s35, v216
	ds_read_b128 v[220:223], v144
	ds_read_b128 v[228:231], v144 offset:1024
	ds_read_b128 v[232:235], v144 offset:2048
	ds_read_b128 v[236:239], v144 offset:3072
	s_setprio 1
	s_barrier
	s_waitcnt lgkmcnt(0)
	v_mfma_f32_16x16x32_bf16 v[116:119], v[220:223], v[156:159], v[116:119]
	v_mfma_f32_16x16x32_bf16 v[112:115], v[232:235], v[156:159], v[112:115]
	v_mfma_f32_16x16x32_bf16 v[100:103], v[220:223], v[164:167], v[100:103]
	v_mfma_f32_16x16x32_bf16 v[96:99], v[232:235], v[164:167], v[96:99]
	v_mfma_f32_16x16x32_bf16 v[84:87], v[220:223], v[192:195], v[84:87]
	v_mfma_f32_16x16x32_bf16 v[80:83], v[232:235], v[192:195], v[80:83]
	v_mfma_f32_16x16x32_bf16 v[68:71], v[220:223], v[200:203], v[68:71]
	v_mfma_f32_16x16x32_bf16 v[64:67], v[232:235], v[200:203], v[64:67]
	v_mfma_f32_16x16x32_bf16 v[116:119], v[228:231], v[160:163], v[116:119]
	v_mfma_f32_16x16x32_bf16 v[112:115], v[236:239], v[160:163], v[112:115]
	v_mfma_f32_16x16x32_bf16 v[100:103], v[228:231], v[188:191], v[100:103]
	v_mfma_f32_16x16x32_bf16 v[96:99], v[236:239], v[188:191], v[96:99]
	v_mfma_f32_16x16x32_bf16 v[84:87], v[228:231], v[196:199], v[84:87]
	v_mfma_f32_16x16x32_bf16 v[80:83], v[236:239], v[196:199], v[80:83]
	v_mfma_f32_16x16x32_bf16 v[68:71], v[228:231], v[204:207], v[68:71]
	v_mfma_f32_16x16x32_bf16 v[64:67], v[236:239], v[204:207], v[64:67]
	s_barrier
	s_setprio 0
	s_mov_b32 m0, s87
	v_lshl_add_u64 v[168:169], v[224:225], 0, s[18:19]
	global_load_lds_dwordx4 v[168:169], off
	v_lshl_add_u64 v[168:169], v[240:241], 0, s[18:19]
	s_mov_b32 m0, s79
	s_nop 0
	global_load_lds_dwordx4 v[168:169], off
	ds_read_b128 v[156:159], v217 offset:49152
	ds_read_b128 v[160:163], v217 offset:50176
	ds_read_b128 v[164:167], v217 offset:51200
	ds_read_b128 v[188:191], v217 offset:52224
	ds_read_b128 v[192:195], v217 offset:53248
	ds_read_b128 v[196:199], v217 offset:54272
	ds_read_b128 v[200:203], v217 offset:55296
	ds_read_b128 v[204:207], v217 offset:56320
	s_setprio 1
	s_barrier
	s_waitcnt lgkmcnt(0)
	v_mfma_f32_16x16x32_bf16 v[60:63], v[128:131], v[156:159], v[60:63]
	v_mfma_f32_16x16x32_bf16 v[56:59], v[136:139], v[156:159], v[56:59]
	v_mfma_f32_16x16x32_bf16 v[44:47], v[128:131], v[164:167], v[44:47]
	v_mfma_f32_16x16x32_bf16 v[40:43], v[136:139], v[164:167], v[40:43]
	v_mfma_f32_16x16x32_bf16 v[28:31], v[128:131], v[192:195], v[28:31]
	v_mfma_f32_16x16x32_bf16 v[24:27], v[136:139], v[192:195], v[24:27]
	v_mfma_f32_16x16x32_bf16 v[12:15], v[128:131], v[200:203], v[12:15]
	v_mfma_f32_16x16x32_bf16 v[8:11], v[136:139], v[200:203], v[8:11]
	v_mfma_f32_16x16x32_bf16 v[60:63], v[132:135], v[160:163], v[60:63]
	v_mfma_f32_16x16x32_bf16 v[56:59], v[140:143], v[160:163], v[56:59]
	v_mfma_f32_16x16x32_bf16 v[44:47], v[132:135], v[188:191], v[44:47]
	v_mfma_f32_16x16x32_bf16 v[40:43], v[140:143], v[188:191], v[40:43]
	v_mfma_f32_16x16x32_bf16 v[28:31], v[132:135], v[196:199], v[28:31]
	v_mfma_f32_16x16x32_bf16 v[24:27], v[140:143], v[196:199], v[24:27]
	v_mfma_f32_16x16x32_bf16 v[12:15], v[132:135], v[204:207], v[12:15]
	v_mfma_f32_16x16x32_bf16 v[8:11], v[140:143], v[204:207], v[8:11]
	s_barrier
	s_setprio 0
	s_add_u32 s36, s72, 0x40080
	s_addc_u32 s37, s73, 0
	s_add_i32 s27, s35, s81
	v_lshl_add_u64 v[128:129], s[36:37], 0, v[148:149]
	s_mov_b32 m0, s27
	s_nop 0
	global_load_lds_dwordx4 v[128:129], off
	v_lshl_add_u64 v[128:129], s[36:37], 0, v[146:147]
	s_add_i32 m0, s27, 0x2000
	s_nop 0
	global_load_lds_dwordx4 v[128:129], off
	s_waitcnt vmcnt(6)
	s_setprio 1
	s_barrier
	v_mfma_f32_16x16x32_bf16 v[52:55], v[220:223], v[156:159], v[52:55]
	v_mfma_f32_16x16x32_bf16 v[48:51], v[232:235], v[156:159], v[48:51]
	v_mfma_f32_16x16x32_bf16 v[36:39], v[220:223], v[164:167], v[36:39]
	v_mfma_f32_16x16x32_bf16 v[32:35], v[232:235], v[164:167], v[32:35]
	v_mfma_f32_16x16x32_bf16 v[20:23], v[220:223], v[192:195], v[20:23]
	v_mfma_f32_16x16x32_bf16 v[16:19], v[232:235], v[192:195], v[16:19]
	v_mfma_f32_16x16x32_bf16 v[4:7], v[220:223], v[200:203], v[4:7]
	v_mfma_f32_16x16x32_bf16 v[0:3], v[232:235], v[200:203], v[0:3]
	v_mfma_f32_16x16x32_bf16 v[52:55], v[228:231], v[160:163], v[52:55]
	v_mfma_f32_16x16x32_bf16 v[48:51], v[236:239], v[160:163], v[48:51]
	v_mfma_f32_16x16x32_bf16 v[36:39], v[228:231], v[188:191], v[36:39]
	v_mfma_f32_16x16x32_bf16 v[32:35], v[236:239], v[188:191], v[32:35]
	v_mfma_f32_16x16x32_bf16 v[20:23], v[228:231], v[196:199], v[20:23]
	v_mfma_f32_16x16x32_bf16 v[16:19], v[236:239], v[196:199], v[16:19]
	v_mfma_f32_16x16x32_bf16 v[4:7], v[228:231], v[204:207], v[4:7]
	v_mfma_f32_16x16x32_bf16 v[0:3], v[236:239], v[204:207], v[0:3]
	s_barrier
	s_setprio 0
	s_add_i32 s34, s34, 2
	s_add_u32 s52, s52, 0x100
	s_addc_u32 s53, s53, 0
	s_add_u32 s31, s31, 0x100
	s_addc_u32 s33, s33, 0
	s_cmp_gt_u32 s34, 13
.LBB0_326:
	v_lshl_add_u64 v[168:169], s[52:53], 0, v[152:153]
	s_add_i32 m0, s83, 0xc000
	s_nop 0
	global_load_lds_dwordx4 v[168:169], off
	v_lshl_add_u64 v[168:169], s[52:53], 0, v[154:155]
	s_add_i32 m0, s83, 0xe000
	s_nop 0
	global_load_lds_dwordx4 v[168:169], off
	s_add_u32 s27, s52, 0xfffc0080
	s_addc_u32 s35, s53, -1
	s_add_i32 s36, 0, 0x10000
	v_add_u32_e32 v140, s36, v216
	ds_read_b128 v[128:131], v140
	ds_read_b128 v[132:135], v140 offset:1024
	ds_read_b128 v[136:139], v140 offset:2048
	ds_read_b128 v[140:143], v140 offset:3072
	s_cmp_eq_u32 s34, 12
	s_cselect_b32 s75, s1, s35
	s_cselect_b32 s74, s11, s27
	s_cselect_b32 s73, s25, s33
	s_cselect_b32 s72, s30, s31
	ds_read_b128 v[156:159], v217
	ds_read_b128 v[160:163], v217 offset:1024
	ds_read_b128 v[164:167], v217 offset:2048
	ds_read_b128 v[188:191], v217 offset:3072
	ds_read_b128 v[192:195], v217 offset:4096
	ds_read_b128 v[196:199], v217 offset:5120
	ds_read_b128 v[200:203], v217 offset:6144
	ds_read_b128 v[204:207], v217 offset:7168
	s_waitcnt lgkmcnt(8)
	s_setprio 1
	s_barrier
	s_waitcnt lgkmcnt(0)
	v_mfma_f32_16x16x32_bf16 v[124:127], v[128:131], v[156:159], v[124:127]
	v_mfma_f32_16x16x32_bf16 v[120:123], v[136:139], v[156:159], v[120:123]
	v_mfma_f32_16x16x32_bf16 v[108:111], v[128:131], v[164:167], v[108:111]
	v_mfma_f32_16x16x32_bf16 v[104:107], v[136:139], v[164:167], v[104:107]
	v_mfma_f32_16x16x32_bf16 v[92:95], v[128:131], v[192:195], v[92:95]
	v_mfma_f32_16x16x32_bf16 v[88:91], v[136:139], v[192:195], v[88:91]
	v_mfma_f32_16x16x32_bf16 v[76:79], v[128:131], v[200:203], v[76:79]
	v_mfma_f32_16x16x32_bf16 v[72:75], v[136:139], v[200:203], v[72:75]
	v_mfma_f32_16x16x32_bf16 v[124:127], v[132:135], v[160:163], v[124:127]
	v_mfma_f32_16x16x32_bf16 v[120:123], v[140:143], v[160:163], v[120:123]
	v_mfma_f32_16x16x32_bf16 v[108:111], v[132:135], v[188:191], v[108:111]
	v_mfma_f32_16x16x32_bf16 v[104:107], v[140:143], v[188:191], v[104:107]
	v_mfma_f32_16x16x32_bf16 v[92:95], v[132:135], v[196:199], v[92:95]
	v_mfma_f32_16x16x32_bf16 v[88:91], v[140:143], v[196:199], v[88:91]
	v_mfma_f32_16x16x32_bf16 v[76:79], v[132:135], v[204:207], v[76:79]
	v_mfma_f32_16x16x32_bf16 v[72:75], v[140:143], v[204:207], v[72:75]
	s_barrier
	s_setprio 0
	s_add_i32 s35, s36, s81
	v_lshl_add_u64 v[168:169], s[72:73], 0, v[148:149]
	s_mov_b32 m0, s35
	s_nop 0
	global_load_lds_dwordx4 v[168:169], off
	v_lshl_add_u64 v[176:177], s[72:73], 0, v[146:147]
	s_add_i32 m0, s35, 0x2000
	s_nop 0
	global_load_lds_dwordx4 v[176:177], off
	s_add_i32 s27, 0, 0x14000
	v_add_u32_e32 v144, s27, v216
	ds_read_b128 v[220:223], v144
	ds_read_b128 v[228:231], v144 offset:1024
	ds_read_b128 v[232:235], v144 offset:2048
	ds_read_b128 v[236:239], v144 offset:3072
	s_setprio 1
	s_barrier
	s_waitcnt lgkmcnt(0)
	v_mfma_f32_16x16x32_bf16 v[116:119], v[220:223], v[156:159], v[116:119]
	v_mfma_f32_16x16x32_bf16 v[112:115], v[232:235], v[156:159], v[112:115]
	v_mfma_f32_16x16x32_bf16 v[100:103], v[220:223], v[164:167], v[100:103]
	v_mfma_f32_16x16x32_bf16 v[96:99], v[232:235], v[164:167], v[96:99]
	v_mfma_f32_16x16x32_bf16 v[84:87], v[220:223], v[192:195], v[84:87]
	v_mfma_f32_16x16x32_bf16 v[80:83], v[232:235], v[192:195], v[80:83]
	v_mfma_f32_16x16x32_bf16 v[68:71], v[220:223], v[200:203], v[68:71]
	v_mfma_f32_16x16x32_bf16 v[64:67], v[232:235], v[200:203], v[64:67]
	v_mfma_f32_16x16x32_bf16 v[116:119], v[228:231], v[160:163], v[116:119]
	v_mfma_f32_16x16x32_bf16 v[112:115], v[236:239], v[160:163], v[112:115]
	v_mfma_f32_16x16x32_bf16 v[100:103], v[228:231], v[188:191], v[100:103]
	v_mfma_f32_16x16x32_bf16 v[96:99], v[236:239], v[188:191], v[96:99]
	v_mfma_f32_16x16x32_bf16 v[84:87], v[228:231], v[196:199], v[84:87]
	v_mfma_f32_16x16x32_bf16 v[80:83], v[236:239], v[196:199], v[80:83]
	v_mfma_f32_16x16x32_bf16 v[68:71], v[228:231], v[204:207], v[68:71]
	v_mfma_f32_16x16x32_bf16 v[64:67], v[236:239], v[204:207], v[64:67]
	s_barrier
	s_setprio 0
	s_mov_b32 m0, s83
	v_lshl_add_u64 v[224:225], s[74:75], 0, v[148:149]
	global_load_lds_dwordx4 v[224:225], off
	v_lshl_add_u64 v[240:241], s[74:75], 0, v[146:147]
	s_mov_b32 m0, s84
	s_nop 0
	global_load_lds_dwordx4 v[240:241], off
	ds_read_b128 v[156:159], v217 offset:16384
	ds_read_b128 v[160:163], v217 offset:17408
	ds_read_b128 v[164:167], v217 offset:18432
	ds_read_b128 v[188:191], v217 offset:19456
	ds_read_b128 v[192:195], v217 offset:20480
	ds_read_b128 v[196:199], v217 offset:21504
	ds_read_b128 v[200:203], v217 offset:22528
	ds_read_b128 v[204:207], v217 offset:23552
	s_setprio 1
	s_barrier
	s_waitcnt lgkmcnt(0)
	v_mfma_f32_16x16x32_bf16 v[60:63], v[128:131], v[156:159], v[60:63]
	v_mfma_f32_16x16x32_bf16 v[56:59], v[136:139], v[156:159], v[56:59]
	v_mfma_f32_16x16x32_bf16 v[44:47], v[128:131], v[164:167], v[44:47]
	v_mfma_f32_16x16x32_bf16 v[40:43], v[136:139], v[164:167], v[40:43]
	v_mfma_f32_16x16x32_bf16 v[28:31], v[128:131], v[192:195], v[28:31]
	v_mfma_f32_16x16x32_bf16 v[24:27], v[136:139], v[192:195], v[24:27]
	v_mfma_f32_16x16x32_bf16 v[12:15], v[128:131], v[200:203], v[12:15]
	v_mfma_f32_16x16x32_bf16 v[8:11], v[136:139], v[200:203], v[8:11]
	v_mfma_f32_16x16x32_bf16 v[60:63], v[132:135], v[160:163], v[60:63]
	v_mfma_f32_16x16x32_bf16 v[56:59], v[140:143], v[160:163], v[56:59]
	v_mfma_f32_16x16x32_bf16 v[44:47], v[132:135], v[188:191], v[44:47]
	v_mfma_f32_16x16x32_bf16 v[40:43], v[140:143], v[188:191], v[40:43]
	v_mfma_f32_16x16x32_bf16 v[28:31], v[132:135], v[196:199], v[28:31]
	v_mfma_f32_16x16x32_bf16 v[24:27], v[140:143], v[196:199], v[24:27]
	v_mfma_f32_16x16x32_bf16 v[12:15], v[132:135], v[204:207], v[12:15]
	v_mfma_f32_16x16x32_bf16 v[8:11], v[140:143], v[204:207], v[8:11]
	s_barrier
	s_setprio 0
	s_add_u32 s36, s72, 0x40000
	s_addc_u32 s37, s73, 0
	s_add_i32 s27, s27, s81
	v_lshl_add_u64 v[128:129], s[36:37], 0, v[148:149]
	s_mov_b32 m0, s27
	s_nop 0
	global_load_lds_dwordx4 v[128:129], off
	v_lshl_add_u64 v[128:129], s[36:37], 0, v[146:147]
	s_add_i32 m0, s27, 0x2000
	s_nop 0
	global_load_lds_dwordx4 v[128:129], off
	s_waitcnt vmcnt(6)
	s_setprio 1
	s_barrier
	v_mfma_f32_16x16x32_bf16 v[52:55], v[220:223], v[156:159], v[52:55]
	v_mfma_f32_16x16x32_bf16 v[48:51], v[232:235], v[156:159], v[48:51]
	v_mfma_f32_16x16x32_bf16 v[36:39], v[220:223], v[164:167], v[36:39]
	v_mfma_f32_16x16x32_bf16 v[32:35], v[232:235], v[164:167], v[32:35]
	v_mfma_f32_16x16x32_bf16 v[20:23], v[220:223], v[192:195], v[20:23]
	v_mfma_f32_16x16x32_bf16 v[16:19], v[232:235], v[192:195], v[16:19]
	v_mfma_f32_16x16x32_bf16 v[4:7], v[220:223], v[200:203], v[4:7]
	v_mfma_f32_16x16x32_bf16 v[0:3], v[232:235], v[200:203], v[0:3]
	v_mfma_f32_16x16x32_bf16 v[52:55], v[228:231], v[160:163], v[52:55]
	v_mfma_f32_16x16x32_bf16 v[48:51], v[236:239], v[160:163], v[48:51]
	v_mfma_f32_16x16x32_bf16 v[36:39], v[228:231], v[188:191], v[36:39]
	v_mfma_f32_16x16x32_bf16 v[32:35], v[236:239], v[188:191], v[32:35]
	v_mfma_f32_16x16x32_bf16 v[20:23], v[228:231], v[196:199], v[20:23]
	v_mfma_f32_16x16x32_bf16 v[16:19], v[236:239], v[196:199], v[16:19]
	v_mfma_f32_16x16x32_bf16 v[4:7], v[228:231], v[204:207], v[4:7]
	v_mfma_f32_16x16x32_bf16 v[0:3], v[236:239], v[204:207], v[0:3]
	s_barrier
	s_setprio 0
	s_add_i32 s27, 0, 0x18000
	v_add_u32_e32 v140, s27, v216
	ds_read_b128 v[128:131], v140
	ds_read_b128 v[132:135], v140 offset:1024
	ds_read_b128 v[136:139], v140 offset:2048
	ds_read_b128 v[140:143], v140 offset:3072
	s_add_u32 s36, s74, 0x40000
	s_addc_u32 s37, s75, 0
	s_mov_b32 m0, s85
	v_lshl_add_u64 v[220:221], s[36:37], 0, v[148:149]
	ds_read_b128 v[156:159], v217 offset:32768
	ds_read_b128 v[160:163], v217 offset:33792
	ds_read_b128 v[164:167], v217 offset:34816
	ds_read_b128 v[188:191], v217 offset:35840
	ds_read_b128 v[192:195], v217 offset:36864
	ds_read_b128 v[196:199], v217 offset:37888
	ds_read_b128 v[200:203], v217 offset:38912
	ds_read_b128 v[204:207], v217 offset:39936
	global_load_lds_dwordx4 v[220:221], off
	v_lshl_add_u64 v[220:221], s[36:37], 0, v[146:147]
	s_mov_b32 m0, s86
	s_nop 0
	global_load_lds_dwordx4 v[220:221], off
	s_waitcnt lgkmcnt(8)
	s_setprio 1
	s_barrier
	s_waitcnt lgkmcnt(0)
	v_mfma_f32_16x16x32_bf16 v[124:127], v[128:131], v[156:159], v[124:127]
	v_mfma_f32_16x16x32_bf16 v[120:123], v[136:139], v[156:159], v[120:123]
	v_mfma_f32_16x16x32_bf16 v[108:111], v[128:131], v[164:167], v[108:111]
	v_mfma_f32_16x16x32_bf16 v[104:107], v[136:139], v[164:167], v[104:107]
	v_mfma_f32_16x16x32_bf16 v[92:95], v[128:131], v[192:195], v[92:95]
	v_mfma_f32_16x16x32_bf16 v[88:91], v[136:139], v[192:195], v[88:91]
	v_mfma_f32_16x16x32_bf16 v[76:79], v[128:131], v[200:203], v[76:79]
	v_mfma_f32_16x16x32_bf16 v[72:75], v[136:139], v[200:203], v[72:75]
	v_mfma_f32_16x16x32_bf16 v[124:127], v[132:135], v[160:163], v[124:127]
	v_mfma_f32_16x16x32_bf16 v[120:123], v[140:143], v[160:163], v[120:123]
	v_mfma_f32_16x16x32_bf16 v[108:111], v[132:135], v[188:191], v[108:111]
	v_mfma_f32_16x16x32_bf16 v[104:107], v[140:143], v[188:191], v[104:107]
	v_mfma_f32_16x16x32_bf16 v[92:95], v[132:135], v[196:199], v[92:95]
	v_mfma_f32_16x16x32_bf16 v[88:91], v[140:143], v[196:199], v[88:91]
	v_mfma_f32_16x16x32_bf16 v[76:79], v[132:135], v[204:207], v[76:79]
	v_mfma_f32_16x16x32_bf16 v[72:75], v[140:143], v[204:207], v[72:75]
	s_barrier
	s_setprio 0
	s_add_i32 s27, s27, s81
	v_lshl_add_u64 v[168:169], v[168:169], 0, s[18:19]
	s_mov_b32 m0, s27
	s_nop 0
	global_load_lds_dwordx4 v[168:169], off
	v_lshl_add_u64 v[168:169], v[176:177], 0, s[18:19]
	s_add_i32 m0, s27, 0x2000
	s_nop 0
	global_load_lds_dwordx4 v[168:169], off
	s_add_i32 s35, 0, 0x1c000
	v_add_u32_e32 v144, s35, v216
	ds_read_b128 v[220:223], v144
	ds_read_b128 v[228:231], v144 offset:1024
	ds_read_b128 v[232:235], v144 offset:2048
	ds_read_b128 v[236:239], v144 offset:3072
	s_setprio 1
	s_barrier
	s_waitcnt lgkmcnt(0)
	v_mfma_f32_16x16x32_bf16 v[116:119], v[220:223], v[156:159], v[116:119]
	v_mfma_f32_16x16x32_bf16 v[112:115], v[232:235], v[156:159], v[112:115]
	v_mfma_f32_16x16x32_bf16 v[100:103], v[220:223], v[164:167], v[100:103]
	v_mfma_f32_16x16x32_bf16 v[96:99], v[232:235], v[164:167], v[96:99]
	v_mfma_f32_16x16x32_bf16 v[84:87], v[220:223], v[192:195], v[84:87]
	v_mfma_f32_16x16x32_bf16 v[80:83], v[232:235], v[192:195], v[80:83]
	v_mfma_f32_16x16x32_bf16 v[68:71], v[220:223], v[200:203], v[68:71]
	v_mfma_f32_16x16x32_bf16 v[64:67], v[232:235], v[200:203], v[64:67]
	v_mfma_f32_16x16x32_bf16 v[116:119], v[228:231], v[160:163], v[116:119]
	v_mfma_f32_16x16x32_bf16 v[112:115], v[236:239], v[160:163], v[112:115]
	v_mfma_f32_16x16x32_bf16 v[100:103], v[228:231], v[188:191], v[100:103]
	v_mfma_f32_16x16x32_bf16 v[96:99], v[236:239], v[188:191], v[96:99]
	v_mfma_f32_16x16x32_bf16 v[84:87], v[228:231], v[196:199], v[84:87]
	v_mfma_f32_16x16x32_bf16 v[80:83], v[236:239], v[196:199], v[80:83]
	v_mfma_f32_16x16x32_bf16 v[68:71], v[228:231], v[204:207], v[68:71]
	v_mfma_f32_16x16x32_bf16 v[64:67], v[236:239], v[204:207], v[64:67]
	s_barrier
	s_setprio 0
	s_mov_b32 m0, s87
	v_lshl_add_u64 v[168:169], v[224:225], 0, s[18:19]
	global_load_lds_dwordx4 v[168:169], off
	v_lshl_add_u64 v[168:169], v[240:241], 0, s[18:19]
	s_mov_b32 m0, s79
	s_nop 0
	global_load_lds_dwordx4 v[168:169], off
	ds_read_b128 v[156:159], v217 offset:49152
	ds_read_b128 v[160:163], v217 offset:50176
	ds_read_b128 v[164:167], v217 offset:51200
	ds_read_b128 v[188:191], v217 offset:52224
	ds_read_b128 v[192:195], v217 offset:53248
	ds_read_b128 v[196:199], v217 offset:54272
	ds_read_b128 v[200:203], v217 offset:55296
	ds_read_b128 v[204:207], v217 offset:56320
	s_setprio 1
	s_barrier
	s_waitcnt lgkmcnt(0)
	v_mfma_f32_16x16x32_bf16 v[60:63], v[128:131], v[156:159], v[60:63]
	v_mfma_f32_16x16x32_bf16 v[56:59], v[136:139], v[156:159], v[56:59]
	v_mfma_f32_16x16x32_bf16 v[44:47], v[128:131], v[164:167], v[44:47]
	v_mfma_f32_16x16x32_bf16 v[40:43], v[136:139], v[164:167], v[40:43]
	v_mfma_f32_16x16x32_bf16 v[28:31], v[128:131], v[192:195], v[28:31]
	v_mfma_f32_16x16x32_bf16 v[24:27], v[136:139], v[192:195], v[24:27]
	v_mfma_f32_16x16x32_bf16 v[12:15], v[128:131], v[200:203], v[12:15]
	v_mfma_f32_16x16x32_bf16 v[8:11], v[136:139], v[200:203], v[8:11]
	v_mfma_f32_16x16x32_bf16 v[60:63], v[132:135], v[160:163], v[60:63]
	v_mfma_f32_16x16x32_bf16 v[56:59], v[140:143], v[160:163], v[56:59]
	v_mfma_f32_16x16x32_bf16 v[44:47], v[132:135], v[188:191], v[44:47]
	v_mfma_f32_16x16x32_bf16 v[40:43], v[140:143], v[188:191], v[40:43]
	v_mfma_f32_16x16x32_bf16 v[28:31], v[132:135], v[196:199], v[28:31]
	v_mfma_f32_16x16x32_bf16 v[24:27], v[140:143], v[196:199], v[24:27]
	v_mfma_f32_16x16x32_bf16 v[12:15], v[132:135], v[204:207], v[12:15]
	v_mfma_f32_16x16x32_bf16 v[8:11], v[140:143], v[204:207], v[8:11]
	s_barrier
	s_setprio 0
	s_add_u32 s36, s72, 0x40080
	s_addc_u32 s37, s73, 0
	s_add_i32 s27, s35, s81
	v_lshl_add_u64 v[128:129], s[36:37], 0, v[148:149]
	s_mov_b32 m0, s27
	s_nop 0
	global_load_lds_dwordx4 v[128:129], off
	v_lshl_add_u64 v[128:129], s[36:37], 0, v[146:147]
	s_add_i32 m0, s27, 0x2000
	s_nop 0
	global_load_lds_dwordx4 v[128:129], off
	s_waitcnt vmcnt(6)
	s_setprio 1
	s_barrier
	v_mfma_f32_16x16x32_bf16 v[52:55], v[220:223], v[156:159], v[52:55]
	v_mfma_f32_16x16x32_bf16 v[48:51], v[232:235], v[156:159], v[48:51]
	v_mfma_f32_16x16x32_bf16 v[36:39], v[220:223], v[164:167], v[36:39]
	v_mfma_f32_16x16x32_bf16 v[32:35], v[232:235], v[164:167], v[32:35]
	v_mfma_f32_16x16x32_bf16 v[20:23], v[220:223], v[192:195], v[20:23]
	v_mfma_f32_16x16x32_bf16 v[16:19], v[232:235], v[192:195], v[16:19]
	v_mfma_f32_16x16x32_bf16 v[4:7], v[220:223], v[200:203], v[4:7]
	v_mfma_f32_16x16x32_bf16 v[0:3], v[232:235], v[200:203], v[0:3]
	v_mfma_f32_16x16x32_bf16 v[52:55], v[228:231], v[160:163], v[52:55]
	v_mfma_f32_16x16x32_bf16 v[48:51], v[236:239], v[160:163], v[48:51]
	v_mfma_f32_16x16x32_bf16 v[36:39], v[228:231], v[188:191], v[36:39]
	v_mfma_f32_16x16x32_bf16 v[32:35], v[236:239], v[188:191], v[32:35]
	v_mfma_f32_16x16x32_bf16 v[20:23], v[228:231], v[196:199], v[20:23]
	v_mfma_f32_16x16x32_bf16 v[16:19], v[236:239], v[196:199], v[16:19]
	v_mfma_f32_16x16x32_bf16 v[4:7], v[228:231], v[204:207], v[4:7]
	v_mfma_f32_16x16x32_bf16 v[0:3], v[236:239], v[204:207], v[0:3]
	s_barrier
	s_setprio 0
	s_add_i32 s34, s34, 2
	s_add_u32 s52, s52, 0x100
	s_addc_u32 s53, s53, 0
	s_add_u32 s31, s31, 0x100
	s_addc_u32 s33, s33, 0
	s_cmp_gt_u32 s34, 13
	s_cbranch_scc0 .LBB0_326
	v_lshl_add_u32 v128, s0, 8, v151
	v_readlane_b32 s0, v252, 36
	v_ashrrev_i32_e32 v129, 31, v128
	v_readlane_b32 s1, v252, 37
	v_or_b32_e32 v132, 16, v128
	v_or_b32_e32 v136, 32, v128
	v_lshl_add_u64 v[130:131], v[128:129], 3, s[0:1]
	v_ashrrev_i32_e32 v133, 31, v132
	v_ashrrev_i32_e32 v137, 31, v136
	v_or_b32_e32 v140, 48, v128
	v_lshl_add_u64 v[134:135], v[132:133], 3, s[0:1]
	v_lshl_add_u64 v[138:139], v[136:137], 3, s[0:1]
	v_ashrrev_i32_e32 v141, 31, v140
	global_load_dwordx2 v[202:203], v[130:131], off
	global_load_dwordx2 v[200:201], v[134:135], off
	global_load_dwordx2 v[192:193], v[138:139], off
	global_load_dwordx2 v[166:167], v[130:131], off offset:1024
	v_add_u32_e32 v164, 0x90, v128
	v_add_u32_e32 v158, 0xa0, v128
	v_add_u32_e32 v156, 0xb0, v128
	v_lshl_add_u64 v[142:143], v[140:141], 3, s[0:1]
	v_ashrrev_i32_e32 v165, 31, v164
	v_ashrrev_i32_e32 v159, 31, v158
	v_ashrrev_i32_e32 v157, 31, v156
	v_lshl_add_u64 v[130:131], v[164:165], 3, s[0:1]
	v_lshl_add_u64 v[134:135], v[158:159], 3, s[0:1]
	v_lshl_add_u64 v[138:139], v[156:157], 3, s[0:1]
	global_load_dwordx2 v[196:197], v[142:143], off
	global_load_dwordx2 v[188:189], v[130:131], off
	global_load_dwordx2 v[162:163], v[134:135], off
	global_load_dwordx2 v[160:161], v[138:139], off
	v_add_u32_e32 v168, 0x80, v128
	s_mov_b64 s[0:1], -1
	s_cmp_gt_u32 s10, 1
	v_lshlrev_b32_e32 v144, 1, v150
	v_ashrrev_i32_e32 v169, 31, v168
	v_lshlrev_b64 v[204:205], 10, v[128:129]
	v_lshlrev_b64 v[198:199], 10, v[132:133]
	v_lshlrev_b64 v[194:195], 10, v[136:137]
	v_lshlrev_b64 v[190:191], 10, v[140:141]
	s_waitcnt vmcnt(0)
	v_ffbh_u32_e32 v222, v203
	v_ffbh_u32_e32 v221, v201
	v_ffbh_u32_e32 v220, v193
	v_ffbh_u32_e32 v219, v197
	s_cbranch_scc0 .LBB0_329
	s_cmp_lt_u32 s10, 4
	s_cselect_b64 vcc, -1, 0
	v_readlane_b32 s56, v254, 23
	s_and_b64 s[0:1], vcc, exec
	v_readlane_b32 s70, v254, 37
	v_readlane_b32 s36, v252, 15
	v_readlane_b32 s71, v254, 38
	v_readlane_b32 s37, v252, 16
	s_cselect_b32 s0, s70, s36
	s_mov_b32 s11, 0x4400000
	v_readlane_b32 s30, v254, 62
	s_cselect_b32 s1, s71, s37
	s_cselect_b32 s11, s11, 0x4800000
	v_readlane_b32 s31, v254, 63
	s_add_u32 s0, s0, s30
	s_addc_u32 s1, s1, s31
	global_load_dwordx4 v[136:139], v218, s[0:1] offset:16
	global_load_dwordx4 v[140:143], v218, s[0:1]
	global_load_dwordx4 v[128:131], v218, s[0:1] offset:144
	global_load_dwordx4 v[132:135], v218, s[0:1] offset:128
	v_and_b32_e32 v177, 64, v214
	v_xor_b32_e32 v176, 16, v214
	v_add_u32_e32 v177, 64, v177
	v_cndmask_b32_e32 v223, 1.0, v215, vcc
	v_cmp_lt_i32_e32 vcc, v176, v177
	v_readlane_b32 s9, v254, 52
	s_add_u32 s11, s9, s11
	v_cndmask_b32_e32 v176, v214, v176, vcc
	v_lshlrev_b32_e32 v225, 2, v176
	v_xor_b32_e32 v176, 32, v214
	v_cmp_lt_i32_e32 vcc, v176, v177
	v_readlane_b32 s9, v254, 61
	s_addc_u32 s25, s9, 0
	v_cndmask_b32_e32 v176, v214, v176, vcc
	v_lshlrev_b32_e32 v224, 2, v176
	v_min_u32_e32 v176, 32, v222
	v_lshlrev_b64 v[228:229], v176, v[202:203]
	v_min_u32_e32 v177, 1, v228
	v_or_b32_e32 v177, v229, v177
	v_cvt_f32_u32_e32 v177, v177
	v_sub_u32_e32 v176, 32, v176
	s_lshl_b32 s0, s10, 9
	s_and_b32 s0, s0, 0x200
	v_ldexp_f32 v176, v177, v176
	v_mul_f32_e32 v176, 0x35800000, v176
	v_fmamk_f32 v176, v176, 0x3a800000, v210
	s_add_u32 s0, s11, s0
	v_rsq_f32_e32 v176, v176
	s_addc_u32 s1, s25, 0
	v_lshl_add_u64 v[206:207], s[0:1], 0, v[144:145]
	v_readlane_b32 s48, v252, 27
	v_mov_b32_e32 v228, v176
	v_pk_mul_f32 v[230:231], v[124:125], v[228:229] op_sel_hi:[1,0]
	v_pk_mul_f32 v[232:233], v[126:127], v[228:229] op_sel_hi:[1,0]
	v_pk_mul_f32 v[236:237], v[230:231], v[230:231]
	v_pk_mul_f32 v[234:235], v[232:233], v[232:233]
	v_pk_mul_f32 v[250:251], v[114:115], v[228:229] op_sel_hi:[1,0]
	v_pk_mov_b32 v[238:239], v[236:237], v[234:235] op_sel:[1,0]
	v_mov_b32_e32 v237, v235
	v_pk_add_f32 v[234:235], v[238:239], v[236:237]
	v_pk_mul_f32 v[236:237], v[120:121], v[228:229] op_sel_hi:[1,0]
	v_pk_mul_f32 v[238:239], v[122:123], v[228:229] op_sel_hi:[1,0]
	v_pk_mul_f32 v[242:243], v[236:237], v[236:237]
	v_pk_mul_f32 v[240:241], v[238:239], v[238:239]
	v_pk_add_f32 v[234:235], v[234:235], v[234:235] op_sel_hi:[0,1]
	v_pk_mov_b32 v[244:245], v[242:243], v[240:241] op_sel:[1,0]
	v_mov_b32_e32 v243, v241
	v_pk_add_f32 v[240:241], v[244:245], v[242:243]
	v_pk_mul_f32 v[244:245], v[116:117], v[228:229] op_sel_hi:[1,0]
	v_pk_mul_f32 v[242:243], v[118:119], v[228:229] op_sel_hi:[1,0]
	v_mul_f32_e32 v234, v244, v244
	v_pk_fma_f32 v[246:247], v[244:245], v[244:245], v[234:235] op_sel_hi:[1,1,0]
	v_mul_f32_e32 v234, v242, v242
	v_pk_add_f32 v[240:241], v[240:241], v[240:241] op_sel_hi:[0,1]
	v_pk_fma_f32 v[248:249], v[242:243], v[242:243], v[234:235] op_sel_hi:[1,1,0]
	v_pk_mul_f32 v[176:177], v[112:113], v[228:229] op_sel_hi:[1,0]
	v_mul_f32_e32 v234, v250, v250
	v_mul_f32_e32 v246, v176, v176
	v_mul_f32_e32 v248, v177, v177
	v_mul_f32_e32 v240, v251, v251
	v_pk_add_f32 v[228:229], v[246:247], v[248:249]
	v_pk_add_f32 v[234:235], v[234:235], v[240:241]
	v_lshl_add_u64 v[240:241], v[206:207], 0, v[204:205]
	v_pk_add_f32 v[228:229], v[228:229], v[234:235]
	v_readlane_b32 s57, v254, 24
	v_add_f32_e32 v228, v228, v229
	ds_bpermute_b32 v229, v225, v228
	v_readlane_b32 s58, v254, 25
	v_readlane_b32 s59, v254, 26
	v_readlane_b32 s60, v254, 27
	v_readlane_b32 s61, v254, 28
	s_waitcnt lgkmcnt(0)
	v_add_f32_e32 v228, v228, v229
	ds_bpermute_b32 v229, v224, v228
	v_readlane_b32 s62, v254, 29
	v_readlane_b32 s63, v254, 30
	v_readlane_b32 s64, v254, 31
	v_readlane_b32 s65, v254, 32
	s_waitcnt lgkmcnt(0)
	v_add_f32_e32 v228, v228, v229
	v_fmamk_f32 v228, v228, 0x3c800000, v210
	v_readlane_b32 s66, v254, 33
	v_rsq_f32_e32 v228, v228
	v_readlane_b32 s67, v254, 34
	v_readlane_b32 s68, v254, 35
	v_readlane_b32 s69, v254, 36
	v_mul_f32_e32 v234, v223, v228
	v_pk_mul_f32 v[228:229], v[230:231], v[234:235] op_sel_hi:[1,0]
	v_pk_mul_f32 v[230:231], v[232:233], v[234:235] op_sel_hi:[1,0]
	s_waitcnt vmcnt(2)
	v_pk_mul_f32 v[228:229], v[140:141], v[228:229]
	v_pk_mul_f32 v[230:231], v[142:143], v[230:231]
	v_pk_mul_f32 v[232:233], v[236:237], v[234:235] op_sel_hi:[1,0]
	v_pk_mul_f32 v[236:237], v[238:239], v[234:235] op_sel_hi:[1,0]
	v_cvt_pk_bf16_f32 v228, v228, v229
	v_cvt_pk_bf16_f32 v229, v230, v231
	v_pk_mul_f32 v[232:233], v[136:137], v[232:233]
	v_pk_mul_f32 v[236:237], v[138:139], v[236:237]
	v_cvt_pk_bf16_f32 v230, v232, v233
	v_pk_mul_f32 v[176:177], v[176:177], v[234:235] op_sel_hi:[1,0]
	v_cvt_pk_bf16_f32 v231, v236, v237
	global_store_dwordx4 v[240:241], v[228:231], off
	v_pk_mul_f32 v[232:233], v[250:251], v[234:235] op_sel_hi:[1,0]
	s_waitcnt vmcnt(2)
	v_pk_mul_f32 v[176:177], v[128:129], v[176:177]
	v_pk_mul_f32 v[228:229], v[244:245], v[234:235] op_sel_hi:[1,0]
	v_pk_mul_f32 v[230:231], v[242:243], v[234:235] op_sel_hi:[1,0]
	s_waitcnt vmcnt(1)
	v_pk_mul_f32 v[228:229], v[132:133], v[228:229]
	v_pk_mul_f32 v[230:231], v[134:135], v[230:231]
	v_cvt_pk_bf16_f32 v228, v228, v229
	v_pk_mul_f32 v[232:233], v[130:131], v[232:233]
	v_cvt_pk_bf16_f32 v229, v230, v231
	v_cvt_pk_bf16_f32 v230, v176, v177
	s_nop 1
	v_readlane_b32 s38, v252, 17
	v_cvt_pk_bf16_f32 v231, v232, v233
	s_nop 1
	global_store_dwordx4 v[240:241], v[228:231], off offset:64
	v_readlane_b32 s39, v252, 18
	v_readlane_b32 s40, v252, 19
	v_min_u32_e32 v228, 32, v221
	v_lshlrev_b64 v[176:177], v228, v[200:201]
	v_min_u32_e32 v176, 1, v176
	v_or_b32_e32 v176, v177, v176
	v_cvt_f32_u32_e32 v176, v176
	v_sub_u32_e32 v177, 32, v228
	v_readlane_b32 s41, v252, 20
	v_readlane_b32 s42, v252, 21
	v_ldexp_f32 v176, v176, v177
	v_mul_f32_e32 v176, 0x35800000, v176
	v_fmamk_f32 v176, v176, 0x3a800000, v210
	v_readlane_b32 s43, v252, 22
	v_rsq_f32_e32 v176, v176
	v_readlane_b32 s44, v252, 23
	v_readlane_b32 s45, v252, 24
	v_readlane_b32 s46, v252, 25
	v_pk_mul_f32 v[228:229], v[108:109], v[176:177] op_sel_hi:[1,0]
	v_pk_mul_f32 v[230:231], v[110:111], v[176:177] op_sel_hi:[1,0]
	v_pk_mul_f32 v[234:235], v[228:229], v[228:229]
	v_pk_mul_f32 v[232:233], v[230:231], v[230:231]
	v_pk_mul_f32 v[248:249], v[98:99], v[176:177] op_sel_hi:[1,0]
	v_pk_mov_b32 v[236:237], v[234:235], v[232:233] op_sel:[1,0]
	v_mov_b32_e32 v235, v233
	v_pk_add_f32 v[232:233], v[236:237], v[234:235]
	v_pk_mul_f32 v[234:235], v[104:105], v[176:177] op_sel_hi:[1,0]
	v_pk_mul_f32 v[236:237], v[106:107], v[176:177] op_sel_hi:[1,0]
	v_pk_mul_f32 v[240:241], v[234:235], v[234:235]
	v_pk_mul_f32 v[238:239], v[236:237], v[236:237]
	v_pk_add_f32 v[232:233], v[232:233], v[232:233] op_sel_hi:[0,1]
	v_pk_mov_b32 v[242:243], v[240:241], v[238:239] op_sel:[1,0]
	v_mov_b32_e32 v241, v239
	v_pk_add_f32 v[238:239], v[242:243], v[240:241]
	v_pk_mul_f32 v[242:243], v[100:101], v[176:177] op_sel_hi:[1,0]
	v_pk_mul_f32 v[240:241], v[102:103], v[176:177] op_sel_hi:[1,0]
	v_mul_f32_e32 v232, v242, v242
	v_pk_fma_f32 v[244:245], v[242:243], v[242:243], v[232:233] op_sel_hi:[1,1,0]
	v_mul_f32_e32 v232, v240, v240
	v_pk_add_f32 v[238:239], v[238:239], v[238:239] op_sel_hi:[0,1]
	v_pk_fma_f32 v[246:247], v[240:241], v[240:241], v[232:233] op_sel_hi:[1,1,0]
	v_pk_mul_f32 v[176:177], v[96:97], v[176:177] op_sel_hi:[1,0]
	v_mul_f32_e32 v232, v248, v248
	v_mul_f32_e32 v244, v176, v176
	v_mul_f32_e32 v246, v177, v177
	v_mul_f32_e32 v238, v249, v249
	v_pk_add_f32 v[244:245], v[244:245], v[246:247]
	v_pk_add_f32 v[232:233], v[232:233], v[238:239]
	v_lshl_add_u64 v[238:239], v[206:207], 0, v[198:199]
	v_pk_add_f32 v[232:233], v[244:245], v[232:233]
	v_readlane_b32 s47, v252, 26
	v_add_f32_e32 v232, v232, v233
	ds_bpermute_b32 v233, v225, v232
	v_readlane_b32 s49, v252, 28
	v_readlane_b32 s50, v252, 29
	v_readlane_b32 s51, v252, 30
	v_readlane_b32 s48, v252, 40
	s_waitcnt lgkmcnt(0)
	v_add_f32_e32 v232, v232, v233
	ds_bpermute_b32 v233, v224, v232
	s_mov_b64 s[0:1], 0
	s_waitcnt lgkmcnt(0)
	v_add_f32_e32 v232, v232, v233
	v_fmamk_f32 v232, v232, 0x3c800000, v210
	s_nop 0
	v_rsq_f32_e32 v232, v232
	s_nop 0
	v_mul_f32_e32 v232, v223, v232
	v_pk_mul_f32 v[228:229], v[228:229], v[232:233] op_sel_hi:[1,0]
	v_pk_mul_f32 v[230:231], v[230:231], v[232:233] op_sel_hi:[1,0]
	v_pk_mul_f32 v[228:229], v[140:141], v[228:229]
	v_pk_mul_f32 v[230:231], v[142:143], v[230:231]
	v_pk_mul_f32 v[234:235], v[234:235], v[232:233] op_sel_hi:[1,0]
	v_pk_mul_f32 v[236:237], v[236:237], v[232:233] op_sel_hi:[1,0]
	v_cvt_pk_bf16_f32 v228, v228, v229
	v_cvt_pk_bf16_f32 v229, v230, v231
	v_pk_mul_f32 v[234:235], v[136:137], v[234:235]
	v_pk_mul_f32 v[236:237], v[138:139], v[236:237]
	v_cvt_pk_bf16_f32 v230, v234, v235
	v_pk_mul_f32 v[176:177], v[176:177], v[232:233] op_sel_hi:[1,0]
	v_cvt_pk_bf16_f32 v231, v236, v237
	global_store_dwordx4 v[238:239], v[228:231], off
	v_pk_mul_f32 v[176:177], v[128:129], v[176:177]
	s_nop 0
	v_pk_mul_f32 v[228:229], v[242:243], v[232:233] op_sel_hi:[1,0]
	v_pk_mul_f32 v[230:231], v[240:241], v[232:233] op_sel_hi:[1,0]
	v_pk_mul_f32 v[228:229], v[132:133], v[228:229]
	v_pk_mul_f32 v[230:231], v[134:135], v[230:231]
	v_pk_mul_f32 v[232:233], v[248:249], v[232:233] op_sel_hi:[1,0]
	v_cvt_pk_bf16_f32 v228, v228, v229
	v_cvt_pk_bf16_f32 v229, v230, v231
	v_cvt_pk_bf16_f32 v230, v176, v177
	s_nop 0
	v_pk_mul_f32 v[232:233], v[130:131], v[232:233]
	s_nop 0
	v_cvt_pk_bf16_f32 v231, v232, v233
	global_store_dwordx4 v[238:239], v[228:231], off offset:64
	s_nop 1
	v_min_u32_e32 v228, 32, v220
	v_lshlrev_b64 v[176:177], v228, v[192:193]
	v_min_u32_e32 v176, 1, v176
	v_or_b32_e32 v176, v177, v176
	v_cvt_f32_u32_e32 v176, v176
	v_sub_u32_e32 v177, 32, v228
	v_ldexp_f32 v176, v176, v177
	v_mul_f32_e32 v176, 0x35800000, v176
	v_fmamk_f32 v176, v176, 0x3a800000, v210
	s_nop 0
	v_rsq_f32_e32 v176, v176
	s_nop 0
	v_pk_mul_f32 v[228:229], v[92:93], v[176:177] op_sel_hi:[1,0]
	v_pk_mul_f32 v[230:231], v[94:95], v[176:177] op_sel_hi:[1,0]
	v_pk_mul_f32 v[234:235], v[228:229], v[228:229]
	v_pk_mul_f32 v[232:233], v[230:231], v[230:231]
	v_pk_mul_f32 v[248:249], v[82:83], v[176:177] op_sel_hi:[1,0]
	v_pk_mov_b32 v[236:237], v[234:235], v[232:233] op_sel:[1,0]
	v_mov_b32_e32 v235, v233
	v_pk_add_f32 v[232:233], v[236:237], v[234:235]
	v_pk_mul_f32 v[234:235], v[88:89], v[176:177] op_sel_hi:[1,0]
	v_pk_mul_f32 v[236:237], v[90:91], v[176:177] op_sel_hi:[1,0]
	v_pk_mul_f32 v[240:241], v[234:235], v[234:235]
	v_pk_mul_f32 v[238:239], v[236:237], v[236:237]
	v_pk_add_f32 v[232:233], v[232:233], v[232:233] op_sel_hi:[0,1]
	v_pk_mov_b32 v[242:243], v[240:241], v[238:239] op_sel:[1,0]
	v_mov_b32_e32 v241, v239
	v_pk_add_f32 v[238:239], v[242:243], v[240:241]
	v_pk_mul_f32 v[242:243], v[84:85], v[176:177] op_sel_hi:[1,0]
	v_pk_mul_f32 v[240:241], v[86:87], v[176:177] op_sel_hi:[1,0]
	v_mul_f32_e32 v232, v242, v242
	v_pk_fma_f32 v[244:245], v[242:243], v[242:243], v[232:233] op_sel_hi:[1,1,0]
	v_mul_f32_e32 v232, v240, v240
	v_pk_add_f32 v[238:239], v[238:239], v[238:239] op_sel_hi:[0,1]
	v_pk_fma_f32 v[246:247], v[240:241], v[240:241], v[232:233] op_sel_hi:[1,1,0]
	v_pk_mul_f32 v[176:177], v[80:81], v[176:177] op_sel_hi:[1,0]
	v_mul_f32_e32 v232, v248, v248
	v_mul_f32_e32 v244, v176, v176
	v_mul_f32_e32 v246, v177, v177
	v_mul_f32_e32 v238, v249, v249
	v_pk_add_f32 v[244:245], v[244:245], v[246:247]
	v_pk_add_f32 v[232:233], v[232:233], v[238:239]
	v_lshl_add_u64 v[238:239], v[206:207], 0, v[194:195]
	v_pk_add_f32 v[232:233], v[244:245], v[232:233]
	s_nop 0
	v_add_f32_e32 v232, v232, v233
	ds_bpermute_b32 v233, v225, v232
	s_waitcnt lgkmcnt(0)
	v_add_f32_e32 v232, v232, v233
	ds_bpermute_b32 v233, v224, v232
	s_waitcnt lgkmcnt(0)
	v_add_f32_e32 v232, v232, v233
	v_fmamk_f32 v232, v232, 0x3c800000, v210
	s_nop 0
	v_rsq_f32_e32 v232, v232
	s_nop 0
	v_mul_f32_e32 v232, v223, v232
	v_pk_mul_f32 v[228:229], v[228:229], v[232:233] op_sel_hi:[1,0]
	v_pk_mul_f32 v[230:231], v[230:231], v[232:233] op_sel_hi:[1,0]
	v_pk_mul_f32 v[228:229], v[140:141], v[228:229]
	v_pk_mul_f32 v[230:231], v[142:143], v[230:231]
	v_pk_mul_f32 v[234:235], v[234:235], v[232:233] op_sel_hi:[1,0]
	v_pk_mul_f32 v[236:237], v[236:237], v[232:233] op_sel_hi:[1,0]
	v_cvt_pk_bf16_f32 v228, v228, v229
	v_cvt_pk_bf16_f32 v229, v230, v231
	v_pk_mul_f32 v[234:235], v[136:137], v[234:235]
	v_pk_mul_f32 v[236:237], v[138:139], v[236:237]
	v_cvt_pk_bf16_f32 v230, v234, v235
	v_pk_mul_f32 v[176:177], v[176:177], v[232:233] op_sel_hi:[1,0]
	v_cvt_pk_bf16_f32 v231, v236, v237
	global_store_dwordx4 v[238:239], v[228:231], off
	v_pk_mul_f32 v[176:177], v[128:129], v[176:177]
	s_nop 0
	v_pk_mul_f32 v[228:229], v[242:243], v[232:233] op_sel_hi:[1,0]
	v_pk_mul_f32 v[230:231], v[240:241], v[232:233] op_sel_hi:[1,0]
	v_pk_mul_f32 v[228:229], v[132:133], v[228:229]
	v_pk_mul_f32 v[230:231], v[134:135], v[230:231]
	v_pk_mul_f32 v[232:233], v[248:249], v[232:233] op_sel_hi:[1,0]
	v_cvt_pk_bf16_f32 v228, v228, v229
	v_cvt_pk_bf16_f32 v229, v230, v231
	v_cvt_pk_bf16_f32 v230, v176, v177
	s_nop 0
	v_pk_mul_f32 v[232:233], v[130:131], v[232:233]
	s_nop 0
	v_cvt_pk_bf16_f32 v231, v232, v233
	global_store_dwordx4 v[238:239], v[228:231], off offset:64
	s_nop 1
	v_min_u32_e32 v228, 32, v219
	v_lshlrev_b64 v[176:177], v228, v[196:197]
	v_min_u32_e32 v176, 1, v176
	v_or_b32_e32 v176, v177, v176
	v_cvt_f32_u32_e32 v176, v176
	v_sub_u32_e32 v177, 32, v228
	v_ldexp_f32 v176, v176, v177
	v_mul_f32_e32 v176, 0x35800000, v176
	v_fmamk_f32 v176, v176, 0x3a800000, v210
	s_nop 0
	v_rsq_f32_e32 v176, v176
	s_nop 0
	v_pk_mul_f32 v[228:229], v[76:77], v[176:177] op_sel_hi:[1,0]
	v_pk_mul_f32 v[230:231], v[78:79], v[176:177] op_sel_hi:[1,0]
	v_pk_mul_f32 v[234:235], v[228:229], v[228:229]
	v_pk_mul_f32 v[232:233], v[230:231], v[230:231]
	v_pk_mul_f32 v[248:249], v[66:67], v[176:177] op_sel_hi:[1,0]
	v_pk_mov_b32 v[236:237], v[234:235], v[232:233] op_sel:[1,0]
	v_mov_b32_e32 v235, v233
	v_pk_add_f32 v[232:233], v[236:237], v[234:235]
	v_pk_mul_f32 v[234:235], v[72:73], v[176:177] op_sel_hi:[1,0]
	v_pk_mul_f32 v[236:237], v[74:75], v[176:177] op_sel_hi:[1,0]
	v_pk_mul_f32 v[240:241], v[234:235], v[234:235]
	v_pk_mul_f32 v[238:239], v[236:237], v[236:237]
	v_pk_add_f32 v[232:233], v[232:233], v[232:233] op_sel_hi:[0,1]
	v_pk_mov_b32 v[242:243], v[240:241], v[238:239] op_sel:[1,0]
	v_mov_b32_e32 v241, v239
	v_pk_add_f32 v[238:239], v[242:243], v[240:241]
	v_pk_mul_f32 v[242:243], v[68:69], v[176:177] op_sel_hi:[1,0]
	v_pk_mul_f32 v[240:241], v[70:71], v[176:177] op_sel_hi:[1,0]
	v_mul_f32_e32 v232, v242, v242
	v_pk_fma_f32 v[244:245], v[242:243], v[242:243], v[232:233] op_sel_hi:[1,1,0]
	v_mul_f32_e32 v232, v240, v240
	v_pk_add_f32 v[238:239], v[238:239], v[238:239] op_sel_hi:[0,1]
	v_pk_fma_f32 v[246:247], v[240:241], v[240:241], v[232:233] op_sel_hi:[1,1,0]
	v_pk_mul_f32 v[176:177], v[64:65], v[176:177] op_sel_hi:[1,0]
	v_mul_f32_e32 v232, v248, v248
	v_mul_f32_e32 v244, v176, v176
	v_mul_f32_e32 v246, v177, v177
	v_mul_f32_e32 v238, v249, v249
	v_pk_add_f32 v[244:245], v[244:245], v[246:247]
	v_pk_add_f32 v[232:233], v[232:233], v[238:239]
	v_lshl_add_u64 v[238:239], v[206:207], 0, v[190:191]
	v_pk_add_f32 v[232:233], v[244:245], v[232:233]
	s_nop 0
	v_add_f32_e32 v232, v232, v233
	ds_bpermute_b32 v233, v225, v232
	s_waitcnt lgkmcnt(0)
	v_add_f32_e32 v232, v232, v233
	ds_bpermute_b32 v233, v224, v232
	s_waitcnt lgkmcnt(0)
	v_add_f32_e32 v232, v232, v233
	v_fmamk_f32 v232, v232, 0x3c800000, v210
	s_nop 0
	v_rsq_f32_e32 v232, v232
	s_nop 0
	v_mul_f32_e32 v232, v223, v232
	v_pk_mul_f32 v[228:229], v[228:229], v[232:233] op_sel_hi:[1,0]
	v_pk_mul_f32 v[230:231], v[230:231], v[232:233] op_sel_hi:[1,0]
	v_pk_mul_f32 v[228:229], v[140:141], v[228:229]
	v_pk_mul_f32 v[230:231], v[142:143], v[230:231]
	v_pk_mul_f32 v[234:235], v[234:235], v[232:233] op_sel_hi:[1,0]
	v_pk_mul_f32 v[236:237], v[236:237], v[232:233] op_sel_hi:[1,0]
	v_pk_mul_f32 v[234:235], v[136:137], v[234:235]
	v_pk_mul_f32 v[236:237], v[138:139], v[236:237]
	v_cvt_pk_bf16_f32 v228, v228, v229
	v_cvt_pk_bf16_f32 v229, v230, v231
	v_cvt_pk_bf16_f32 v230, v234, v235
	v_pk_mul_f32 v[176:177], v[176:177], v[232:233] op_sel_hi:[1,0]
	v_cvt_pk_bf16_f32 v231, v236, v237
	global_store_dwordx4 v[238:239], v[228:231], off
	v_pk_mul_f32 v[176:177], v[128:129], v[176:177]
	s_nop 0
	v_pk_mul_f32 v[228:229], v[242:243], v[232:233] op_sel_hi:[1,0]
	v_pk_mul_f32 v[230:231], v[240:241], v[232:233] op_sel_hi:[1,0]
	v_pk_mul_f32 v[228:229], v[132:133], v[228:229]
	v_pk_mul_f32 v[230:231], v[134:135], v[230:231]
	v_pk_mul_f32 v[232:233], v[248:249], v[232:233] op_sel_hi:[1,0]
	v_cvt_pk_bf16_f32 v228, v228, v229
	v_cvt_pk_bf16_f32 v229, v230, v231
	v_cvt_pk_bf16_f32 v230, v176, v177
	v_ffbh_u32_e32 v176, v167
	v_pk_mul_f32 v[232:233], v[130:131], v[232:233]
	s_nop 0
	v_cvt_pk_bf16_f32 v231, v232, v233
	global_store_dwordx4 v[238:239], v[228:231], off offset:64
	s_nop 1
	v_min_u32_e32 v228, 32, v176
	v_lshlrev_b64 v[176:177], v228, v[166:167]
	v_min_u32_e32 v176, 1, v176
	v_or_b32_e32 v176, v177, v176
	v_cvt_f32_u32_e32 v176, v176
	v_sub_u32_e32 v177, 32, v228
	v_ldexp_f32 v176, v176, v177
	v_mul_f32_e32 v176, 0x35800000, v176
	v_fmamk_f32 v176, v176, 0x3a800000, v210
	s_nop 0
	v_rsq_f32_e32 v176, v176
	s_nop 0
	v_pk_mul_f32 v[228:229], v[60:61], v[176:177] op_sel_hi:[1,0]
	v_pk_mul_f32 v[230:231], v[62:63], v[176:177] op_sel_hi:[1,0]
	v_pk_mul_f32 v[234:235], v[228:229], v[228:229]
	v_pk_mul_f32 v[232:233], v[230:231], v[230:231]
	v_pk_mul_f32 v[248:249], v[50:51], v[176:177] op_sel_hi:[1,0]
	v_pk_mov_b32 v[236:237], v[234:235], v[232:233] op_sel:[1,0]
	v_mov_b32_e32 v235, v233
	v_pk_add_f32 v[232:233], v[236:237], v[234:235]
	v_pk_mul_f32 v[234:235], v[56:57], v[176:177] op_sel_hi:[1,0]
	v_pk_mul_f32 v[236:237], v[58:59], v[176:177] op_sel_hi:[1,0]
	v_pk_mul_f32 v[240:241], v[234:235], v[234:235]
	v_pk_mul_f32 v[238:239], v[236:237], v[236:237]
	v_pk_add_f32 v[232:233], v[232:233], v[232:233] op_sel_hi:[0,1]
	v_pk_mov_b32 v[242:243], v[240:241], v[238:239] op_sel:[1,0]
	v_mov_b32_e32 v241, v239
	v_pk_add_f32 v[238:239], v[242:243], v[240:241]
	v_pk_mul_f32 v[242:243], v[52:53], v[176:177] op_sel_hi:[1,0]
	v_pk_mul_f32 v[240:241], v[54:55], v[176:177] op_sel_hi:[1,0]
	v_mul_f32_e32 v232, v242, v242
	v_pk_fma_f32 v[244:245], v[242:243], v[242:243], v[232:233] op_sel_hi:[1,1,0]
	v_mul_f32_e32 v232, v240, v240
	v_pk_add_f32 v[238:239], v[238:239], v[238:239] op_sel_hi:[0,1]
	v_pk_fma_f32 v[246:247], v[240:241], v[240:241], v[232:233] op_sel_hi:[1,1,0]
	v_pk_mul_f32 v[176:177], v[48:49], v[176:177] op_sel_hi:[1,0]
	v_mul_f32_e32 v232, v248, v248
	v_mul_f32_e32 v244, v176, v176
	v_mul_f32_e32 v246, v177, v177
	v_mul_f32_e32 v238, v249, v249
	v_pk_add_f32 v[244:245], v[244:245], v[246:247]
	v_pk_add_f32 v[232:233], v[232:233], v[238:239]
	v_lshlrev_b64 v[238:239], 10, v[168:169]
	v_pk_add_f32 v[232:233], v[244:245], v[232:233]
	v_lshl_add_u64 v[238:239], v[206:207], 0, v[238:239]
	v_add_f32_e32 v232, v232, v233
	ds_bpermute_b32 v233, v225, v232
	s_waitcnt lgkmcnt(0)
	v_add_f32_e32 v232, v232, v233
	ds_bpermute_b32 v233, v224, v232
	s_waitcnt lgkmcnt(0)
	v_add_f32_e32 v232, v232, v233
	v_fmamk_f32 v232, v232, 0x3c800000, v210
	s_nop 0
	v_rsq_f32_e32 v232, v232
	s_nop 0
	v_mul_f32_e32 v232, v223, v232
	v_pk_mul_f32 v[228:229], v[228:229], v[232:233] op_sel_hi:[1,0]
	v_pk_mul_f32 v[230:231], v[230:231], v[232:233] op_sel_hi:[1,0]
	v_pk_mul_f32 v[228:229], v[140:141], v[228:229]
	v_pk_mul_f32 v[230:231], v[142:143], v[230:231]
	v_pk_mul_f32 v[234:235], v[234:235], v[232:233] op_sel_hi:[1,0]
	v_pk_mul_f32 v[236:237], v[236:237], v[232:233] op_sel_hi:[1,0]
	v_pk_mul_f32 v[234:235], v[136:137], v[234:235]
	v_pk_mul_f32 v[236:237], v[138:139], v[236:237]
	v_cvt_pk_bf16_f32 v228, v228, v229
	v_cvt_pk_bf16_f32 v229, v230, v231
	v_cvt_pk_bf16_f32 v230, v234, v235
	v_pk_mul_f32 v[176:177], v[176:177], v[232:233] op_sel_hi:[1,0]
	v_cvt_pk_bf16_f32 v231, v236, v237
	global_store_dwordx4 v[238:239], v[228:231], off
	v_pk_mul_f32 v[176:177], v[128:129], v[176:177]
	s_nop 0
	v_pk_mul_f32 v[228:229], v[242:243], v[232:233] op_sel_hi:[1,0]
	v_pk_mul_f32 v[230:231], v[240:241], v[232:233] op_sel_hi:[1,0]
	v_pk_mul_f32 v[228:229], v[132:133], v[228:229]
	v_pk_mul_f32 v[230:231], v[134:135], v[230:231]
	v_pk_mul_f32 v[232:233], v[248:249], v[232:233] op_sel_hi:[1,0]
	v_cvt_pk_bf16_f32 v228, v228, v229
	v_cvt_pk_bf16_f32 v229, v230, v231
	v_cvt_pk_bf16_f32 v230, v176, v177
	v_ffbh_u32_e32 v176, v189
	v_pk_mul_f32 v[232:233], v[130:131], v[232:233]
	s_nop 0
	v_cvt_pk_bf16_f32 v231, v232, v233
	global_store_dwordx4 v[238:239], v[228:231], off offset:64
	s_nop 1
	v_min_u32_e32 v228, 32, v176
	v_lshlrev_b64 v[176:177], v228, v[188:189]
	v_min_u32_e32 v176, 1, v176
	v_or_b32_e32 v176, v177, v176
	v_cvt_f32_u32_e32 v176, v176
	v_sub_u32_e32 v177, 32, v228
	v_ldexp_f32 v176, v176, v177
	v_mul_f32_e32 v176, 0x35800000, v176
	v_fmamk_f32 v176, v176, 0x3a800000, v210
	s_nop 0
	v_rsq_f32_e32 v176, v176
	s_nop 0
	v_pk_mul_f32 v[228:229], v[44:45], v[176:177] op_sel_hi:[1,0]
	v_pk_mul_f32 v[230:231], v[46:47], v[176:177] op_sel_hi:[1,0]
	v_pk_mul_f32 v[234:235], v[228:229], v[228:229]
	v_pk_mul_f32 v[232:233], v[230:231], v[230:231]
	v_pk_mul_f32 v[248:249], v[34:35], v[176:177] op_sel_hi:[1,0]
	v_pk_mov_b32 v[236:237], v[234:235], v[232:233] op_sel:[1,0]
	v_mov_b32_e32 v235, v233
	v_pk_add_f32 v[232:233], v[236:237], v[234:235]
	v_pk_mul_f32 v[234:235], v[40:41], v[176:177] op_sel_hi:[1,0]
	v_pk_mul_f32 v[236:237], v[42:43], v[176:177] op_sel_hi:[1,0]
	v_pk_mul_f32 v[240:241], v[234:235], v[234:235]
	v_pk_mul_f32 v[238:239], v[236:237], v[236:237]
	v_pk_add_f32 v[232:233], v[232:233], v[232:233] op_sel_hi:[0,1]
	v_pk_mov_b32 v[242:243], v[240:241], v[238:239] op_sel:[1,0]
	v_mov_b32_e32 v241, v239
	v_pk_add_f32 v[238:239], v[242:243], v[240:241]
	v_pk_mul_f32 v[242:243], v[36:37], v[176:177] op_sel_hi:[1,0]
	v_pk_mul_f32 v[240:241], v[38:39], v[176:177] op_sel_hi:[1,0]
	v_mul_f32_e32 v232, v242, v242
	v_pk_fma_f32 v[244:245], v[242:243], v[242:243], v[232:233] op_sel_hi:[1,1,0]
	v_mul_f32_e32 v232, v240, v240
	v_pk_add_f32 v[238:239], v[238:239], v[238:239] op_sel_hi:[0,1]
	v_pk_fma_f32 v[246:247], v[240:241], v[240:241], v[232:233] op_sel_hi:[1,1,0]
	v_pk_mul_f32 v[176:177], v[32:33], v[176:177] op_sel_hi:[1,0]
	v_mul_f32_e32 v232, v248, v248
	v_mul_f32_e32 v244, v176, v176
	v_mul_f32_e32 v246, v177, v177
	v_mul_f32_e32 v238, v249, v249
	v_pk_add_f32 v[244:245], v[244:245], v[246:247]
	v_pk_add_f32 v[232:233], v[232:233], v[238:239]
	v_lshlrev_b64 v[238:239], 10, v[164:165]
	v_pk_add_f32 v[232:233], v[244:245], v[232:233]
	v_lshl_add_u64 v[238:239], v[206:207], 0, v[238:239]
	v_add_f32_e32 v232, v232, v233
	ds_bpermute_b32 v233, v225, v232
	s_waitcnt lgkmcnt(0)
	v_add_f32_e32 v232, v232, v233
	ds_bpermute_b32 v233, v224, v232
	s_waitcnt lgkmcnt(0)
	v_add_f32_e32 v232, v232, v233
	v_fmamk_f32 v232, v232, 0x3c800000, v210
	s_nop 0
	v_rsq_f32_e32 v232, v232
	s_nop 0
	v_mul_f32_e32 v232, v223, v232
	v_pk_mul_f32 v[228:229], v[228:229], v[232:233] op_sel_hi:[1,0]
	v_pk_mul_f32 v[230:231], v[230:231], v[232:233] op_sel_hi:[1,0]
	v_pk_mul_f32 v[228:229], v[140:141], v[228:229]
	v_pk_mul_f32 v[230:231], v[142:143], v[230:231]
	v_pk_mul_f32 v[234:235], v[234:235], v[232:233] op_sel_hi:[1,0]
	v_pk_mul_f32 v[236:237], v[236:237], v[232:233] op_sel_hi:[1,0]
	v_pk_mul_f32 v[234:235], v[136:137], v[234:235]
	v_pk_mul_f32 v[236:237], v[138:139], v[236:237]
	v_cvt_pk_bf16_f32 v228, v228, v229
	v_cvt_pk_bf16_f32 v229, v230, v231
	v_cvt_pk_bf16_f32 v230, v234, v235
	v_pk_mul_f32 v[176:177], v[176:177], v[232:233] op_sel_hi:[1,0]
	v_cvt_pk_bf16_f32 v231, v236, v237
	global_store_dwordx4 v[238:239], v[228:231], off
	v_pk_mul_f32 v[176:177], v[128:129], v[176:177]
	s_nop 0
	v_pk_mul_f32 v[228:229], v[242:243], v[232:233] op_sel_hi:[1,0]
	v_pk_mul_f32 v[230:231], v[240:241], v[232:233] op_sel_hi:[1,0]
	v_pk_mul_f32 v[228:229], v[132:133], v[228:229]
	v_pk_mul_f32 v[230:231], v[134:135], v[230:231]
	v_pk_mul_f32 v[232:233], v[248:249], v[232:233] op_sel_hi:[1,0]
	v_cvt_pk_bf16_f32 v228, v228, v229
	v_cvt_pk_bf16_f32 v229, v230, v231
	v_cvt_pk_bf16_f32 v230, v176, v177
	v_ffbh_u32_e32 v176, v163
	v_pk_mul_f32 v[232:233], v[130:131], v[232:233]
	s_nop 0
	v_cvt_pk_bf16_f32 v231, v232, v233
	global_store_dwordx4 v[238:239], v[228:231], off offset:64
	s_nop 1
	v_min_u32_e32 v228, 32, v176
	v_lshlrev_b64 v[176:177], v228, v[162:163]
	v_min_u32_e32 v176, 1, v176
	v_or_b32_e32 v176, v177, v176
	v_cvt_f32_u32_e32 v176, v176
	v_sub_u32_e32 v177, 32, v228
	v_ldexp_f32 v176, v176, v177
	v_mul_f32_e32 v176, 0x35800000, v176
	v_fmamk_f32 v176, v176, 0x3a800000, v210
	s_nop 0
	v_rsq_f32_e32 v176, v176
	s_nop 0
	v_pk_mul_f32 v[228:229], v[28:29], v[176:177] op_sel_hi:[1,0]
	v_pk_mul_f32 v[230:231], v[30:31], v[176:177] op_sel_hi:[1,0]
	v_pk_mul_f32 v[234:235], v[228:229], v[228:229]
	v_pk_mul_f32 v[232:233], v[230:231], v[230:231]
	v_pk_mul_f32 v[248:249], v[18:19], v[176:177] op_sel_hi:[1,0]
	v_pk_mov_b32 v[236:237], v[234:235], v[232:233] op_sel:[1,0]
	v_mov_b32_e32 v235, v233
	v_pk_add_f32 v[232:233], v[236:237], v[234:235]
	v_pk_mul_f32 v[234:235], v[24:25], v[176:177] op_sel_hi:[1,0]
	v_pk_mul_f32 v[236:237], v[26:27], v[176:177] op_sel_hi:[1,0]
	v_pk_mul_f32 v[240:241], v[234:235], v[234:235]
	v_pk_mul_f32 v[238:239], v[236:237], v[236:237]
	v_pk_add_f32 v[232:233], v[232:233], v[232:233] op_sel_hi:[0,1]
	v_pk_mov_b32 v[242:243], v[240:241], v[238:239] op_sel:[1,0]
	v_mov_b32_e32 v241, v239
	v_pk_add_f32 v[238:239], v[242:243], v[240:241]
	v_pk_mul_f32 v[242:243], v[20:21], v[176:177] op_sel_hi:[1,0]
	v_pk_mul_f32 v[240:241], v[22:23], v[176:177] op_sel_hi:[1,0]
	v_mul_f32_e32 v232, v242, v242
	v_pk_fma_f32 v[244:245], v[242:243], v[242:243], v[232:233] op_sel_hi:[1,1,0]
	v_mul_f32_e32 v232, v240, v240
	v_pk_add_f32 v[238:239], v[238:239], v[238:239] op_sel_hi:[0,1]
	v_pk_fma_f32 v[246:247], v[240:241], v[240:241], v[232:233] op_sel_hi:[1,1,0]
	v_pk_mul_f32 v[176:177], v[16:17], v[176:177] op_sel_hi:[1,0]
	v_mul_f32_e32 v232, v248, v248
	v_mul_f32_e32 v244, v176, v176
	v_mul_f32_e32 v246, v177, v177
	v_mul_f32_e32 v238, v249, v249
	v_pk_add_f32 v[244:245], v[244:245], v[246:247]
	v_pk_add_f32 v[232:233], v[232:233], v[238:239]
	v_lshlrev_b64 v[238:239], 10, v[158:159]
	v_pk_add_f32 v[232:233], v[244:245], v[232:233]
	v_lshl_add_u64 v[238:239], v[206:207], 0, v[238:239]
	v_add_f32_e32 v232, v232, v233
	ds_bpermute_b32 v233, v225, v232
	s_waitcnt lgkmcnt(0)
	v_add_f32_e32 v232, v232, v233
	ds_bpermute_b32 v233, v224, v232
	s_waitcnt lgkmcnt(0)
	v_add_f32_e32 v232, v232, v233
	v_fmamk_f32 v232, v232, 0x3c800000, v210
	s_nop 0
	v_rsq_f32_e32 v232, v232
	s_nop 0
	v_mul_f32_e32 v232, v223, v232
	v_pk_mul_f32 v[228:229], v[228:229], v[232:233] op_sel_hi:[1,0]
	v_pk_mul_f32 v[230:231], v[230:231], v[232:233] op_sel_hi:[1,0]
	v_pk_mul_f32 v[228:229], v[140:141], v[228:229]
	v_pk_mul_f32 v[230:231], v[142:143], v[230:231]
	v_pk_mul_f32 v[234:235], v[234:235], v[232:233] op_sel_hi:[1,0]
	v_pk_mul_f32 v[236:237], v[236:237], v[232:233] op_sel_hi:[1,0]
	v_pk_mul_f32 v[234:235], v[136:137], v[234:235]
	v_pk_mul_f32 v[236:237], v[138:139], v[236:237]
	v_cvt_pk_bf16_f32 v228, v228, v229
	v_cvt_pk_bf16_f32 v229, v230, v231
	v_cvt_pk_bf16_f32 v230, v234, v235
	v_pk_mul_f32 v[176:177], v[176:177], v[232:233] op_sel_hi:[1,0]
	v_cvt_pk_bf16_f32 v231, v236, v237
	global_store_dwordx4 v[238:239], v[228:231], off
	v_pk_mul_f32 v[176:177], v[128:129], v[176:177]
	s_nop 0
	v_pk_mul_f32 v[228:229], v[242:243], v[232:233] op_sel_hi:[1,0]
	v_pk_mul_f32 v[230:231], v[240:241], v[232:233] op_sel_hi:[1,0]
	v_pk_mul_f32 v[228:229], v[132:133], v[228:229]
	v_pk_mul_f32 v[230:231], v[134:135], v[230:231]
	v_pk_mul_f32 v[232:233], v[248:249], v[232:233] op_sel_hi:[1,0]
	v_cvt_pk_bf16_f32 v228, v228, v229
	v_cvt_pk_bf16_f32 v229, v230, v231
	v_cvt_pk_bf16_f32 v230, v176, v177
	v_ffbh_u32_e32 v176, v161
	v_pk_mul_f32 v[232:233], v[130:131], v[232:233]
	s_nop 0
	v_cvt_pk_bf16_f32 v231, v232, v233
	global_store_dwordx4 v[238:239], v[228:231], off offset:64
	s_nop 1
	v_min_u32_e32 v228, 32, v176
	v_lshlrev_b64 v[176:177], v228, v[160:161]
	v_min_u32_e32 v176, 1, v176
	v_or_b32_e32 v176, v177, v176
	v_cvt_f32_u32_e32 v176, v176
	v_sub_u32_e32 v177, 32, v228
	v_ldexp_f32 v176, v176, v177
	v_mul_f32_e32 v176, 0x35800000, v176
	v_fmamk_f32 v176, v176, 0x3a800000, v210
	s_nop 0
	v_rsq_f32_e32 v176, v176
	s_nop 0
	v_pk_mul_f32 v[228:229], v[12:13], v[176:177] op_sel_hi:[1,0]
	v_pk_mul_f32 v[230:231], v[14:15], v[176:177] op_sel_hi:[1,0]
	v_pk_mul_f32 v[234:235], v[228:229], v[228:229]
	v_pk_mul_f32 v[232:233], v[230:231], v[230:231]
	v_pk_mul_f32 v[248:249], v[2:3], v[176:177] op_sel_hi:[1,0]
	v_pk_mov_b32 v[236:237], v[234:235], v[232:233] op_sel:[1,0]
	v_mov_b32_e32 v235, v233
	v_pk_add_f32 v[232:233], v[236:237], v[234:235]
	v_pk_mul_f32 v[234:235], v[8:9], v[176:177] op_sel_hi:[1,0]
	v_pk_mul_f32 v[236:237], v[10:11], v[176:177] op_sel_hi:[1,0]
	v_pk_mul_f32 v[240:241], v[234:235], v[234:235]
	v_pk_mul_f32 v[238:239], v[236:237], v[236:237]
	v_pk_add_f32 v[232:233], v[232:233], v[232:233] op_sel_hi:[0,1]
	v_pk_mov_b32 v[242:243], v[240:241], v[238:239] op_sel:[1,0]
	v_mov_b32_e32 v241, v239
	v_pk_add_f32 v[238:239], v[242:243], v[240:241]
	v_pk_mul_f32 v[242:243], v[4:5], v[176:177] op_sel_hi:[1,0]
	v_pk_mul_f32 v[240:241], v[6:7], v[176:177] op_sel_hi:[1,0]
	v_mul_f32_e32 v232, v242, v242
	v_pk_fma_f32 v[244:245], v[242:243], v[242:243], v[232:233] op_sel_hi:[1,1,0]
	v_mul_f32_e32 v232, v240, v240
	v_pk_add_f32 v[238:239], v[238:239], v[238:239] op_sel_hi:[0,1]
	v_pk_fma_f32 v[246:247], v[240:241], v[240:241], v[232:233] op_sel_hi:[1,1,0]
	v_pk_mul_f32 v[176:177], v[0:1], v[176:177] op_sel_hi:[1,0]
	v_mul_f32_e32 v232, v248, v248
	v_mul_f32_e32 v244, v176, v176
	v_mul_f32_e32 v246, v177, v177
	v_mul_f32_e32 v238, v249, v249
	v_pk_add_f32 v[244:245], v[244:245], v[246:247]
	v_pk_add_f32 v[232:233], v[232:233], v[238:239]
	s_nop 0
	v_pk_add_f32 v[232:233], v[244:245], v[232:233]
	s_nop 0
	v_add_f32_e32 v232, v232, v233
	ds_bpermute_b32 v225, v225, v232
	s_waitcnt lgkmcnt(0)
	v_add_f32_e32 v225, v232, v225
	ds_bpermute_b32 v224, v224, v225
	v_lshlrev_b64 v[232:233], 10, v[156:157]
	v_lshl_add_u64 v[206:207], v[206:207], 0, v[232:233]
	s_waitcnt lgkmcnt(0)
	v_add_f32_e32 v224, v225, v224
	v_fmamk_f32 v224, v224, 0x3c800000, v210
	s_nop 0
	v_rsq_f32_e32 v224, v224
	s_nop 0
	v_mul_f32_e32 v224, v223, v224
	v_pk_mul_f32 v[228:229], v[228:229], v[224:225] op_sel_hi:[1,0]
	v_pk_mul_f32 v[230:231], v[230:231], v[224:225] op_sel_hi:[1,0]
	v_pk_mul_f32 v[140:141], v[140:141], v[228:229]
	v_pk_mul_f32 v[142:143], v[142:143], v[230:231]
	v_pk_mul_f32 v[228:229], v[234:235], v[224:225] op_sel_hi:[1,0]
	v_pk_mul_f32 v[230:231], v[236:237], v[224:225] op_sel_hi:[1,0]
	s_nop 0
	v_pk_mul_f32 v[230:231], v[138:139], v[230:231]
	v_pk_mul_f32 v[138:139], v[136:137], v[228:229]
	v_cvt_pk_bf16_f32 v136, v140, v141
	v_cvt_pk_bf16_f32 v137, v142, v143
	s_nop 0
	v_cvt_pk_bf16_f32 v138, v138, v139
	v_cvt_pk_bf16_f32 v139, v230, v231
	global_store_dwordx4 v[206:207], v[136:139], off
	s_nop 1
	v_pk_mul_f32 v[136:137], v[242:243], v[224:225] op_sel_hi:[1,0]
	v_pk_mul_f32 v[138:139], v[240:241], v[224:225] op_sel_hi:[1,0]
	v_pk_mul_f32 v[132:133], v[132:133], v[136:137]
	v_pk_mul_f32 v[134:135], v[134:135], v[138:139]
	v_pk_mul_f32 v[136:137], v[176:177], v[224:225] op_sel_hi:[1,0]
	v_pk_mul_f32 v[138:139], v[248:249], v[224:225] op_sel_hi:[1,0]
	s_nop 0
	v_pk_mul_f32 v[138:139], v[130:131], v[138:139]
	v_pk_mul_f32 v[130:131], v[128:129], v[136:137]
	v_cvt_pk_bf16_f32 v128, v132, v133
	v_cvt_pk_bf16_f32 v129, v134, v135
	s_nop 0
	v_cvt_pk_bf16_f32 v130, v130, v131
	v_cvt_pk_bf16_f32 v131, v138, v139
	s_nop 1

.LBB0_350:
	s_lshl_b32 s25, s84, 1
	s_add_i32 s25, s85, s25
	s_and_b32 s85, s25, 3
	s_lshl_b32 s25, s85, 19
	s_add_u32 s92, s74, s25
	v_cmp_lt_i64_e32 vcc, s[52:53], v[180:181]
	s_addc_u32 s93, s75, 0
	s_and_b64 s[30:31], vcc, exec
	s_cselect_b32 s25, s93, s1
	s_cselect_b32 s30, s92, s0
	s_ashr_i32 s47, s46, 31
	s_lshl_b64 s[34:35], s[46:47], 19
	s_add_u32 s94, s54, s34
	s_addc_u32 s95, s55, s35
	s_and_b64 s[34:35], vcc, exec
	s_cselect_b32 s31, s95, s51
	s_cselect_b32 s33, s94, s50
	s_add_u32 s0, s0, 0x40080
	s_addc_u32 s1, s1, 0
	s_add_u32 s34, s50, 0x100
	s_addc_u32 s35, s51, 0
	s_mov_b32 s36, -2
	s_add_u32 s27, s0, 0xfffc0080
	s_addc_u32 s37, s1, -1
	s_add_i32 s47, 0, 0x10000
	v_add_u32_e32 v140, s47, v192
	ds_read_b128 v[128:131], v140
	ds_read_b128 v[132:135], v140 offset:1024
	ds_read_b128 v[136:139], v140 offset:2048
	ds_read_b128 v[140:143], v140 offset:3072
	s_cmp_eq_u32 s36, 12
	s_cselect_b32 s53, s25, s37
	s_cselect_b32 s52, s30, s27
	s_cselect_b32 s51, s31, s35
	s_cselect_b32 s50, s33, s34
	v_lshl_add_u64 v[176:177], s[0:1], 0, v[156:157]
	s_add_i32 m0, s77, 0xc000
	ds_read_b128 v[162:165], v194
	ds_read_b128 v[166:169], v194 offset:1024
	ds_read_b128 v[196:199], v194 offset:2048
	ds_read_b128 v[200:203], v194 offset:3072
	ds_read_b128 v[204:207], v194 offset:4096
	ds_read_b128 v[216:219], v194 offset:5120
	ds_read_b128 v[220:223], v194 offset:6144
	ds_read_b128 v[228:231], v194 offset:7168
	global_load_lds_dwordx4 v[176:177], off
	v_lshl_add_u64 v[176:177], s[0:1], 0, v[158:159]
	s_add_i32 m0, s77, 0xe000
	s_nop 0
	global_load_lds_dwordx4 v[176:177], off
	s_waitcnt lgkmcnt(8)
	s_setprio 1
	s_barrier
	s_waitcnt lgkmcnt(0)
	v_mfma_f32_16x16x32_bf16 v[124:127], v[128:131], v[162:165], 0
	v_mfma_f32_16x16x32_bf16 v[120:123], v[136:139], v[162:165], 0
	v_mfma_f32_16x16x32_bf16 v[116:119], v[128:131], v[196:199], 0
	v_mfma_f32_16x16x32_bf16 v[112:115], v[136:139], v[196:199], 0
	v_mfma_f32_16x16x32_bf16 v[108:111], v[128:131], v[204:207], 0
	v_mfma_f32_16x16x32_bf16 v[104:107], v[136:139], v[204:207], 0
	v_mfma_f32_16x16x32_bf16 v[100:103], v[128:131], v[220:223], 0
	v_mfma_f32_16x16x32_bf16 v[96:99], v[136:139], v[220:223], 0
	v_mfma_f32_16x16x32_bf16 v[124:127], v[132:135], v[166:169], v[124:127]
	v_mfma_f32_16x16x32_bf16 v[120:123], v[140:143], v[166:169], v[120:123]
	v_mfma_f32_16x16x32_bf16 v[116:119], v[132:135], v[200:203], v[116:119]
	v_mfma_f32_16x16x32_bf16 v[112:115], v[140:143], v[200:203], v[112:115]
	v_mfma_f32_16x16x32_bf16 v[108:111], v[132:135], v[216:219], v[108:111]
	v_mfma_f32_16x16x32_bf16 v[104:107], v[140:143], v[216:219], v[104:107]
	v_mfma_f32_16x16x32_bf16 v[100:103], v[132:135], v[228:231], v[100:103]
	v_mfma_f32_16x16x32_bf16 v[96:99], v[140:143], v[228:231], v[96:99]
	s_barrier
	s_setprio 0
	s_add_i32 s37, s47, s76
	v_lshl_add_u64 v[176:177], s[50:51], 0, v[148:149]
	s_mov_b32 m0, s37
	s_nop 0
	global_load_lds_dwordx4 v[176:177], off
	v_lshl_add_u64 v[188:189], s[50:51], 0, v[152:153]
	s_add_i32 m0, s37, 0x2000
	s_nop 0
	global_load_lds_dwordx4 v[188:189], off
	s_add_i32 s27, 0, 0x14000
	v_add_u32_e32 v161, s27, v192
	ds_read_b128 v[232:235], v161
	ds_read_b128 v[236:239], v161 offset:1024
	ds_read_b128 v[240:243], v161 offset:2048
	ds_read_b128 v[244:247], v161 offset:3072
	s_setprio 1
	s_barrier
	s_waitcnt lgkmcnt(0)
	v_mfma_f32_16x16x32_bf16 v[92:95], v[232:235], v[162:165], 0
	v_mfma_f32_16x16x32_bf16 v[88:91], v[240:243], v[162:165], 0
	v_mfma_f32_16x16x32_bf16 v[84:87], v[232:235], v[196:199], 0
	v_mfma_f32_16x16x32_bf16 v[80:83], v[240:243], v[196:199], 0
	v_mfma_f32_16x16x32_bf16 v[76:79], v[232:235], v[204:207], 0
	v_mfma_f32_16x16x32_bf16 v[72:75], v[240:243], v[204:207], 0
	v_mfma_f32_16x16x32_bf16 v[68:71], v[232:235], v[220:223], 0
	v_mfma_f32_16x16x32_bf16 v[64:67], v[240:243], v[220:223], 0
	v_mfma_f32_16x16x32_bf16 v[92:95], v[236:239], v[166:169], v[92:95]
	v_mfma_f32_16x16x32_bf16 v[88:91], v[244:247], v[166:169], v[88:91]
	v_mfma_f32_16x16x32_bf16 v[84:87], v[236:239], v[200:203], v[84:87]
	v_mfma_f32_16x16x32_bf16 v[80:83], v[244:247], v[200:203], v[80:83]
	v_mfma_f32_16x16x32_bf16 v[76:79], v[236:239], v[216:219], v[76:79]
	v_mfma_f32_16x16x32_bf16 v[72:75], v[244:247], v[216:219], v[72:75]
	v_mfma_f32_16x16x32_bf16 v[68:71], v[236:239], v[228:231], v[68:71]
	v_mfma_f32_16x16x32_bf16 v[64:67], v[244:247], v[228:231], v[64:67]
	s_barrier
	s_setprio 0
	s_mov_b32 m0, s77
	v_lshl_add_u64 v[224:225], s[52:53], 0, v[146:147]
	global_load_lds_dwordx4 v[224:225], off
	v_lshl_add_u64 v[248:249], s[52:53], 0, v[150:151]
	s_mov_b32 m0, s78
	s_nop 0
	global_load_lds_dwordx4 v[248:249], off
	ds_read_b128 v[162:165], v194 offset:16384
	ds_read_b128 v[166:169], v194 offset:17408
	ds_read_b128 v[196:199], v194 offset:18432
	ds_read_b128 v[200:203], v194 offset:19456
	ds_read_b128 v[204:207], v194 offset:20480
	ds_read_b128 v[216:219], v194 offset:21504
	ds_read_b128 v[220:223], v194 offset:22528
	ds_read_b128 v[228:231], v194 offset:23552
	s_setprio 1
	s_barrier
	s_waitcnt lgkmcnt(0)
	v_mfma_f32_16x16x32_bf16 v[60:63], v[128:131], v[162:165], 0
	v_mfma_f32_16x16x32_bf16 v[56:59], v[136:139], v[162:165], 0
	v_mfma_f32_16x16x32_bf16 v[52:55], v[128:131], v[196:199], 0
	v_mfma_f32_16x16x32_bf16 v[48:51], v[136:139], v[196:199], 0
	v_mfma_f32_16x16x32_bf16 v[44:47], v[128:131], v[204:207], 0
	v_mfma_f32_16x16x32_bf16 v[40:43], v[136:139], v[204:207], 0
	v_mfma_f32_16x16x32_bf16 v[36:39], v[128:131], v[220:223], 0
	v_mfma_f32_16x16x32_bf16 v[32:35], v[136:139], v[220:223], 0
	v_mfma_f32_16x16x32_bf16 v[60:63], v[132:135], v[166:169], v[60:63]
	v_mfma_f32_16x16x32_bf16 v[56:59], v[140:143], v[166:169], v[56:59]
	v_mfma_f32_16x16x32_bf16 v[52:55], v[132:135], v[200:203], v[52:55]
	v_mfma_f32_16x16x32_bf16 v[48:51], v[140:143], v[200:203], v[48:51]
	v_mfma_f32_16x16x32_bf16 v[44:47], v[132:135], v[216:219], v[44:47]
	v_mfma_f32_16x16x32_bf16 v[40:43], v[140:143], v[216:219], v[40:43]
	v_mfma_f32_16x16x32_bf16 v[36:39], v[132:135], v[228:231], v[36:39]
	v_mfma_f32_16x16x32_bf16 v[32:35], v[140:143], v[228:231], v[32:35]
	s_barrier
	s_setprio 0
	s_add_u32 s56, s50, 0x40000
	s_addc_u32 s57, s51, 0
	s_add_i32 s27, s27, s76
	v_lshl_add_u64 v[128:129], s[56:57], 0, v[148:149]
	s_mov_b32 m0, s27
	s_nop 0
	global_load_lds_dwordx4 v[128:129], off
	v_lshl_add_u64 v[128:129], s[56:57], 0, v[152:153]
	s_add_i32 m0, s27, 0x2000
	s_nop 0
	global_load_lds_dwordx4 v[128:129], off
	s_waitcnt vmcnt(6)
	s_setprio 1
	s_barrier
	v_mfma_f32_16x16x32_bf16 v[28:31], v[232:235], v[162:165], 0
	v_mfma_f32_16x16x32_bf16 v[24:27], v[240:243], v[162:165], 0
	v_mfma_f32_16x16x32_bf16 v[20:23], v[232:235], v[196:199], 0
	v_mfma_f32_16x16x32_bf16 v[16:19], v[240:243], v[196:199], 0
	v_mfma_f32_16x16x32_bf16 v[12:15], v[232:235], v[204:207], 0
	v_mfma_f32_16x16x32_bf16 v[8:11], v[240:243], v[204:207], 0
	v_mfma_f32_16x16x32_bf16 v[4:7], v[232:235], v[220:223], 0
	v_mfma_f32_16x16x32_bf16 v[0:3], v[240:243], v[220:223], 0
	v_mfma_f32_16x16x32_bf16 v[28:31], v[236:239], v[166:169], v[28:31]
	v_mfma_f32_16x16x32_bf16 v[24:27], v[244:247], v[166:169], v[24:27]
	v_mfma_f32_16x16x32_bf16 v[20:23], v[236:239], v[200:203], v[20:23]
	v_mfma_f32_16x16x32_bf16 v[16:19], v[244:247], v[200:203], v[16:19]
	v_mfma_f32_16x16x32_bf16 v[12:15], v[236:239], v[216:219], v[12:15]
	v_mfma_f32_16x16x32_bf16 v[8:11], v[244:247], v[216:219], v[8:11]
	v_mfma_f32_16x16x32_bf16 v[4:7], v[236:239], v[228:231], v[4:7]
	v_mfma_f32_16x16x32_bf16 v[0:3], v[244:247], v[228:231], v[0:3]
	s_barrier
	s_setprio 0
	s_add_i32 s27, 0, 0x18000
	v_add_u32_e32 v140, s27, v192
	ds_read_b128 v[128:131], v140
	ds_read_b128 v[132:135], v140 offset:1024
	ds_read_b128 v[136:139], v140 offset:2048
	ds_read_b128 v[140:143], v140 offset:3072
	s_add_u32 s52, s52, 0x40000
	s_addc_u32 s53, s53, 0
	s_mov_b32 m0, s81
	v_lshl_add_u64 v[232:233], s[52:53], 0, v[146:147]
	ds_read_b128 v[162:165], v194 offset:32768
	ds_read_b128 v[166:169], v194 offset:33792
	ds_read_b128 v[196:199], v194 offset:34816
	ds_read_b128 v[200:203], v194 offset:35840
	ds_read_b128 v[204:207], v194 offset:36864
	ds_read_b128 v[216:219], v194 offset:37888
	ds_read_b128 v[220:223], v194 offset:38912
	ds_read_b128 v[228:231], v194 offset:39936
	global_load_lds_dwordx4 v[232:233], off
	v_lshl_add_u64 v[232:233], s[52:53], 0, v[150:151]
	s_mov_b32 m0, s82
	s_nop 0
	global_load_lds_dwordx4 v[232:233], off
	s_waitcnt lgkmcnt(8)
	s_setprio 1
	s_barrier
	s_waitcnt lgkmcnt(0)
	v_mfma_f32_16x16x32_bf16 v[124:127], v[128:131], v[162:165], v[124:127]
	v_mfma_f32_16x16x32_bf16 v[120:123], v[136:139], v[162:165], v[120:123]
	v_mfma_f32_16x16x32_bf16 v[116:119], v[128:131], v[196:199], v[116:119]
	v_mfma_f32_16x16x32_bf16 v[112:115], v[136:139], v[196:199], v[112:115]
	v_mfma_f32_16x16x32_bf16 v[108:111], v[128:131], v[204:207], v[108:111]
	v_mfma_f32_16x16x32_bf16 v[104:107], v[136:139], v[204:207], v[104:107]
	v_mfma_f32_16x16x32_bf16 v[100:103], v[128:131], v[220:223], v[100:103]
	v_mfma_f32_16x16x32_bf16 v[96:99], v[136:139], v[220:223], v[96:99]
	v_mfma_f32_16x16x32_bf16 v[124:127], v[132:135], v[166:169], v[124:127]
	v_mfma_f32_16x16x32_bf16 v[120:123], v[140:143], v[166:169], v[120:123]
	v_mfma_f32_16x16x32_bf16 v[116:119], v[132:135], v[200:203], v[116:119]
	v_mfma_f32_16x16x32_bf16 v[112:115], v[140:143], v[200:203], v[112:115]
	v_mfma_f32_16x16x32_bf16 v[108:111], v[132:135], v[216:219], v[108:111]
	v_mfma_f32_16x16x32_bf16 v[104:107], v[140:143], v[216:219], v[104:107]
	v_mfma_f32_16x16x32_bf16 v[100:103], v[132:135], v[228:231], v[100:103]
	v_mfma_f32_16x16x32_bf16 v[96:99], v[140:143], v[228:231], v[96:99]
	s_barrier
	s_setprio 0
	s_add_i32 s27, s27, s76
	v_lshl_add_u64 v[176:177], v[176:177], 0, s[18:19]
	s_mov_b32 m0, s27
	s_nop 0
	global_load_lds_dwordx4 v[176:177], off
	v_lshl_add_u64 v[176:177], v[188:189], 0, s[18:19]
	s_add_i32 m0, s27, 0x2000
	s_nop 0
	global_load_lds_dwordx4 v[176:177], off
	s_add_i32 s37, 0, 0x1c000
	v_add_u32_e32 v161, s37, v192
	ds_read_b128 v[232:235], v161
	ds_read_b128 v[236:239], v161 offset:1024
	ds_read_b128 v[240:243], v161 offset:2048
	ds_read_b128 v[244:247], v161 offset:3072
	s_setprio 1
	s_barrier
	s_waitcnt lgkmcnt(0)
	v_mfma_f32_16x16x32_bf16 v[92:95], v[232:235], v[162:165], v[92:95]
	v_mfma_f32_16x16x32_bf16 v[88:91], v[240:243], v[162:165], v[88:91]
	v_mfma_f32_16x16x32_bf16 v[84:87], v[232:235], v[196:199], v[84:87]
	v_mfma_f32_16x16x32_bf16 v[80:83], v[240:243], v[196:199], v[80:83]
	v_mfma_f32_16x16x32_bf16 v[76:79], v[232:235], v[204:207], v[76:79]
	v_mfma_f32_16x16x32_bf16 v[72:75], v[240:243], v[204:207], v[72:75]
	v_mfma_f32_16x16x32_bf16 v[68:71], v[232:235], v[220:223], v[68:71]
	v_mfma_f32_16x16x32_bf16 v[64:67], v[240:243], v[220:223], v[64:67]
	v_mfma_f32_16x16x32_bf16 v[92:95], v[236:239], v[166:169], v[92:95]
	v_mfma_f32_16x16x32_bf16 v[88:91], v[244:247], v[166:169], v[88:91]
	v_mfma_f32_16x16x32_bf16 v[84:87], v[236:239], v[200:203], v[84:87]
	v_mfma_f32_16x16x32_bf16 v[80:83], v[244:247], v[200:203], v[80:83]
	v_mfma_f32_16x16x32_bf16 v[76:79], v[236:239], v[216:219], v[76:79]
	v_mfma_f32_16x16x32_bf16 v[72:75], v[244:247], v[216:219], v[72:75]
	v_mfma_f32_16x16x32_bf16 v[68:71], v[236:239], v[228:231], v[68:71]
	v_mfma_f32_16x16x32_bf16 v[64:67], v[244:247], v[228:231], v[64:67]
	s_barrier
	s_setprio 0
	s_mov_b32 m0, s80
	v_lshl_add_u64 v[176:177], v[224:225], 0, s[18:19]
	global_load_lds_dwordx4 v[176:177], off
	v_lshl_add_u64 v[176:177], v[248:249], 0, s[18:19]
	s_mov_b32 m0, s83
	s_nop 0
	global_load_lds_dwordx4 v[176:177], off
	ds_read_b128 v[162:165], v194 offset:49152
	ds_read_b128 v[166:169], v194 offset:50176
	ds_read_b128 v[196:199], v194 offset:51200
	ds_read_b128 v[200:203], v194 offset:52224
	ds_read_b128 v[204:207], v194 offset:53248
	ds_read_b128 v[216:219], v194 offset:54272
	ds_read_b128 v[220:223], v194 offset:55296
	ds_read_b128 v[228:231], v194 offset:56320
	s_setprio 1
	s_barrier
	s_waitcnt lgkmcnt(0)
	v_mfma_f32_16x16x32_bf16 v[60:63], v[128:131], v[162:165], v[60:63]
	v_mfma_f32_16x16x32_bf16 v[56:59], v[136:139], v[162:165], v[56:59]
	v_mfma_f32_16x16x32_bf16 v[52:55], v[128:131], v[196:199], v[52:55]
	v_mfma_f32_16x16x32_bf16 v[48:51], v[136:139], v[196:199], v[48:51]
	v_mfma_f32_16x16x32_bf16 v[44:47], v[128:131], v[204:207], v[44:47]
	v_mfma_f32_16x16x32_bf16 v[40:43], v[136:139], v[204:207], v[40:43]
	v_mfma_f32_16x16x32_bf16 v[36:39], v[128:131], v[220:223], v[36:39]
	v_mfma_f32_16x16x32_bf16 v[32:35], v[136:139], v[220:223], v[32:35]
	v_mfma_f32_16x16x32_bf16 v[60:63], v[132:135], v[166:169], v[60:63]
	v_mfma_f32_16x16x32_bf16 v[56:59], v[140:143], v[166:169], v[56:59]
	v_mfma_f32_16x16x32_bf16 v[52:55], v[132:135], v[200:203], v[52:55]
	v_mfma_f32_16x16x32_bf16 v[48:51], v[140:143], v[200:203], v[48:51]
	v_mfma_f32_16x16x32_bf16 v[44:47], v[132:135], v[216:219], v[44:47]
	v_mfma_f32_16x16x32_bf16 v[40:43], v[140:143], v[216:219], v[40:43]
	v_mfma_f32_16x16x32_bf16 v[36:39], v[132:135], v[228:231], v[36:39]
	v_mfma_f32_16x16x32_bf16 v[32:35], v[140:143], v[228:231], v[32:35]
	s_barrier
	s_setprio 0
	s_add_u32 s50, s50, 0x40080
	s_addc_u32 s51, s51, 0
	s_add_i32 s27, s37, s76
	v_lshl_add_u64 v[128:129], s[50:51], 0, v[148:149]
	s_mov_b32 m0, s27
	s_nop 0
	global_load_lds_dwordx4 v[128:129], off
	v_lshl_add_u64 v[128:129], s[50:51], 0, v[152:153]
	s_add_i32 m0, s27, 0x2000
	s_nop 0
	global_load_lds_dwordx4 v[128:129], off
	s_waitcnt vmcnt(6)
	s_setprio 1
	s_barrier
	v_mfma_f32_16x16x32_bf16 v[28:31], v[232:235], v[162:165], v[28:31]
	v_mfma_f32_16x16x32_bf16 v[24:27], v[240:243], v[162:165], v[24:27]
	v_mfma_f32_16x16x32_bf16 v[20:23], v[232:235], v[196:199], v[20:23]
	v_mfma_f32_16x16x32_bf16 v[16:19], v[240:243], v[196:199], v[16:19]
	v_mfma_f32_16x16x32_bf16 v[12:15], v[232:235], v[204:207], v[12:15]
	v_mfma_f32_16x16x32_bf16 v[8:11], v[240:243], v[204:207], v[8:11]
	v_mfma_f32_16x16x32_bf16 v[4:7], v[232:235], v[220:223], v[4:7]
	v_mfma_f32_16x16x32_bf16 v[0:3], v[240:243], v[220:223], v[0:3]
	v_mfma_f32_16x16x32_bf16 v[28:31], v[236:239], v[166:169], v[28:31]
	v_mfma_f32_16x16x32_bf16 v[24:27], v[244:247], v[166:169], v[24:27]
	v_mfma_f32_16x16x32_bf16 v[20:23], v[236:239], v[200:203], v[20:23]
	v_mfma_f32_16x16x32_bf16 v[16:19], v[244:247], v[200:203], v[16:19]
	v_mfma_f32_16x16x32_bf16 v[12:15], v[236:239], v[216:219], v[12:15]
	v_mfma_f32_16x16x32_bf16 v[8:11], v[244:247], v[216:219], v[8:11]
	v_mfma_f32_16x16x32_bf16 v[4:7], v[236:239], v[228:231], v[4:7]
	v_mfma_f32_16x16x32_bf16 v[0:3], v[244:247], v[228:231], v[0:3]
	s_barrier
	s_setprio 0
	s_add_i32 s36, s36, 2
	s_add_u32 s0, s0, 0x100
	s_addc_u32 s1, s1, 0
	s_add_u32 s34, s34, 0x100
	s_addc_u32 s35, s35, 0
	s_cmp_gt_u32 s36, 13
.LBB0_351:
	v_lshl_add_u64 v[176:177], s[0:1], 0, v[156:157]
	s_add_i32 m0, s77, 0xc000
	s_nop 0
	global_load_lds_dwordx4 v[176:177], off
	v_lshl_add_u64 v[176:177], s[0:1], 0, v[158:159]
	s_add_i32 m0, s77, 0xe000
	s_nop 0
	global_load_lds_dwordx4 v[176:177], off
	s_add_u32 s27, s0, 0xfffc0080
	s_addc_u32 s37, s1, -1
	s_add_i32 s47, 0, 0x10000
	v_add_u32_e32 v140, s47, v192
	ds_read_b128 v[128:131], v140
	ds_read_b128 v[132:135], v140 offset:1024
	ds_read_b128 v[136:139], v140 offset:2048
	ds_read_b128 v[140:143], v140 offset:3072
	s_cmp_eq_u32 s36, 12
	s_cselect_b32 s53, s25, s37
	s_cselect_b32 s52, s30, s27
	s_cselect_b32 s51, s31, s35
	s_cselect_b32 s50, s33, s34
	ds_read_b128 v[162:165], v194
	ds_read_b128 v[166:169], v194 offset:1024
	ds_read_b128 v[196:199], v194 offset:2048
	ds_read_b128 v[200:203], v194 offset:3072
	ds_read_b128 v[204:207], v194 offset:4096
	ds_read_b128 v[216:219], v194 offset:5120
	ds_read_b128 v[220:223], v194 offset:6144
	ds_read_b128 v[228:231], v194 offset:7168
	s_waitcnt lgkmcnt(8)
	s_setprio 1
	s_barrier
	s_waitcnt lgkmcnt(0)
	v_mfma_f32_16x16x32_bf16 v[124:127], v[128:131], v[162:165], v[124:127]
	v_mfma_f32_16x16x32_bf16 v[120:123], v[136:139], v[162:165], v[120:123]
	v_mfma_f32_16x16x32_bf16 v[116:119], v[128:131], v[196:199], v[116:119]
	v_mfma_f32_16x16x32_bf16 v[112:115], v[136:139], v[196:199], v[112:115]
	v_mfma_f32_16x16x32_bf16 v[108:111], v[128:131], v[204:207], v[108:111]
	v_mfma_f32_16x16x32_bf16 v[104:107], v[136:139], v[204:207], v[104:107]
	v_mfma_f32_16x16x32_bf16 v[100:103], v[128:131], v[220:223], v[100:103]
	v_mfma_f32_16x16x32_bf16 v[96:99], v[136:139], v[220:223], v[96:99]
	v_mfma_f32_16x16x32_bf16 v[124:127], v[132:135], v[166:169], v[124:127]
	v_mfma_f32_16x16x32_bf16 v[120:123], v[140:143], v[166:169], v[120:123]
	v_mfma_f32_16x16x32_bf16 v[116:119], v[132:135], v[200:203], v[116:119]
	v_mfma_f32_16x16x32_bf16 v[112:115], v[140:143], v[200:203], v[112:115]
	v_mfma_f32_16x16x32_bf16 v[108:111], v[132:135], v[216:219], v[108:111]
	v_mfma_f32_16x16x32_bf16 v[104:107], v[140:143], v[216:219], v[104:107]
	v_mfma_f32_16x16x32_bf16 v[100:103], v[132:135], v[228:231], v[100:103]
	v_mfma_f32_16x16x32_bf16 v[96:99], v[140:143], v[228:231], v[96:99]
	s_barrier
	s_setprio 0
	s_add_i32 s37, s47, s76
	v_lshl_add_u64 v[176:177], s[50:51], 0, v[148:149]
	s_mov_b32 m0, s37
	s_nop 0
	global_load_lds_dwordx4 v[176:177], off
	v_lshl_add_u64 v[188:189], s[50:51], 0, v[152:153]
	s_add_i32 m0, s37, 0x2000
	s_nop 0
	global_load_lds_dwordx4 v[188:189], off
	s_add_i32 s27, 0, 0x14000
	v_add_u32_e32 v161, s27, v192
	ds_read_b128 v[232:235], v161
	ds_read_b128 v[236:239], v161 offset:1024
	ds_read_b128 v[240:243], v161 offset:2048
	ds_read_b128 v[244:247], v161 offset:3072
	s_setprio 1
	s_barrier
	s_waitcnt lgkmcnt(0)
	v_mfma_f32_16x16x32_bf16 v[92:95], v[232:235], v[162:165], v[92:95]
	v_mfma_f32_16x16x32_bf16 v[88:91], v[240:243], v[162:165], v[88:91]
	v_mfma_f32_16x16x32_bf16 v[84:87], v[232:235], v[196:199], v[84:87]
	v_mfma_f32_16x16x32_bf16 v[80:83], v[240:243], v[196:199], v[80:83]
	v_mfma_f32_16x16x32_bf16 v[76:79], v[232:235], v[204:207], v[76:79]
	v_mfma_f32_16x16x32_bf16 v[72:75], v[240:243], v[204:207], v[72:75]
	v_mfma_f32_16x16x32_bf16 v[68:71], v[232:235], v[220:223], v[68:71]
	v_mfma_f32_16x16x32_bf16 v[64:67], v[240:243], v[220:223], v[64:67]
	v_mfma_f32_16x16x32_bf16 v[92:95], v[236:239], v[166:169], v[92:95]
	v_mfma_f32_16x16x32_bf16 v[88:91], v[244:247], v[166:169], v[88:91]
	v_mfma_f32_16x16x32_bf16 v[84:87], v[236:239], v[200:203], v[84:87]
	v_mfma_f32_16x16x32_bf16 v[80:83], v[244:247], v[200:203], v[80:83]
	v_mfma_f32_16x16x32_bf16 v[76:79], v[236:239], v[216:219], v[76:79]
	v_mfma_f32_16x16x32_bf16 v[72:75], v[244:247], v[216:219], v[72:75]
	v_mfma_f32_16x16x32_bf16 v[68:71], v[236:239], v[228:231], v[68:71]
	v_mfma_f32_16x16x32_bf16 v[64:67], v[244:247], v[228:231], v[64:67]
	s_barrier
	s_setprio 0
	s_mov_b32 m0, s77
	v_lshl_add_u64 v[224:225], s[52:53], 0, v[146:147]
	global_load_lds_dwordx4 v[224:225], off
	v_lshl_add_u64 v[248:249], s[52:53], 0, v[150:151]
	s_mov_b32 m0, s78
	s_nop 0
	global_load_lds_dwordx4 v[248:249], off
	ds_read_b128 v[162:165], v194 offset:16384
	ds_read_b128 v[166:169], v194 offset:17408
	ds_read_b128 v[196:199], v194 offset:18432
	ds_read_b128 v[200:203], v194 offset:19456
	ds_read_b128 v[204:207], v194 offset:20480
	ds_read_b128 v[216:219], v194 offset:21504
	ds_read_b128 v[220:223], v194 offset:22528
	ds_read_b128 v[228:231], v194 offset:23552
	s_setprio 1
	s_barrier
	s_waitcnt lgkmcnt(0)
	v_mfma_f32_16x16x32_bf16 v[60:63], v[128:131], v[162:165], v[60:63]
	v_mfma_f32_16x16x32_bf16 v[56:59], v[136:139], v[162:165], v[56:59]
	v_mfma_f32_16x16x32_bf16 v[52:55], v[128:131], v[196:199], v[52:55]
	v_mfma_f32_16x16x32_bf16 v[48:51], v[136:139], v[196:199], v[48:51]
	v_mfma_f32_16x16x32_bf16 v[44:47], v[128:131], v[204:207], v[44:47]
	v_mfma_f32_16x16x32_bf16 v[40:43], v[136:139], v[204:207], v[40:43]
	v_mfma_f32_16x16x32_bf16 v[36:39], v[128:131], v[220:223], v[36:39]
	v_mfma_f32_16x16x32_bf16 v[32:35], v[136:139], v[220:223], v[32:35]
	v_mfma_f32_16x16x32_bf16 v[60:63], v[132:135], v[166:169], v[60:63]
	v_mfma_f32_16x16x32_bf16 v[56:59], v[140:143], v[166:169], v[56:59]
	v_mfma_f32_16x16x32_bf16 v[52:55], v[132:135], v[200:203], v[52:55]
	v_mfma_f32_16x16x32_bf16 v[48:51], v[140:143], v[200:203], v[48:51]
	v_mfma_f32_16x16x32_bf16 v[44:47], v[132:135], v[216:219], v[44:47]
	v_mfma_f32_16x16x32_bf16 v[40:43], v[140:143], v[216:219], v[40:43]
	v_mfma_f32_16x16x32_bf16 v[36:39], v[132:135], v[228:231], v[36:39]
	v_mfma_f32_16x16x32_bf16 v[32:35], v[140:143], v[228:231], v[32:35]
	s_barrier
	s_setprio 0
	s_add_u32 s56, s50, 0x40000
	s_addc_u32 s57, s51, 0
	s_add_i32 s27, s27, s76
	v_lshl_add_u64 v[128:129], s[56:57], 0, v[148:149]
	s_mov_b32 m0, s27
	s_nop 0
	global_load_lds_dwordx4 v[128:129], off
	v_lshl_add_u64 v[128:129], s[56:57], 0, v[152:153]
	s_add_i32 m0, s27, 0x2000
	s_nop 0
	global_load_lds_dwordx4 v[128:129], off
	s_waitcnt vmcnt(6)
	s_setprio 1
	s_barrier
	v_mfma_f32_16x16x32_bf16 v[28:31], v[232:235], v[162:165], v[28:31]
	v_mfma_f32_16x16x32_bf16 v[24:27], v[240:243], v[162:165], v[24:27]
	v_mfma_f32_16x16x32_bf16 v[20:23], v[232:235], v[196:199], v[20:23]
	v_mfma_f32_16x16x32_bf16 v[16:19], v[240:243], v[196:199], v[16:19]
	v_mfma_f32_16x16x32_bf16 v[12:15], v[232:235], v[204:207], v[12:15]
	v_mfma_f32_16x16x32_bf16 v[8:11], v[240:243], v[204:207], v[8:11]
	v_mfma_f32_16x16x32_bf16 v[4:7], v[232:235], v[220:223], v[4:7]
	v_mfma_f32_16x16x32_bf16 v[0:3], v[240:243], v[220:223], v[0:3]
	v_mfma_f32_16x16x32_bf16 v[28:31], v[236:239], v[166:169], v[28:31]
	v_mfma_f32_16x16x32_bf16 v[24:27], v[244:247], v[166:169], v[24:27]
	v_mfma_f32_16x16x32_bf16 v[20:23], v[236:239], v[200:203], v[20:23]
	v_mfma_f32_16x16x32_bf16 v[16:19], v[244:247], v[200:203], v[16:19]
	v_mfma_f32_16x16x32_bf16 v[12:15], v[236:239], v[216:219], v[12:15]
	v_mfma_f32_16x16x32_bf16 v[8:11], v[244:247], v[216:219], v[8:11]
	v_mfma_f32_16x16x32_bf16 v[4:7], v[236:239], v[228:231], v[4:7]
	v_mfma_f32_16x16x32_bf16 v[0:3], v[244:247], v[228:231], v[0:3]
	s_barrier
	s_setprio 0
	s_add_i32 s27, 0, 0x18000
	v_add_u32_e32 v140, s27, v192
	ds_read_b128 v[128:131], v140
	ds_read_b128 v[132:135], v140 offset:1024
	ds_read_b128 v[136:139], v140 offset:2048
	ds_read_b128 v[140:143], v140 offset:3072
	s_add_u32 s52, s52, 0x40000
	s_addc_u32 s53, s53, 0
	s_mov_b32 m0, s81
	v_lshl_add_u64 v[232:233], s[52:53], 0, v[146:147]
	ds_read_b128 v[162:165], v194 offset:32768
	ds_read_b128 v[166:169], v194 offset:33792
	ds_read_b128 v[196:199], v194 offset:34816
	ds_read_b128 v[200:203], v194 offset:35840
	ds_read_b128 v[204:207], v194 offset:36864
	ds_read_b128 v[216:219], v194 offset:37888
	ds_read_b128 v[220:223], v194 offset:38912
	ds_read_b128 v[228:231], v194 offset:39936
	global_load_lds_dwordx4 v[232:233], off
	v_lshl_add_u64 v[232:233], s[52:53], 0, v[150:151]
	s_mov_b32 m0, s82
	s_nop 0
	global_load_lds_dwordx4 v[232:233], off
	s_waitcnt lgkmcnt(8)
	s_setprio 1
	s_barrier
	s_waitcnt lgkmcnt(0)
	v_mfma_f32_16x16x32_bf16 v[124:127], v[128:131], v[162:165], v[124:127]
	v_mfma_f32_16x16x32_bf16 v[120:123], v[136:139], v[162:165], v[120:123]
	v_mfma_f32_16x16x32_bf16 v[116:119], v[128:131], v[196:199], v[116:119]
	v_mfma_f32_16x16x32_bf16 v[112:115], v[136:139], v[196:199], v[112:115]
	v_mfma_f32_16x16x32_bf16 v[108:111], v[128:131], v[204:207], v[108:111]
	v_mfma_f32_16x16x32_bf16 v[104:107], v[136:139], v[204:207], v[104:107]
	v_mfma_f32_16x16x32_bf16 v[100:103], v[128:131], v[220:223], v[100:103]
	v_mfma_f32_16x16x32_bf16 v[96:99], v[136:139], v[220:223], v[96:99]
	v_mfma_f32_16x16x32_bf16 v[124:127], v[132:135], v[166:169], v[124:127]
	v_mfma_f32_16x16x32_bf16 v[120:123], v[140:143], v[166:169], v[120:123]
	v_mfma_f32_16x16x32_bf16 v[116:119], v[132:135], v[200:203], v[116:119]
	v_mfma_f32_16x16x32_bf16 v[112:115], v[140:143], v[200:203], v[112:115]
	v_mfma_f32_16x16x32_bf16 v[108:111], v[132:135], v[216:219], v[108:111]
	v_mfma_f32_16x16x32_bf16 v[104:107], v[140:143], v[216:219], v[104:107]
	v_mfma_f32_16x16x32_bf16 v[100:103], v[132:135], v[228:231], v[100:103]
	v_mfma_f32_16x16x32_bf16 v[96:99], v[140:143], v[228:231], v[96:99]
	s_barrier
	s_setprio 0
	s_add_i32 s27, s27, s76
	v_lshl_add_u64 v[176:177], v[176:177], 0, s[18:19]
	s_mov_b32 m0, s27
	s_nop 0
	global_load_lds_dwordx4 v[176:177], off
	v_lshl_add_u64 v[176:177], v[188:189], 0, s[18:19]
	s_add_i32 m0, s27, 0x2000
	s_nop 0
	global_load_lds_dwordx4 v[176:177], off
	s_add_i32 s37, 0, 0x1c000
	v_add_u32_e32 v161, s37, v192
	ds_read_b128 v[232:235], v161
	ds_read_b128 v[236:239], v161 offset:1024
	ds_read_b128 v[240:243], v161 offset:2048
	ds_read_b128 v[244:247], v161 offset:3072
	s_setprio 1
	s_barrier
	s_waitcnt lgkmcnt(0)
	v_mfma_f32_16x16x32_bf16 v[92:95], v[232:235], v[162:165], v[92:95]
	v_mfma_f32_16x16x32_bf16 v[88:91], v[240:243], v[162:165], v[88:91]
	v_mfma_f32_16x16x32_bf16 v[84:87], v[232:235], v[196:199], v[84:87]
	v_mfma_f32_16x16x32_bf16 v[80:83], v[240:243], v[196:199], v[80:83]
	v_mfma_f32_16x16x32_bf16 v[76:79], v[232:235], v[204:207], v[76:79]
	v_mfma_f32_16x16x32_bf16 v[72:75], v[240:243], v[204:207], v[72:75]
	v_mfma_f32_16x16x32_bf16 v[68:71], v[232:235], v[220:223], v[68:71]
	v_mfma_f32_16x16x32_bf16 v[64:67], v[240:243], v[220:223], v[64:67]
	v_mfma_f32_16x16x32_bf16 v[92:95], v[236:239], v[166:169], v[92:95]
	v_mfma_f32_16x16x32_bf16 v[88:91], v[244:247], v[166:169], v[88:91]
	v_mfma_f32_16x16x32_bf16 v[84:87], v[236:239], v[200:203], v[84:87]
	v_mfma_f32_16x16x32_bf16 v[80:83], v[244:247], v[200:203], v[80:83]
	v_mfma_f32_16x16x32_bf16 v[76:79], v[236:239], v[216:219], v[76:79]
	v_mfma_f32_16x16x32_bf16 v[72:75], v[244:247], v[216:219], v[72:75]
	v_mfma_f32_16x16x32_bf16 v[68:71], v[236:239], v[228:231], v[68:71]
	v_mfma_f32_16x16x32_bf16 v[64:67], v[244:247], v[228:231], v[64:67]
	s_barrier
	s_setprio 0
	s_mov_b32 m0, s80
	v_lshl_add_u64 v[176:177], v[224:225], 0, s[18:19]
	global_load_lds_dwordx4 v[176:177], off
	v_lshl_add_u64 v[176:177], v[248:249], 0, s[18:19]
	s_mov_b32 m0, s83
	s_nop 0
	global_load_lds_dwordx4 v[176:177], off
	ds_read_b128 v[162:165], v194 offset:49152
	ds_read_b128 v[166:169], v194 offset:50176
	ds_read_b128 v[196:199], v194 offset:51200
	ds_read_b128 v[200:203], v194 offset:52224
	ds_read_b128 v[204:207], v194 offset:53248
	ds_read_b128 v[216:219], v194 offset:54272
	ds_read_b128 v[220:223], v194 offset:55296
	ds_read_b128 v[228:231], v194 offset:56320
	s_setprio 1
	s_barrier
	s_waitcnt lgkmcnt(0)
	v_mfma_f32_16x16x32_bf16 v[60:63], v[128:131], v[162:165], v[60:63]
	v_mfma_f32_16x16x32_bf16 v[56:59], v[136:139], v[162:165], v[56:59]
	v_mfma_f32_16x16x32_bf16 v[52:55], v[128:131], v[196:199], v[52:55]
	v_mfma_f32_16x16x32_bf16 v[48:51], v[136:139], v[196:199], v[48:51]
	v_mfma_f32_16x16x32_bf16 v[44:47], v[128:131], v[204:207], v[44:47]
	v_mfma_f32_16x16x32_bf16 v[40:43], v[136:139], v[204:207], v[40:43]
	v_mfma_f32_16x16x32_bf16 v[36:39], v[128:131], v[220:223], v[36:39]
	v_mfma_f32_16x16x32_bf16 v[32:35], v[136:139], v[220:223], v[32:35]
	v_mfma_f32_16x16x32_bf16 v[60:63], v[132:135], v[166:169], v[60:63]
	v_mfma_f32_16x16x32_bf16 v[56:59], v[140:143], v[166:169], v[56:59]
	v_mfma_f32_16x16x32_bf16 v[52:55], v[132:135], v[200:203], v[52:55]
	v_mfma_f32_16x16x32_bf16 v[48:51], v[140:143], v[200:203], v[48:51]
	v_mfma_f32_16x16x32_bf16 v[44:47], v[132:135], v[216:219], v[44:47]
	v_mfma_f32_16x16x32_bf16 v[40:43], v[140:143], v[216:219], v[40:43]
	v_mfma_f32_16x16x32_bf16 v[36:39], v[132:135], v[228:231], v[36:39]
	v_mfma_f32_16x16x32_bf16 v[32:35], v[140:143], v[228:231], v[32:35]
	s_barrier
	s_setprio 0
	s_add_u32 s50, s50, 0x40080
	s_addc_u32 s51, s51, 0
	s_add_i32 s27, s37, s76
	v_lshl_add_u64 v[128:129], s[50:51], 0, v[148:149]
	s_mov_b32 m0, s27
	s_nop 0
	global_load_lds_dwordx4 v[128:129], off
	v_lshl_add_u64 v[128:129], s[50:51], 0, v[152:153]
	s_add_i32 m0, s27, 0x2000
	s_nop 0
	global_load_lds_dwordx4 v[128:129], off
	s_waitcnt vmcnt(6)
	s_setprio 1
	s_barrier
	v_mfma_f32_16x16x32_bf16 v[28:31], v[232:235], v[162:165], v[28:31]
	v_mfma_f32_16x16x32_bf16 v[24:27], v[240:243], v[162:165], v[24:27]
	v_mfma_f32_16x16x32_bf16 v[20:23], v[232:235], v[196:199], v[20:23]
	v_mfma_f32_16x16x32_bf16 v[16:19], v[240:243], v[196:199], v[16:19]
	v_mfma_f32_16x16x32_bf16 v[12:15], v[232:235], v[204:207], v[12:15]
	v_mfma_f32_16x16x32_bf16 v[8:11], v[240:243], v[204:207], v[8:11]
	v_mfma_f32_16x16x32_bf16 v[4:7], v[232:235], v[220:223], v[4:7]
	v_mfma_f32_16x16x32_bf16 v[0:3], v[240:243], v[220:223], v[0:3]
	v_mfma_f32_16x16x32_bf16 v[28:31], v[236:239], v[166:169], v[28:31]
	v_mfma_f32_16x16x32_bf16 v[24:27], v[244:247], v[166:169], v[24:27]
	v_mfma_f32_16x16x32_bf16 v[20:23], v[236:239], v[200:203], v[20:23]
	v_mfma_f32_16x16x32_bf16 v[16:19], v[244:247], v[200:203], v[16:19]
	v_mfma_f32_16x16x32_bf16 v[12:15], v[236:239], v[216:219], v[12:15]
	v_mfma_f32_16x16x32_bf16 v[8:11], v[244:247], v[216:219], v[8:11]
	v_mfma_f32_16x16x32_bf16 v[4:7], v[236:239], v[228:231], v[4:7]
	v_mfma_f32_16x16x32_bf16 v[0:3], v[244:247], v[228:231], v[0:3]
	s_barrier
	s_setprio 0
	s_add_i32 s36, s36, 2
	s_add_u32 s0, s0, 0x100
	s_addc_u32 s1, s1, 0
	s_add_u32 s34, s34, 0x100
	s_addc_u32 s35, s35, 0
	s_cmp_gt_u32 s36, 13
	s_cbranch_scc0 .LBB0_351
	s_lshl_b32 s0, s11, 8
	s_or_b32 s50, s0, s79
	s_ashr_i32 s51, s50, 31
	v_lshl_add_u64 v[140:141], s[50:51], 3, v[154:155]
	global_load_dwordx4 v[128:131], v[140:141], off offset:48
	global_load_dwordx4 v[132:135], v[140:141], off offset:32
	global_load_dwordx4 v[136:139], v[140:141], off offset:16
	global_load_dwordx4 v[162:165], v[140:141], off
	s_mov_b32 s34, 0x35800000
	s_mov_b32 s0, 0x358637bd
	v_mov_b64_e32 v[168:169], s[0:1]
	s_mov_b32 s30, 0x45800000
	s_cmp_lt_u32 s10, 2
	s_waitcnt vmcnt(0)
	v_ffbh_u32_e32 v142, v165
	v_min_u32_e32 v161, 32, v142
	v_lshlrev_b64 v[142:143], v161, v[164:165]
	v_min_u32_e32 v142, 1, v142
	v_or_b32_e32 v142, v143, v142
	v_cvt_f32_u32_e32 v142, v142
	v_sub_u32_e32 v143, 32, v161
	v_ldexp_f32 v143, v142, v143
	v_ffbh_u32_e32 v142, v163
	v_min_u32_e32 v142, 32, v142
	v_lshlrev_b64 v[162:163], v142, v[162:163]
	v_min_u32_e32 v161, 1, v162
	v_or_b32_e32 v161, v163, v161
	v_cvt_f32_u32_e32 v161, v161
	v_sub_u32_e32 v142, 32, v142
	v_ldexp_f32 v142, v161, v142
	v_pk_mul_f32 v[142:143], v[142:143], s[34:35] op_sel_hi:[1,0]
	s_nop 0
	v_pk_fma_f32 v[142:143], v[142:143], s[2:3], v[168:169] op_sel_hi:[1,0,0]
	s_nop 0
	v_mul_f32_e32 v161, 0x4b800000, v142
	v_cmp_gt_f32_e64 s[0:1], s89, v142
	v_cmp_gt_f32_e32 vcc, s89, v143
	s_nop 0
	v_cndmask_b32_e64 v142, v142, v161, s[0:1]
	v_mul_f32_e32 v161, 0x4b800000, v143
	v_cndmask_b32_e32 v143, v143, v161, vcc
	v_rsq_f32_e32 v142, v142
	v_rsq_f32_e32 v143, v143
	s_nop 0
	v_pk_mul_f32 v[162:163], v[142:143], s[30:31] op_sel_hi:[1,0]
	s_nop 0
	v_cndmask_b32_e64 v166, v142, v162, s[0:1]
	v_ffbh_u32_e32 v142, v139
	v_min_u32_e32 v142, 32, v142
	v_lshlrev_b64 v[138:139], v142, v[138:139]
	v_min_u32_e32 v138, 1, v138
	v_or_b32_e32 v138, v139, v138
	v_cvt_f32_u32_e32 v138, v138
	v_sub_u32_e32 v139, 32, v142
	v_cndmask_b32_e32 v167, v143, v163, vcc
	v_pk_mul_f32 v[60:61], v[60:61], v[166:167]
	v_ldexp_f32 v139, v138, v139
	v_ffbh_u32_e32 v138, v137
	v_min_u32_e32 v138, 32, v138
	v_lshlrev_b64 v[136:137], v138, v[136:137]
	v_min_u32_e32 v136, 1, v136
	v_or_b32_e32 v136, v137, v136
	v_cvt_f32_u32_e32 v136, v136
	v_sub_u32_e32 v137, 32, v138
	v_pk_mul_f32 v[52:53], v[52:53], v[166:167]
	v_pk_mul_f32 v[44:45], v[44:45], v[166:167]
	v_ldexp_f32 v138, v136, v137
	v_pk_mul_f32 v[136:137], v[138:139], s[34:35] op_sel_hi:[1,0]
	v_pk_mul_f32 v[36:37], v[36:37], v[166:167]
	v_pk_fma_f32 v[136:137], v[136:137], s[2:3], v[168:169] op_sel_hi:[1,0,0]
	s_nop 0
	v_mul_f32_e32 v138, 0x4b800000, v136
	v_cmp_gt_f32_e64 s[0:1], s89, v136
	v_cmp_gt_f32_e32 vcc, s89, v137
	s_nop 0
	v_cndmask_b32_e64 v136, v136, v138, s[0:1]
	v_mul_f32_e32 v138, 0x4b800000, v137
	v_cndmask_b32_e32 v137, v137, v138, vcc
	v_rsq_f32_e32 v136, v136
	v_rsq_f32_e32 v137, v137
	s_nop 0
	v_pk_mul_f32 v[138:139], v[136:137], s[30:31] op_sel_hi:[1,0]
	s_nop 0
	v_cndmask_b32_e64 v162, v136, v138, s[0:1]
	v_ffbh_u32_e32 v136, v135
	v_min_u32_e32 v136, 32, v136
	v_lshlrev_b64 v[134:135], v136, v[134:135]
	v_min_u32_e32 v134, 1, v134
	v_or_b32_e32 v134, v135, v134
	v_cvt_f32_u32_e32 v134, v134
	v_sub_u32_e32 v135, 32, v136
	v_cndmask_b32_e32 v163, v137, v139, vcc
	v_ldexp_f32 v135, v134, v135
	v_ffbh_u32_e32 v134, v133
	v_min_u32_e32 v134, 32, v134
	v_lshlrev_b64 v[132:133], v134, v[132:133]
	v_min_u32_e32 v132, 1, v132
	v_or_b32_e32 v132, v133, v132
	v_cvt_f32_u32_e32 v132, v132
	v_sub_u32_e32 v133, 32, v134
	v_ldexp_f32 v134, v132, v133
	v_pk_mul_f32 v[132:133], v[134:135], s[34:35] op_sel_hi:[1,0]
	s_nop 0
	v_pk_fma_f32 v[132:133], v[132:133], s[2:3], v[168:169] op_sel_hi:[1,0,0]
	s_nop 0
	v_mul_f32_e32 v134, 0x4b800000, v132
	v_cmp_gt_f32_e64 s[0:1], s89, v132
	v_cmp_gt_f32_e32 vcc, s89, v133
	s_nop 0
	v_cndmask_b32_e64 v132, v132, v134, s[0:1]
	v_mul_f32_e32 v134, 0x4b800000, v133
	v_cndmask_b32_e32 v133, v133, v134, vcc
	v_rsq_f32_e32 v132, v132
	v_rsq_f32_e32 v133, v133
	s_nop 0
	v_pk_mul_f32 v[134:135], v[132:133], s[30:31] op_sel_hi:[1,0]
	s_nop 0
	v_cndmask_b32_e64 v188, v132, v134, s[0:1]
	v_ffbh_u32_e32 v132, v131
	v_min_u32_e32 v132, 32, v132
	v_lshlrev_b64 v[130:131], v132, v[130:131]
	v_min_u32_e32 v130, 1, v130
	v_or_b32_e32 v130, v131, v130
	v_cvt_f32_u32_e32 v130, v130
	v_sub_u32_e32 v131, 32, v132
	v_cndmask_b32_e32 v189, v133, v135, vcc
	v_pk_mul_f32 v[56:57], v[56:57], v[188:189]
	v_ldexp_f32 v131, v130, v131
	v_ffbh_u32_e32 v130, v129
	v_min_u32_e32 v130, 32, v130
	v_lshlrev_b64 v[128:129], v130, v[128:129]
	v_min_u32_e32 v128, 1, v128
	v_or_b32_e32 v128, v129, v128
	v_cvt_f32_u32_e32 v128, v128
	v_sub_u32_e32 v129, 32, v130
	v_pk_mul_f32 v[48:49], v[48:49], v[188:189]
	v_pk_mul_f32 v[40:41], v[40:41], v[188:189]
	v_ldexp_f32 v130, v128, v129
	v_pk_mul_f32 v[128:129], v[130:131], s[34:35] op_sel_hi:[1,0]
	v_pk_mul_f32 v[32:33], v[32:33], v[188:189]
	v_pk_fma_f32 v[128:129], v[128:129], s[2:3], v[168:169] op_sel_hi:[1,0,0]
	s_nop 0
	v_mul_f32_e32 v130, 0x4b800000, v128
	v_cmp_gt_f32_e64 s[0:1], s89, v128
	v_cmp_gt_f32_e32 vcc, s89, v129
	s_nop 0
	v_cndmask_b32_e64 v128, v128, v130, s[0:1]
	v_mul_f32_e32 v130, 0x4b800000, v129
	v_cndmask_b32_e32 v129, v129, v130, vcc
	v_rsq_f32_e32 v128, v128
	v_rsq_f32_e32 v129, v129
	s_nop 0
	v_pk_mul_f32 v[130:131], v[128:129], s[30:31] op_sel_hi:[1,0]
	s_nop 0
	v_cndmask_b32_e32 v165, v129, v131, vcc
	v_cndmask_b32_e64 v164, v128, v130, s[0:1]
	global_load_dwordx4 v[128:131], v[140:141], off offset:1072
	global_load_dwordx4 v[132:135], v[140:141], off offset:1056
	global_load_dwordx4 v[136:139], v[140:141], off offset:1040
	s_nop 0
	global_load_dwordx4 v[140:143], v[140:141], off offset:1024
	s_waitcnt vmcnt(0)
	v_ffbh_u32_e32 v161, v143
	v_min_u32_e32 v161, 32, v161
	v_lshlrev_b64 v[142:143], v161, v[142:143]
	v_min_u32_e32 v142, 1, v142
	v_or_b32_e32 v142, v143, v142
	v_cvt_f32_u32_e32 v142, v142
	v_sub_u32_e32 v143, 32, v161
	v_ldexp_f32 v143, v142, v143
	v_ffbh_u32_e32 v142, v141
	v_min_u32_e32 v142, 32, v142
	v_lshlrev_b64 v[140:141], v142, v[140:141]
	v_min_u32_e32 v140, 1, v140
	v_or_b32_e32 v140, v141, v140
	v_cvt_f32_u32_e32 v140, v140
	v_sub_u32_e32 v141, 32, v142
	v_ldexp_f32 v142, v140, v141
	v_pk_mul_f32 v[140:141], v[142:143], s[34:35] op_sel_hi:[1,0]
	s_nop 0
	v_pk_fma_f32 v[140:141], v[140:141], s[2:3], v[168:169] op_sel_hi:[1,0,0]
	s_nop 0
	v_mul_f32_e32 v142, 0x4b800000, v140
	v_cmp_gt_f32_e64 s[0:1], s89, v140
	v_cmp_gt_f32_e32 vcc, s89, v141
	s_nop 0
	v_cndmask_b32_e64 v140, v140, v142, s[0:1]
	v_mul_f32_e32 v142, 0x4b800000, v141
	v_cndmask_b32_e32 v141, v141, v142, vcc
	v_rsq_f32_e32 v140, v140
	v_rsq_f32_e32 v141, v141
	s_nop 0
	v_pk_mul_f32 v[142:143], v[140:141], s[30:31] op_sel_hi:[1,0]
	s_nop 0
	v_cndmask_b32_e64 v142, v140, v142, s[0:1]
	v_ffbh_u32_e32 v140, v139
	v_min_u32_e32 v140, 32, v140
	v_lshlrev_b64 v[138:139], v140, v[138:139]
	v_min_u32_e32 v138, 1, v138
	v_or_b32_e32 v138, v139, v138
	v_cvt_f32_u32_e32 v138, v138
	v_sub_u32_e32 v139, 32, v140
	v_cndmask_b32_e32 v143, v141, v143, vcc
	v_pk_mul_f32 v[140:141], v[124:125], v[166:167]
	v_ldexp_f32 v139, v138, v139
	v_ffbh_u32_e32 v138, v137
	v_min_u32_e32 v138, 32, v138
	v_lshlrev_b64 v[136:137], v138, v[136:137]
	v_min_u32_e32 v136, 1, v136
	v_or_b32_e32 v136, v137, v136
	v_cvt_f32_u32_e32 v136, v136
	v_sub_u32_e32 v137, 32, v138
	v_pk_mul_f32 v[28:29], v[28:29], v[142:143]
	v_pk_mul_f32 v[20:21], v[20:21], v[142:143]
	v_ldexp_f32 v138, v136, v137
	v_pk_mul_f32 v[136:137], v[138:139], s[34:35] op_sel_hi:[1,0]
	v_pk_mul_f32 v[12:13], v[12:13], v[142:143]
	v_pk_fma_f32 v[136:137], v[136:137], s[2:3], v[168:169] op_sel_hi:[1,0,0]
	v_pk_mul_f32 v[4:5], v[4:5], v[142:143]
	v_mul_f32_e32 v138, 0x4b800000, v136
	v_cmp_gt_f32_e64 s[0:1], s89, v136
	v_cmp_gt_f32_e32 vcc, s89, v137
	s_nop 0
	v_cndmask_b32_e64 v136, v136, v138, s[0:1]
	v_mul_f32_e32 v138, 0x4b800000, v137
	v_cndmask_b32_e32 v137, v137, v138, vcc
	v_rsq_f32_e32 v136, v136
	v_rsq_f32_e32 v137, v137
	s_nop 0
	v_pk_mul_f32 v[138:139], v[136:137], s[30:31] op_sel_hi:[1,0]
	s_nop 0
	v_cndmask_b32_e64 v136, v136, v138, s[0:1]
	v_ffbh_u32_e32 v138, v135
	v_min_u32_e32 v138, 32, v138
	v_lshlrev_b64 v[134:135], v138, v[134:135]
	v_min_u32_e32 v134, 1, v134
	v_or_b32_e32 v134, v135, v134
	v_cvt_f32_u32_e32 v134, v134
	v_sub_u32_e32 v135, 32, v138
	v_cndmask_b32_e32 v137, v137, v139, vcc
	v_pk_mul_f32 v[138:139], v[120:121], v[188:189]
	v_ldexp_f32 v135, v134, v135
	v_ffbh_u32_e32 v134, v133
	v_min_u32_e32 v134, 32, v134
	v_lshlrev_b64 v[132:133], v134, v[132:133]
	v_min_u32_e32 v132, 1, v132
	v_or_b32_e32 v132, v133, v132
	v_cvt_f32_u32_e32 v132, v132
	v_sub_u32_e32 v133, 32, v134
	v_pk_mul_f32 v[120:121], v[84:85], v[142:143]
	v_ldexp_f32 v134, v132, v133
	v_pk_mul_f32 v[132:133], v[134:135], s[34:35] op_sel_hi:[1,0]
	s_nop 0
	v_pk_fma_f32 v[132:133], v[132:133], s[2:3], v[168:169] op_sel_hi:[1,0,0]
	s_nop 0
	v_mul_f32_e32 v134, 0x4b800000, v132
	v_cmp_gt_f32_e64 s[0:1], s89, v132
	v_cmp_gt_f32_e32 vcc, s89, v133
	s_nop 0
	v_cndmask_b32_e64 v132, v132, v134, s[0:1]
	v_mul_f32_e32 v134, 0x4b800000, v133
	v_cndmask_b32_e32 v133, v133, v134, vcc
	v_rsq_f32_e32 v132, v132
	v_rsq_f32_e32 v133, v133
	s_nop 0
	v_pk_mul_f32 v[134:135], v[132:133], s[30:31] op_sel_hi:[1,0]
	s_nop 0
	v_cndmask_b32_e64 v176, v132, v134, s[0:1]
	v_ffbh_u32_e32 v132, v131
	v_min_u32_e32 v132, 32, v132
	v_lshlrev_b64 v[130:131], v132, v[130:131]
	v_min_u32_e32 v130, 1, v130
	v_or_b32_e32 v130, v131, v130
	v_cvt_f32_u32_e32 v130, v130
	v_sub_u32_e32 v131, 32, v132
	v_cndmask_b32_e32 v177, v133, v135, vcc
	v_pk_mul_f32 v[124:125], v[88:89], v[176:177]
	v_ldexp_f32 v131, v130, v131
	v_ffbh_u32_e32 v130, v129
	v_min_u32_e32 v130, 32, v130
	v_lshlrev_b64 v[128:129], v130, v[128:129]
	v_min_u32_e32 v128, 1, v128
	v_or_b32_e32 v128, v129, v128
	v_cvt_f32_u32_e32 v128, v128
	v_sub_u32_e32 v129, 32, v130
	v_pk_mul_f32 v[134:135], v[116:117], v[166:167]
	v_pk_mul_f32 v[132:133], v[112:113], v[188:189]
	v_ldexp_f32 v130, v128, v129
	v_pk_mul_f32 v[128:129], v[130:131], s[34:35] op_sel_hi:[1,0]
	v_pk_mul_f32 v[116:117], v[80:81], v[176:177]
	v_pk_fma_f32 v[128:129], v[128:129], s[2:3], v[168:169] op_sel_hi:[1,0,0]
	v_pk_mul_f32 v[88:89], v[104:105], v[188:189]
	v_mul_f32_e32 v130, 0x4b800000, v128
	v_cmp_gt_f32_e64 s[0:1], s89, v128
	v_cmp_gt_f32_e32 vcc, s89, v129
	v_pk_mul_f32 v[112:113], v[76:77], v[142:143]
	v_cndmask_b32_e64 v128, v128, v130, s[0:1]
	v_mul_f32_e32 v130, 0x4b800000, v129
	v_cndmask_b32_e32 v129, v129, v130, vcc
	v_rsq_f32_e32 v128, v128
	v_rsq_f32_e32 v129, v129
	v_pk_mul_f32 v[76:77], v[100:101], v[166:167]
	v_pk_mul_f32 v[104:105], v[68:69], v[142:143]
	v_pk_mul_f32 v[24:25], v[24:25], v[176:177]
	v_pk_mul_f32 v[130:131], v[128:129], s[30:31] op_sel_hi:[1,0]
	v_pk_mul_f32 v[16:17], v[16:17], v[176:177]
	v_cndmask_b32_e32 v129, v129, v131, vcc
	v_cndmask_b32_e64 v128, v128, v130, s[0:1]
	s_mov_b64 s[0:1], -1
	v_pk_mul_f32 v[130:131], v[92:93], v[142:143]
	v_pk_mul_f32 v[92:93], v[108:109], v[166:167]
	v_pk_mul_f32 v[108:109], v[72:73], v[176:177]
	v_pk_mul_f32 v[72:73], v[96:97], v[188:189]
	v_pk_mul_f32 v[96:97], v[64:65], v[176:177]
	v_pk_mul_f32 v[8:9], v[8:9], v[176:177]
	v_pk_mul_f32 v[0:1], v[0:1], v[176:177]
	s_cbranch_scc1 .LBB0_354
	v_lshl_add_u32 v68, s10, 8, v193
	v_ashrrev_i32_e32 v69, 31, v68
	v_pk_mul_f32 v[64:65], v[126:127], v[162:163]
	v_cvt_pk_bf16_f32 v80, v140, v141
	s_lshl_b64 s[0:1], s[50:51], 1
	v_cvt_pk_bf16_f32 v81, v64, v65
	v_lshlrev_b64 v[64:65], 13, v[68:69]
	v_lshl_add_u64 v[64:65], s[44:45], 0, v[64:65]
	v_lshl_add_u64 v[64:65], v[64:65], 0, s[0:1]
	v_lshl_add_u64 v[64:65], v[64:65], 0, v[144:145]
	v_mov_b32_e32 v161, v145
	v_lshl_add_u64 v[64:65], v[64:65], 0, v[160:161]
	global_store_dwordx2 v[64:65], v[80:81], off
	v_pk_mul_f32 v[80:81], v[122:123], v[164:165]
	v_cvt_pk_bf16_f32 v84, v138, v139
	s_nop 0
	v_cvt_pk_bf16_f32 v85, v80, v81
	v_pk_mul_f32 v[80:81], v[94:95], v[136:137]
	global_store_dwordx2 v[64:65], v[84:85], off offset:16
	v_cvt_pk_bf16_f32 v84, v130, v131
	v_cvt_pk_bf16_f32 v85, v80, v81
	v_pk_mul_f32 v[80:81], v[90:91], v[128:129]
	global_store_dwordx2 v[64:65], v[84:85], off offset:256
	v_cvt_pk_bf16_f32 v84, v124, v125
	v_cvt_pk_bf16_f32 v85, v80, v81
	v_or_b32_e32 v80, 16, v68
	v_ashrrev_i32_e32 v81, 31, v80
	v_lshlrev_b64 v[80:81], 13, v[80:81]
	v_lshl_add_u64 v[80:81], s[44:45], 0, v[80:81]
	v_lshl_add_u64 v[80:81], v[80:81], 0, s[0:1]
	v_lshl_add_u64 v[80:81], v[80:81], 0, v[144:145]
	global_store_dwordx2 v[64:65], v[84:85], off offset:272
	v_pk_mul_f32 v[84:85], v[118:119], v[162:163]
	v_cvt_pk_bf16_f32 v100, v134, v135
	v_lshl_add_u64 v[80:81], v[80:81], 0, v[160:161]
	v_cvt_pk_bf16_f32 v101, v84, v85
	global_store_dwordx2 v[80:81], v[100:101], off
	v_pk_mul_f32 v[84:85], v[114:115], v[164:165]
	v_cvt_pk_bf16_f32 v100, v132, v133
	s_nop 0
	v_cvt_pk_bf16_f32 v101, v84, v85
	global_store_dwordx2 v[80:81], v[100:101], off offset:16
	v_pk_mul_f32 v[84:85], v[86:87], v[136:137]
	v_cvt_pk_bf16_f32 v100, v120, v121
	s_nop 0
	v_cvt_pk_bf16_f32 v101, v84, v85
	global_store_dwordx2 v[80:81], v[100:101], off offset:256
	v_pk_mul_f32 v[84:85], v[82:83], v[128:129]
	v_cvt_pk_bf16_f32 v100, v116, v117
	s_nop 0
	v_cvt_pk_bf16_f32 v101, v84, v85
	global_store_dwordx2 v[80:81], v[100:101], off offset:272
	v_or_b32_e32 v80, 32, v68
	v_ashrrev_i32_e32 v81, 31, v80
	v_lshlrev_b64 v[80:81], 13, v[80:81]
	v_lshl_add_u64 v[80:81], s[44:45], 0, v[80:81]
	v_or_b32_e32 v68, 48, v68
	v_lshl_add_u64 v[80:81], v[80:81], 0, s[0:1]
	v_ashrrev_i32_e32 v69, 31, v68
	v_pk_mul_f32 v[84:85], v[110:111], v[162:163]
	v_lshl_add_u64 v[80:81], v[80:81], 0, v[144:145]
	v_lshlrev_b64 v[68:69], 13, v[68:69]
	v_cvt_pk_bf16_f32 v100, v92, v93
	v_cvt_pk_bf16_f32 v101, v84, v85
	v_lshl_add_u64 v[80:81], v[80:81], 0, v[160:161]
	v_pk_mul_f32 v[84:85], v[106:107], v[164:165]
	v_lshl_add_u64 v[68:69], s[44:45], 0, v[68:69]
	global_store_dwordx2 v[80:81], v[100:101], off
	v_cvt_pk_bf16_f32 v100, v88, v89
	v_cvt_pk_bf16_f32 v101, v84, v85
	v_pk_mul_f32 v[84:85], v[78:79], v[136:137]
	v_lshl_add_u64 v[68:69], v[68:69], 0, s[0:1]
	global_store_dwordx2 v[80:81], v[100:101], off offset:16
	v_cvt_pk_bf16_f32 v100, v112, v113
	v_cvt_pk_bf16_f32 v101, v84, v85
	v_pk_mul_f32 v[84:85], v[74:75], v[128:129]
	v_lshl_add_u64 v[68:69], v[68:69], 0, v[144:145]
	global_store_dwordx2 v[80:81], v[100:101], off offset:256
	v_cvt_pk_bf16_f32 v100, v108, v109
	v_cvt_pk_bf16_f32 v101, v84, v85
	global_store_dwordx2 v[80:81], v[100:101], off offset:272
	v_cvt_pk_bf16_f32 v84, v76, v77
	v_lshl_add_u64 v[68:69], v[68:69], 0, v[160:161]
	v_pk_mul_f32 v[80:81], v[102:103], v[162:163]
	s_mov_b64 s[0:1], 0x100000
	v_cvt_pk_bf16_f32 v85, v80, v81
	global_store_dwordx2 v[68:69], v[84:85], off
	v_cvt_pk_bf16_f32 v84, v72, v73
	v_pk_mul_f32 v[80:81], v[98:99], v[164:165]
	s_nop 0
	v_cvt_pk_bf16_f32 v85, v80, v81
	global_store_dwordx2 v[68:69], v[84:85], off offset:16
	v_cvt_pk_bf16_f32 v84, v104, v105
	v_pk_mul_f32 v[80:81], v[70:71], v[136:137]
	s_nop 0
	v_cvt_pk_bf16_f32 v85, v80, v81
	global_store_dwordx2 v[68:69], v[84:85], off offset:256
	v_cvt_pk_bf16_f32 v84, v96, v97
	v_pk_mul_f32 v[80:81], v[66:67], v[128:129]
	s_nop 0
	v_cvt_pk_bf16_f32 v85, v80, v81
	global_store_dwordx2 v[68:69], v[84:85], off offset:272
	v_add_co_u32_e32 v84, vcc, s29, v64
	v_pk_mul_f32 v[68:69], v[62:63], v[162:163]
	s_nop 0
	v_addc_co_u32_e32 v85, vcc, 0, v65, vcc
	v_cvt_pk_bf16_f32 v80, v60, v61
	v_cvt_pk_bf16_f32 v81, v68, v69
	v_lshl_add_u64 v[68:69], v[64:65], 0, s[0:1]
	global_store_dwordx2 v[84:85], v[80:81], off
	v_cvt_pk_bf16_f32 v84, v56, v57
	v_pk_mul_f32 v[80:81], v[58:59], v[164:165]
	s_mov_b64 s[0:1], 0x120000
	v_cvt_pk_bf16_f32 v85, v80, v81
	global_store_dwordx2 v[68:69], v[84:85], off offset:16
	v_cvt_pk_bf16_f32 v84, v28, v29
	v_pk_mul_f32 v[80:81], v[30:31], v[136:137]
	s_nop 0
	v_cvt_pk_bf16_f32 v85, v80, v81
	global_store_dwordx2 v[68:69], v[84:85], off offset:256
	v_cvt_pk_bf16_f32 v84, v24, v25
	v_pk_mul_f32 v[80:81], v[26:27], v[128:129]
	s_nop 0
	v_cvt_pk_bf16_f32 v85, v80, v81
	global_store_dwordx2 v[68:69], v[84:85], off offset:272
	v_add_co_u32_e32 v84, vcc, s49, v64
	v_pk_mul_f32 v[68:69], v[54:55], v[162:163]
	v_cvt_pk_bf16_f32 v80, v52, v53
	s_nop 0
	v_addc_co_u32_e32 v85, vcc, 0, v65, vcc
	v_cvt_pk_bf16_f32 v81, v68, v69
	v_lshl_add_u64 v[68:69], v[64:65], 0, s[0:1]
	global_store_dwordx2 v[84:85], v[80:81], off
	v_pk_mul_f32 v[80:81], v[50:51], v[164:165]
	v_cvt_pk_bf16_f32 v84, v48, v49
	s_mov_b64 s[0:1], 0x140000
	v_cvt_pk_bf16_f32 v85, v80, v81
	global_store_dwordx2 v[68:69], v[84:85], off offset:16
	v_pk_mul_f32 v[80:81], v[22:23], v[136:137]
	v_cvt_pk_bf16_f32 v84, v20, v21
	s_nop 0
	v_cvt_pk_bf16_f32 v85, v80, v81
	global_store_dwordx2 v[68:69], v[84:85], off offset:256
	v_pk_mul_f32 v[80:81], v[18:19], v[128:129]
	v_cvt_pk_bf16_f32 v84, v16, v17
	s_nop 0
	v_cvt_pk_bf16_f32 v85, v80, v81
	global_store_dwordx2 v[68:69], v[84:85], off offset:272
	v_pk_mul_f32 v[68:69], v[46:47], v[162:163]
	v_cvt_pk_bf16_f32 v80, v44, v45
	s_nop 0
	v_cvt_pk_bf16_f32 v81, v68, v69
	v_lshl_add_u64 v[68:69], v[64:65], 0, s[0:1]
	s_mov_b32 s0, 0x140000
	v_add_co_u32_e32 v84, vcc, s0, v64
	s_mov_b64 s[0:1], 0x160000
	s_nop 0
	v_addc_co_u32_e32 v85, vcc, 0, v65, vcc
	global_store_dwordx2 v[84:85], v[80:81], off
	v_pk_mul_f32 v[80:81], v[42:43], v[164:165]
	v_cvt_pk_bf16_f32 v84, v40, v41
	s_nop 0
	v_cvt_pk_bf16_f32 v85, v80, v81
	global_store_dwordx2 v[68:69], v[84:85], off offset:16
	v_pk_mul_f32 v[80:81], v[14:15], v[136:137]
	v_cvt_pk_bf16_f32 v84, v12, v13
	s_nop 0
	v_cvt_pk_bf16_f32 v85, v80, v81
	global_store_dwordx2 v[68:69], v[84:85], off offset:256
	v_pk_mul_f32 v[80:81], v[10:11], v[128:129]
	v_cvt_pk_bf16_f32 v84, v8, v9
	s_nop 0
	v_cvt_pk_bf16_f32 v85, v80, v81
	global_store_dwordx2 v[68:69], v[84:85], off offset:272
	v_pk_mul_f32 v[68:69], v[38:39], v[162:163]
	v_cvt_pk_bf16_f32 v80, v36, v37
	s_nop 0
	v_cvt_pk_bf16_f32 v81, v68, v69
	v_lshl_add_u64 v[68:69], v[64:65], 0, s[0:1]
	s_mov_b32 s0, 0x160000
	v_add_co_u32_e32 v64, vcc, s0, v64
	s_mov_b64 s[0:1], 0
	s_nop 0
	v_addc_co_u32_e32 v65, vcc, 0, v65, vcc
	global_store_dwordx2 v[64:65], v[80:81], off
	v_pk_mul_f32 v[64:65], v[34:35], v[164:165]
	v_cvt_pk_bf16_f32 v80, v32, v33
	s_nop 0
	v_cvt_pk_bf16_f32 v81, v64, v65
	global_store_dwordx2 v[68:69], v[80:81], off offset:16
	v_pk_mul_f32 v[64:65], v[6:7], v[136:137]
	v_cvt_pk_bf16_f32 v80, v4, v5
	s_nop 0
	v_cvt_pk_bf16_f32 v81, v64, v65
	global_store_dwordx2 v[68:69], v[80:81], off offset:256
	v_pk_mul_f32 v[64:65], v[2:3], v[128:129]
	v_cvt_pk_bf16_f32 v80, v0, v1
	s_nop 0
	v_cvt_pk_bf16_f32 v81, v64, v65
	s_nop 1
	global_store_dwordx2 v[68:69], v[80:81], off offset:272
